# k20 plus loop-invariant LDS read bases hoisted out of the GEMM K-loops into dead VGPRs
# speedup vs baseline: 1.0263x; 1.0004x over previous
; #define PG8_STAGE(bufoff, gbase, voff) do { _Pragma("unroll") for (int _i = 0; _i < 2; ++_i) \
;         __builtin_amdgcn_global_load_lds((const unsigned*)((const char*)(gbase) + (voff)[_i]), (LAS unsigned*)(lds + (bufoff) + ldsw + _i * 8192), 16, 0, 0); } while (0)
; #define PG8_LDA(dst, b, h) do { _Pragma("unroll") for (int m = 0; m < 4; ++m) _Pragma("unroll") for (int k = 0; k < 2; ++k) dst[m][k] = *(const LAS bf16x8*)(lds + PG8_SA(b, h) + aoff + m * 2048 + k * 1024); } while (0)
; #define PG8_LDB(dst, b, h) do { _Pragma("unroll") for (int n = 0; n < 2; ++n) _Pragma("unroll") for (int k = 0; k < 2; ++k) dst[n][k] = *(const LAS bf16x8*)(lds + PG8_SB(b, h) + boff + n * 2048 + k * 1024); } while (0)
; #define PG8_WAIT_L(n) asm volatile("s_waitcnt lgkmcnt(" #n ")" ::: "memory")
; #define PG8_BAR __builtin_amdgcn_s_barrier()
; template <class Epi, class Sched>
; __device__ __forceinline__ void gemm_phase(LAS unsigned char* lds, const Gemm g, const Sched& S, const Epi& E, const int tid) {
;     ...
;         const bool has_next = S.next(ui + 1, nxt);
;         const char* nA = has_next ? (const char*)g.A + (size_t)nxt.pm * tstep + (size_t)nxt.ks * nxt.nt * kstep : cA; const char* nB = has_next ? (const char*)g.Bt + (size_t)nxt.pn * tstep + (size_t)nxt.ks * nxt.nt * kstep : cB;
;         const int nt = cur.nt;
;         for (int t = 0; t < nt; t += 2) {
;             const bool last = (t == nt - 2);
;             const char* a1 = cA + (size_t)(t + 1) * kstep;
;             const char* a2 = last ? nA : cA + (size_t)(t + 2) * kstep; const char* b2 = last ? nB : cB + (size_t)(t + 2) * kstep;
;             const char* a3 = a2 + kstep; const char* b3 = b2 + kstep;
;             if (last && has_next) S.a_ready(nxt);
;             if constexpr (Epi::PRELOAD) { if (last) E.preload(cur, lds, wid, lane); }
;             PG8_LDB(B0, 0, 0); PG8_SCHED; PG8_LDA(At, 0, 0); PG8_STAGE(PG8_SA(1, 1), a1 + hstep, voffA);
;             PG8_WAIT_L(8); PG8_BAR; PG8_WAIT_L(0); PG8_MMA(0, 0, At, B0); PG8_BAR; PG8_SCHED;
;     ...
; #pragma unroll
;         for (int a = 0; a < 2; ++a)
; #pragma unroll
;             for (int b = 0; b < 2; ++b)
; #pragma unroll
;                 for (int m = 0; m < 4; ++m)
; #pragma unroll
;                     for (int n = 0; n < 2; ++n) acc[a][b][m][n] = (f32x4){0.f, 0.f, 0.f, 0.f};
;         cur = nxt; cA = nA; cB = nB; ++ui;
.LBB0_276:
	v_mov_b64_e32 v[2:3], 0x5ee
	s_ashr_i32 s11, s10, 31
	v_cmp_lt_i64_e32 vcc, s[12:13], v[2:3]
	s_lshl_b64 s[12:13], s[10:11], 20
	s_add_u32 s12, s38, s12
	s_addc_u32 s13, s39, s13
	s_and_b64 s[14:15], vcc, exec
	s_cselect_b32 s11, s13, s17
	s_cselect_b32 s25, s12, s16
	s_ashr_i32 s7, s6, 31
	s_lshl_b64 s[14:15], s[6:7], 20
	s_add_u32 s14, s40, s14
	s_addc_u32 s15, s41, s15
	s_and_b64 s[20:21], vcc, exec
	s_cselect_b32 s7, s15, s19
	s_cselect_b32 s49, s14, s18
	s_add_u32 s16, s16, 0x80080
	s_addc_u32 s17, s17, 0
	s_add_u32 s50, s18, 0x100
	v_mov_b32_e32 v2, 0
	s_addc_u32 s51, s19, 0
	s_mov_b32 s52, -2
	v_mov_b32_e32 v3, v2
	v_mov_b32_e32 v4, v2
	v_mov_b32_e32 v5, v2
	v_mov_b32_e32 v6, v2
	v_mov_b32_e32 v7, v2
	v_mov_b32_e32 v8, v2
	v_mov_b32_e32 v9, v2
	v_mov_b32_e32 v10, v2
	v_mov_b32_e32 v11, v2
	v_mov_b32_e32 v12, v2
	v_mov_b32_e32 v13, v2
	v_mov_b32_e32 v14, v2
	v_mov_b32_e32 v15, v2
	v_mov_b32_e32 v16, v2
	v_mov_b32_e32 v17, v2
	v_mov_b32_e32 v26, v2
	v_mov_b32_e32 v27, v2
	v_mov_b32_e32 v28, v2
	v_mov_b32_e32 v29, v2
	v_mov_b32_e32 v30, v2
	v_mov_b32_e32 v31, v2
	v_mov_b32_e32 v32, v2
	v_mov_b32_e32 v33, v2
	v_mov_b32_e32 v42, v2
	v_mov_b32_e32 v43, v2
	v_mov_b32_e32 v44, v2
	v_mov_b32_e32 v45, v2
	v_mov_b32_e32 v46, v2
	v_mov_b32_e32 v47, v2
	v_mov_b32_e32 v48, v2
	v_mov_b32_e32 v49, v2
	v_mov_b32_e32 v18, v2
	v_mov_b32_e32 v19, v2
	v_mov_b32_e32 v20, v2
	v_mov_b32_e32 v21, v2
	v_mov_b32_e32 v22, v2
	v_mov_b32_e32 v23, v2
	v_mov_b32_e32 v24, v2
	v_mov_b32_e32 v25, v2
	v_mov_b32_e32 v34, v2
	v_mov_b32_e32 v35, v2
	v_mov_b32_e32 v36, v2
	v_mov_b32_e32 v37, v2
	v_mov_b32_e32 v38, v2
	v_mov_b32_e32 v39, v2
	v_mov_b32_e32 v40, v2
	v_mov_b32_e32 v41, v2
	v_mov_b32_e32 v50, v2
	v_mov_b32_e32 v51, v2
	v_mov_b32_e32 v52, v2
	v_mov_b32_e32 v53, v2
	v_mov_b32_e32 v54, v2
	v_mov_b32_e32 v55, v2
	v_mov_b32_e32 v56, v2
	v_mov_b32_e32 v57, v2
	v_mov_b32_e32 v58, v2
	v_mov_b32_e32 v59, v2
	v_mov_b32_e32 v60, v2
	v_mov_b32_e32 v61, v2
	v_mov_b32_e32 v62, v2
	v_mov_b32_e32 v63, v2
	v_mov_b32_e32 v64, v2
	v_mov_b32_e32 v65, v2
	v_mov_b32_e32 v66, v2
	v_mov_b32_e32 v67, v2
	v_mov_b32_e32 v68, v2
	v_mov_b32_e32 v69, v2
	v_mov_b32_e32 v70, v2
	v_mov_b32_e32 v71, v2
	v_mov_b32_e32 v72, v2
	v_mov_b32_e32 v73, v2
	v_mov_b32_e32 v74, v2
	v_mov_b32_e32 v75, v2
	v_mov_b32_e32 v76, v2
	v_mov_b32_e32 v77, v2
	v_mov_b32_e32 v78, v2
	v_mov_b32_e32 v79, v2
	v_mov_b32_e32 v80, v2
	v_mov_b32_e32 v81, v2
	v_mov_b32_e32 v90, v2
	v_mov_b32_e32 v91, v2
	v_mov_b32_e32 v92, v2
	v_mov_b32_e32 v93, v2
	v_mov_b32_e32 v94, v2
	v_mov_b32_e32 v95, v2
	v_mov_b32_e32 v96, v2
	v_mov_b32_e32 v97, v2
	v_mov_b32_e32 v106, v2
	v_mov_b32_e32 v107, v2
	v_mov_b32_e32 v108, v2
	v_mov_b32_e32 v109, v2
	v_mov_b32_e32 v110, v2
	v_mov_b32_e32 v111, v2
	v_mov_b32_e32 v112, v2
	v_mov_b32_e32 v113, v2
	v_mov_b32_e32 v82, v2
	v_mov_b32_e32 v83, v2
	v_mov_b32_e32 v84, v2
	v_mov_b32_e32 v85, v2
	v_mov_b32_e32 v86, v2
	v_mov_b32_e32 v87, v2
	v_mov_b32_e32 v88, v2
	v_mov_b32_e32 v89, v2
	v_mov_b32_e32 v98, v2
	v_mov_b32_e32 v99, v2
	v_mov_b32_e32 v100, v2
	v_mov_b32_e32 v101, v2
	v_mov_b32_e32 v102, v2
	v_mov_b32_e32 v103, v2
	v_mov_b32_e32 v104, v2
	v_mov_b32_e32 v105, v2
	v_mov_b32_e32 v114, v2
	v_mov_b32_e32 v115, v2
	v_mov_b32_e32 v116, v2
	v_mov_b32_e32 v117, v2
	v_mov_b32_e32 v118, v2
	v_mov_b32_e32 v119, v2
	v_mov_b32_e32 v120, v2
	v_mov_b32_e32 v121, v2
	v_mov_b32_e32 v122, v2
	v_mov_b32_e32 v123, v2
	v_mov_b32_e32 v124, v2
	v_mov_b32_e32 v125, v2
	v_mov_b32_e32 v126, v2
	v_mov_b32_e32 v127, v2
	v_mov_b32_e32 v128, v2
	v_mov_b32_e32 v129, v2
	v_add_u32_e32 v252, 0x10000, v141
	v_add_u32_e32 v251, 0x14000, v141
	v_add_u32_e32 v250, 0x18000, v141
	v_add_u32_e32 v249, 0x1c000, v141
.LBB0_277:
	s_add_u32 s18, s16, 0xfff80080
	s_addc_u32 s19, s17, -1
	s_add_i32 s53, 0, 0x10000
	ds_read_b128 v[144:147], v252
	ds_read_b128 v[148:151], v252 offset:1024
	ds_read_b128 v[152:155], v252 offset:2048
	ds_read_b128 v[156:159], v252 offset:3072
	s_cmp_eq_u32 s52, 28
	s_cselect_b32 s21, s11, s19
	s_cselect_b32 s20, s25, s18
	s_cselect_b32 s19, s7, s51
	s_cselect_b32 s18, s49, s50
	s_add_i32 m0, s5, 0xc000
	ds_read_b128 v[160:163], v143
	ds_read_b128 v[164:167], v143 offset:1024
	ds_read_b128 v[168:171], v143 offset:2048
	ds_read_b128 v[172:175], v143 offset:3072
	ds_read_b128 v[176:179], v143 offset:4096
	ds_read_b128 v[180:183], v143 offset:5120
	ds_read_b128 v[184:187], v143 offset:6144
	global_load_lds_dwordx4 v136, s[16:17]
	s_add_i32 m0, s5, 0xe000
	ds_read_b128 v[188:191], v143 offset:7168
	global_load_lds_dwordx4 v138, s[16:17]
	s_waitcnt lgkmcnt(8)
	s_barrier
	s_waitcnt lgkmcnt(0)
	v_mfma_f32_16x16x32_bf16 v[126:129], v[144:147], v[160:163], v[126:129]
	v_mfma_f32_16x16x32_bf16 v[122:125], v[152:155], v[160:163], v[122:125]
	v_mfma_f32_16x16x32_bf16 v[118:121], v[144:147], v[168:171], v[118:121]
	v_mfma_f32_16x16x32_bf16 v[114:117], v[152:155], v[168:171], v[114:117]
	v_mfma_f32_16x16x32_bf16 v[102:105], v[144:147], v[176:179], v[102:105]
	v_mfma_f32_16x16x32_bf16 v[98:101], v[152:155], v[176:179], v[98:101]
	v_mfma_f32_16x16x32_bf16 v[86:89], v[144:147], v[184:187], v[86:89]
	v_mfma_f32_16x16x32_bf16 v[82:85], v[152:155], v[184:187], v[82:85]
	v_mfma_f32_16x16x32_bf16 v[126:129], v[148:151], v[164:167], v[126:129]
	v_mfma_f32_16x16x32_bf16 v[122:125], v[156:159], v[164:167], v[122:125]
	v_mfma_f32_16x16x32_bf16 v[118:121], v[148:151], v[172:175], v[118:121]
	v_mfma_f32_16x16x32_bf16 v[114:117], v[156:159], v[172:175], v[114:117]
	v_mfma_f32_16x16x32_bf16 v[102:105], v[148:151], v[180:183], v[102:105]
	v_mfma_f32_16x16x32_bf16 v[98:101], v[156:159], v[180:183], v[98:101]
	v_mfma_f32_16x16x32_bf16 v[86:89], v[148:151], v[188:191], v[86:89]
	v_mfma_f32_16x16x32_bf16 v[82:85], v[156:159], v[188:191], v[82:85]
	s_barrier
; #define PG8_STAGE(bufoff, gbase, voff) do { _Pragma("unroll") for (int _i = 0; _i < 2; ++_i) \
;         __builtin_amdgcn_global_load_lds((const unsigned*)((const char*)(gbase) + (voff)[_i]), (LAS unsigned*)(lds + (bufoff) + ldsw + _i * 8192), 16, 0, 0); } while (0)
; #define PG8_LDA(dst, b, h) do { _Pragma("unroll") for (int m = 0; m < 4; ++m) _Pragma("unroll") for (int k = 0; k < 2; ++k) dst[m][k] = *(const LAS bf16x8*)(lds + PG8_SA(b, h) + aoff + m * 2048 + k * 1024); } while (0)
; #define PG8_LDB(dst, b, h) do { _Pragma("unroll") for (int n = 0; n < 2; ++n) _Pragma("unroll") for (int k = 0; k < 2; ++k) dst[n][k] = *(const LAS bf16x8*)(lds + PG8_SB(b, h) + boff + n * 2048 + k * 1024); } while (0)
; #define PG8_MMA(ai, bj, At, Bt) do { __builtin_amdgcn_s_setprio(1); _Pragma("unroll") for (int m = 0; m < 4; ++m) _Pragma("unroll") for (int n = 0; n < 2; ++n) _Pragma("unroll") for (int k = 0; k < 2; ++k) \
;         acc[ai][bj][m][n] = __builtin_amdgcn_mfma_f32_16x16x32_bf16(Bt[n][k], At[m][k], acc[ai][bj][m][n], 0, 0, 0); __builtin_amdgcn_s_setprio(0); } while (0)
; #define PG8_WAIT_V(n) asm volatile("s_waitcnt vmcnt(" #n ")" ::: "memory")
; #define PG8_WAIT_L(n) asm volatile("s_waitcnt lgkmcnt(" #n ")" ::: "memory")
; template <class Epi, class Sched>
; __device__ __forceinline__ void gemm_phase(LAS unsigned char* lds, const Gemm g, const Sched& S, const Epi& E, const int tid) {
;     ...
;             PG8_LDB(B1, 0, 1); PG8_STAGE(PG8_SB(0, 0), b2, voffB);
;             PG8_BAR; PG8_WAIT_L(0); PG8_MMA(0, 1, At, B1); PG8_BAR;
;             PG8_LDA(At, 0, 1); PG8_STAGE(PG8_SA(0, 0), a2, voffA);
;             PG8_BAR; PG8_WAIT_L(0); PG8_MMA(1, 0, At, B0); PG8_BAR; PG8_SCHED;
;             PG8_STAGE(PG8_SB(0, 1), b2 + hstep, voffB);
;             PG8_WAIT_V(6); PG8_BAR; PG8_MMA(1, 1, At, B1); PG8_BAR;
;             PG8_LDB(B0, 1, 0); PG8_SCHED; PG8_LDA(At, 1, 0); PG8_STAGE(PG8_SA(0, 1), a2 + hstep, voffA);
;             PG8_WAIT_L(8); PG8_BAR; PG8_WAIT_L(0); PG8_MMA(0, 0, At, B0); PG8_BAR; PG8_SCHED;
;             PG8_LDB(B1, 1, 1); PG8_STAGE(PG8_SB(1, 0), b3, voffB);
;             PG8_BAR; PG8_WAIT_L(0); PG8_MMA(0, 1, At, B1); PG8_BAR;
;             PG8_LDA(At, 1, 1); PG8_STAGE(PG8_SA(1, 0), a3, voffA);
;             PG8_BAR; PG8_WAIT_L(0); PG8_MMA(1, 0, At, B0); PG8_BAR; PG8_SCHED;
;             PG8_STAGE(PG8_SB(1, 1), b3 + hstep, voffB);
	s_add_i32 s56, 0, 0x14000
	s_add_i32 s53, s53, s42
	s_mov_b32 m0, s53
	ds_read_b128 v[192:195], v251
	ds_read_b128 v[196:199], v251 offset:1024
	ds_read_b128 v[200:203], v251 offset:2048
	ds_read_b128 v[204:207], v251 offset:3072
	global_load_lds_dwordx4 v0, s[18:19]
	s_add_i32 m0, s53, 0x2000
	s_nop 0
	global_load_lds_dwordx4 v134, s[18:19]
	s_barrier
	s_waitcnt lgkmcnt(0)
	v_mfma_f32_16x16x32_bf16 v[110:113], v[192:195], v[160:163], v[110:113]
	v_mfma_f32_16x16x32_bf16 v[106:109], v[200:203], v[160:163], v[106:109]
	v_mfma_f32_16x16x32_bf16 v[94:97], v[192:195], v[168:171], v[94:97]
	v_mfma_f32_16x16x32_bf16 v[90:93], v[200:203], v[168:171], v[90:93]
	v_mfma_f32_16x16x32_bf16 v[78:81], v[192:195], v[176:179], v[78:81]
	v_mfma_f32_16x16x32_bf16 v[74:77], v[200:203], v[176:179], v[74:77]
	v_mfma_f32_16x16x32_bf16 v[70:73], v[192:195], v[184:187], v[70:73]
	v_mfma_f32_16x16x32_bf16 v[66:69], v[200:203], v[184:187], v[66:69]
	v_mfma_f32_16x16x32_bf16 v[110:113], v[196:199], v[164:167], v[110:113]
	v_mfma_f32_16x16x32_bf16 v[106:109], v[204:207], v[164:167], v[106:109]
	v_mfma_f32_16x16x32_bf16 v[94:97], v[196:199], v[172:175], v[94:97]
	v_mfma_f32_16x16x32_bf16 v[90:93], v[204:207], v[172:175], v[90:93]
	v_mfma_f32_16x16x32_bf16 v[78:81], v[196:199], v[180:183], v[78:81]
	v_mfma_f32_16x16x32_bf16 v[74:77], v[204:207], v[180:183], v[74:77]
	v_mfma_f32_16x16x32_bf16 v[70:73], v[196:199], v[188:191], v[70:73]
	v_mfma_f32_16x16x32_bf16 v[66:69], v[204:207], v[188:191], v[66:69]
	s_mov_b32 m0, s5
	v_lshl_add_u64 v[214:215], s[20:21], 0, v[130:131]
	s_barrier
	ds_read_b128 v[160:163], v143 offset:16384
	ds_read_b128 v[164:167], v143 offset:17408
	ds_read_b128 v[168:171], v143 offset:18432
	ds_read_b128 v[172:175], v143 offset:19456
	ds_read_b128 v[176:179], v143 offset:20480
	ds_read_b128 v[180:183], v143 offset:21504
	ds_read_b128 v[184:187], v143 offset:22528
	ds_read_b128 v[188:191], v143 offset:23552
	global_load_lds_dwordx4 v[214:215], off
	s_mov_b32 m0, s43
	v_lshl_add_u64 v[216:217], s[20:21], 0, v[132:133]
	global_load_lds_dwordx4 v[216:217], off
	s_barrier
	s_waitcnt lgkmcnt(0)
	v_mfma_f32_16x16x32_bf16 v[62:65], v[144:147], v[160:163], v[62:65]
	v_mfma_f32_16x16x32_bf16 v[58:61], v[152:155], v[160:163], v[58:61]
	v_mfma_f32_16x16x32_bf16 v[54:57], v[144:147], v[168:171], v[54:57]
	v_mfma_f32_16x16x32_bf16 v[50:53], v[152:155], v[168:171], v[50:53]
	v_mfma_f32_16x16x32_bf16 v[38:41], v[144:147], v[176:179], v[38:41]
	v_mfma_f32_16x16x32_bf16 v[34:37], v[152:155], v[176:179], v[34:37]
	v_mfma_f32_16x16x32_bf16 v[22:25], v[144:147], v[184:187], v[22:25]
	v_mfma_f32_16x16x32_bf16 v[18:21], v[152:155], v[184:187], v[18:21]
	v_mfma_f32_16x16x32_bf16 v[62:65], v[148:151], v[164:167], v[62:65]
	v_mfma_f32_16x16x32_bf16 v[58:61], v[156:159], v[164:167], v[58:61]
	v_mfma_f32_16x16x32_bf16 v[54:57], v[148:151], v[172:175], v[54:57]
	v_mfma_f32_16x16x32_bf16 v[50:53], v[156:159], v[172:175], v[50:53]
	v_mfma_f32_16x16x32_bf16 v[38:41], v[148:151], v[180:183], v[38:41]
	v_mfma_f32_16x16x32_bf16 v[34:37], v[156:159], v[180:183], v[34:37]
	v_mfma_f32_16x16x32_bf16 v[22:25], v[148:151], v[188:191], v[22:25]
	v_mfma_f32_16x16x32_bf16 v[18:21], v[156:159], v[188:191], v[18:21]
	s_barrier
	s_add_u32 s54, s18, 0x80000
	s_addc_u32 s55, s19, 0
	s_add_i32 s53, s56, s42
	s_mov_b32 m0, s53
	s_nop 0
	global_load_lds_dwordx4 v0, s[54:55]
	s_add_i32 m0, s53, 0x2000
	s_nop 0
	global_load_lds_dwordx4 v134, s[54:55]
	s_waitcnt vmcnt(6)
	s_barrier
	v_mfma_f32_16x16x32_bf16 v[46:49], v[192:195], v[160:163], v[46:49]
	v_mfma_f32_16x16x32_bf16 v[42:45], v[200:203], v[160:163], v[42:45]
	v_mfma_f32_16x16x32_bf16 v[30:33], v[192:195], v[168:171], v[30:33]
	v_mfma_f32_16x16x32_bf16 v[26:29], v[200:203], v[168:171], v[26:29]
	v_mfma_f32_16x16x32_bf16 v[14:17], v[192:195], v[176:179], v[14:17]
	v_mfma_f32_16x16x32_bf16 v[10:13], v[200:203], v[176:179], v[10:13]
	v_mfma_f32_16x16x32_bf16 v[6:9], v[192:195], v[184:187], v[6:9]
	v_mfma_f32_16x16x32_bf16 v[2:5], v[200:203], v[184:187], v[2:5]
	v_mfma_f32_16x16x32_bf16 v[46:49], v[196:199], v[164:167], v[46:49]
	v_mfma_f32_16x16x32_bf16 v[42:45], v[204:207], v[164:167], v[42:45]
	v_mfma_f32_16x16x32_bf16 v[30:33], v[196:199], v[172:175], v[30:33]
	v_mfma_f32_16x16x32_bf16 v[26:29], v[204:207], v[172:175], v[26:29]
	v_mfma_f32_16x16x32_bf16 v[14:17], v[196:199], v[180:183], v[14:17]
	v_mfma_f32_16x16x32_bf16 v[10:13], v[204:207], v[180:183], v[10:13]
	v_mfma_f32_16x16x32_bf16 v[6:9], v[196:199], v[188:191], v[6:9]
	v_mfma_f32_16x16x32_bf16 v[2:5], v[204:207], v[188:191], v[2:5]
	s_add_i32 s53, 0, 0x18000
	s_barrier
	ds_read_b128 v[144:147], v250
	ds_read_b128 v[148:151], v250 offset:1024
	ds_read_b128 v[152:155], v250 offset:2048
	ds_read_b128 v[156:159], v250 offset:3072
	s_add_u32 s20, s20, 0x80000
	s_addc_u32 s21, s21, 0
	s_mov_b32 m0, s44
	ds_read_b128 v[160:163], v143 offset:32768
	ds_read_b128 v[164:167], v143 offset:33792
	ds_read_b128 v[168:171], v143 offset:34816
	ds_read_b128 v[172:175], v143 offset:35840
	ds_read_b128 v[176:179], v143 offset:36864
	ds_read_b128 v[180:183], v143 offset:37888
	ds_read_b128 v[184:187], v143 offset:38912
	global_load_lds_dwordx4 v130, s[20:21]
	s_mov_b32 m0, s45
	ds_read_b128 v[188:191], v143 offset:39936
	global_load_lds_dwordx4 v132, s[20:21]
	s_waitcnt lgkmcnt(8)
	s_barrier
; #define PG8_STAGE(bufoff, gbase, voff) do { _Pragma("unroll") for (int _i = 0; _i < 2; ++_i) \
;         __builtin_amdgcn_global_load_lds((const unsigned*)((const char*)(gbase) + (voff)[_i]), (LAS unsigned*)(lds + (bufoff) + ldsw + _i * 8192), 16, 0, 0); } while (0)
; #define PG8_LDA(dst, b, h) do { _Pragma("unroll") for (int m = 0; m < 4; ++m) _Pragma("unroll") for (int k = 0; k < 2; ++k) dst[m][k] = *(const LAS bf16x8*)(lds + PG8_SA(b, h) + aoff + m * 2048 + k * 1024); } while (0)
; #define PG8_LDB(dst, b, h) do { _Pragma("unroll") for (int n = 0; n < 2; ++n) _Pragma("unroll") for (int k = 0; k < 2; ++k) dst[n][k] = *(const LAS bf16x8*)(lds + PG8_SB(b, h) + boff + n * 2048 + k * 1024); } while (0)
; #define PG8_MMA(ai, bj, At, Bt) do { __builtin_amdgcn_s_setprio(1); _Pragma("unroll") for (int m = 0; m < 4; ++m) _Pragma("unroll") for (int n = 0; n < 2; ++n) _Pragma("unroll") for (int k = 0; k < 2; ++k) \
;         acc[ai][bj][m][n] = __builtin_amdgcn_mfma_f32_16x16x32_bf16(Bt[n][k], At[m][k], acc[ai][bj][m][n], 0, 0, 0); __builtin_amdgcn_s_setprio(0); } while (0)
; #define PG8_WAIT_L(n) asm volatile("s_waitcnt lgkmcnt(" #n ")" ::: "memory")
; #define PG8_BAR __builtin_amdgcn_s_barrier()
; #define PG8_SCHED __builtin_amdgcn_sched_barrier(0)
; template <class Epi, class Sched>
; __device__ __forceinline__ void gemm_phase(LAS unsigned char* lds, const Gemm g, const Sched& S, const Epi& E, const int tid) {
;     ...
;             PG8_LDB(B0, 1, 0); PG8_SCHED; PG8_LDA(At, 1, 0); PG8_STAGE(PG8_SA(0, 1), a2 + hstep, voffA);
;             PG8_WAIT_L(8); PG8_BAR; PG8_WAIT_L(0); PG8_MMA(0, 0, At, B0); PG8_BAR; PG8_SCHED;
;             PG8_LDB(B1, 1, 1); PG8_STAGE(PG8_SB(1, 0), b3, voffB);
;             PG8_BAR; PG8_WAIT_L(0); PG8_MMA(0, 1, At, B1); PG8_BAR;
;             PG8_LDA(At, 1, 1); PG8_STAGE(PG8_SA(1, 0), a3, voffA);
;             PG8_BAR; PG8_WAIT_L(0); PG8_MMA(1, 0, At, B0); PG8_BAR; PG8_SCHED;
;             PG8_STAGE(PG8_SB(1, 1), b3 + hstep, voffB);
	s_waitcnt lgkmcnt(0)
	v_mfma_f32_16x16x32_bf16 v[126:129], v[144:147], v[160:163], v[126:129]
	v_mfma_f32_16x16x32_bf16 v[122:125], v[152:155], v[160:163], v[122:125]
	v_mfma_f32_16x16x32_bf16 v[118:121], v[144:147], v[168:171], v[118:121]
	v_mfma_f32_16x16x32_bf16 v[114:117], v[152:155], v[168:171], v[114:117]
	v_mfma_f32_16x16x32_bf16 v[102:105], v[144:147], v[176:179], v[102:105]
	v_mfma_f32_16x16x32_bf16 v[98:101], v[152:155], v[176:179], v[98:101]
	v_mfma_f32_16x16x32_bf16 v[86:89], v[144:147], v[184:187], v[86:89]
	v_mfma_f32_16x16x32_bf16 v[82:85], v[152:155], v[184:187], v[82:85]
	v_mfma_f32_16x16x32_bf16 v[126:129], v[148:151], v[164:167], v[126:129]
	v_mfma_f32_16x16x32_bf16 v[122:125], v[156:159], v[164:167], v[122:125]
	v_mfma_f32_16x16x32_bf16 v[118:121], v[148:151], v[172:175], v[118:121]
	v_mfma_f32_16x16x32_bf16 v[114:117], v[156:159], v[172:175], v[114:117]
	v_mfma_f32_16x16x32_bf16 v[102:105], v[148:151], v[180:183], v[102:105]
	v_mfma_f32_16x16x32_bf16 v[98:101], v[156:159], v[180:183], v[98:101]
	v_mfma_f32_16x16x32_bf16 v[86:89], v[148:151], v[188:191], v[86:89]
	v_mfma_f32_16x16x32_bf16 v[82:85], v[156:159], v[188:191], v[82:85]
	s_barrier
	s_add_i32 s20, 0, 0x1c000
	s_add_i32 s21, s53, s42
	s_add_u32 s98, s18, s36
	s_addc_u32 s99, s19, s37
	s_mov_b32 m0, s21
	ds_read_b128 v[192:195], v249
	ds_read_b128 v[196:199], v249 offset:1024
	ds_read_b128 v[200:203], v249 offset:2048
	ds_read_b128 v[204:207], v249 offset:3072
	global_load_lds_dwordx4 v0, s[98:99]
	s_add_i32 m0, s21, 0x2000
	s_add_u32 s98, s18, s36
	s_addc_u32 s99, s19, s37
	global_load_lds_dwordx4 v134, s[98:99]
	s_barrier
	s_waitcnt lgkmcnt(0)
	v_mfma_f32_16x16x32_bf16 v[110:113], v[192:195], v[160:163], v[110:113]
	v_mfma_f32_16x16x32_bf16 v[106:109], v[200:203], v[160:163], v[106:109]
	v_mfma_f32_16x16x32_bf16 v[94:97], v[192:195], v[168:171], v[94:97]
	v_mfma_f32_16x16x32_bf16 v[90:93], v[200:203], v[168:171], v[90:93]
	v_mfma_f32_16x16x32_bf16 v[78:81], v[192:195], v[176:179], v[78:81]
	v_mfma_f32_16x16x32_bf16 v[74:77], v[200:203], v[176:179], v[74:77]
	v_mfma_f32_16x16x32_bf16 v[70:73], v[192:195], v[184:187], v[70:73]
	v_mfma_f32_16x16x32_bf16 v[66:69], v[200:203], v[184:187], v[66:69]
	v_mfma_f32_16x16x32_bf16 v[110:113], v[196:199], v[164:167], v[110:113]
	v_mfma_f32_16x16x32_bf16 v[106:109], v[204:207], v[164:167], v[106:109]
	v_mfma_f32_16x16x32_bf16 v[94:97], v[196:199], v[172:175], v[94:97]
	v_mfma_f32_16x16x32_bf16 v[90:93], v[204:207], v[172:175], v[90:93]
	v_mfma_f32_16x16x32_bf16 v[78:81], v[196:199], v[180:183], v[78:81]
	v_mfma_f32_16x16x32_bf16 v[74:77], v[204:207], v[180:183], v[74:77]
	v_mfma_f32_16x16x32_bf16 v[70:73], v[196:199], v[188:191], v[70:73]
	v_mfma_f32_16x16x32_bf16 v[66:69], v[204:207], v[188:191], v[66:69]
	s_mov_b32 m0, s28
	v_lshl_add_u64 v[208:209], v[214:215], 0, s[36:37]
	s_barrier
	ds_read_b128 v[160:163], v143 offset:49152
	ds_read_b128 v[164:167], v143 offset:50176
	ds_read_b128 v[168:171], v143 offset:51200
	ds_read_b128 v[172:175], v143 offset:52224
	ds_read_b128 v[176:179], v143 offset:53248
	ds_read_b128 v[180:183], v143 offset:54272
	ds_read_b128 v[184:187], v143 offset:55296
	ds_read_b128 v[188:191], v143 offset:56320
	global_load_lds_dwordx4 v[208:209], off
	s_mov_b32 m0, s29
	v_lshl_add_u64 v[208:209], v[216:217], 0, s[36:37]
	global_load_lds_dwordx4 v[208:209], off
	s_barrier
	s_waitcnt lgkmcnt(0)
	v_mfma_f32_16x16x32_bf16 v[62:65], v[144:147], v[160:163], v[62:65]
	v_mfma_f32_16x16x32_bf16 v[58:61], v[152:155], v[160:163], v[58:61]
	v_mfma_f32_16x16x32_bf16 v[54:57], v[144:147], v[168:171], v[54:57]
	v_mfma_f32_16x16x32_bf16 v[50:53], v[152:155], v[168:171], v[50:53]
	v_mfma_f32_16x16x32_bf16 v[38:41], v[144:147], v[176:179], v[38:41]
	v_mfma_f32_16x16x32_bf16 v[34:37], v[152:155], v[176:179], v[34:37]
	v_mfma_f32_16x16x32_bf16 v[22:25], v[144:147], v[184:187], v[22:25]
	v_mfma_f32_16x16x32_bf16 v[18:21], v[152:155], v[184:187], v[18:21]
	v_mfma_f32_16x16x32_bf16 v[62:65], v[148:151], v[164:167], v[62:65]
	v_mfma_f32_16x16x32_bf16 v[58:61], v[156:159], v[164:167], v[58:61]
	v_mfma_f32_16x16x32_bf16 v[54:57], v[148:151], v[172:175], v[54:57]
	v_mfma_f32_16x16x32_bf16 v[50:53], v[156:159], v[172:175], v[50:53]
	v_mfma_f32_16x16x32_bf16 v[38:41], v[148:151], v[180:183], v[38:41]
	v_mfma_f32_16x16x32_bf16 v[34:37], v[156:159], v[180:183], v[34:37]
	v_mfma_f32_16x16x32_bf16 v[22:25], v[148:151], v[188:191], v[22:25]
	v_mfma_f32_16x16x32_bf16 v[18:21], v[156:159], v[188:191], v[18:21]
	s_barrier
	s_add_u32 s18, s18, 0x80080
	s_addc_u32 s19, s19, 0
	s_add_i32 s20, s20, s42
	s_mov_b32 m0, s20
	s_nop 0
	global_load_lds_dwordx4 v0, s[18:19]
	s_add_i32 m0, s20, 0x2000
	s_nop 0
	global_load_lds_dwordx4 v134, s[18:19]
	s_waitcnt vmcnt(6)
	s_barrier
; DI unsigned cvtpk(float lo, float hi) { const f32x2 v = {lo, hi}; const bf16x2n r = __builtin_convertvector(v, bf16x2n); return __builtin_bit_cast(unsigned, r); }
; #define PG8_MMA(ai, bj, At, Bt) do { __builtin_amdgcn_s_setprio(1); _Pragma("unroll") for (int m = 0; m < 4; ++m) _Pragma("unroll") for (int n = 0; n < 2; ++n) _Pragma("unroll") for (int k = 0; k < 2; ++k) \
;         acc[ai][bj][m][n] = __builtin_amdgcn_mfma_f32_16x16x32_bf16(Bt[n][k], At[m][k], acc[ai][bj][m][n], 0, 0, 0); __builtin_amdgcn_s_setprio(0); } while (0)
; #define PG8_WAIT_V(n) asm volatile("s_waitcnt vmcnt(" #n ")" ::: "memory")
; #define PG8_BAR __builtin_amdgcn_s_barrier()
;     __device__ __forceinline__ void operator()(const f32x4 (&acc)[2][2][4][2], const Unit& u, int wr, int wc, int fr, int fq) const {
;     ...
; #pragma unroll
;         for (int ai = 0; ai < 2; ++ai)
; #pragma unroll
;             for (int m = 0; m < 4; ++m) { bf16_t* rowp = O + (size_t)(row0 + ai * HALF + m * 16) * ldc + col0;
; #pragma unroll
;                 for (int bj = 0; bj < 2; ++bj) { const f32x4 v0 = acc[ai][bj][m][0], v1 = acc[ai][bj][m][1];
;                     u32x4 w; w.x = cvtpk(v0[0], v0[1]); w.y = cvtpk(v0[2], v0[3]); w.z = cvtpk(v1[0], v1[1]); w.w = cvtpk(v1[2], v1[3]);
;                     *(u32x4*)(rowp + bj * HALF) = w; } }
; template <class Epi, class Sched>
; __device__ __forceinline__ void gemm_phase(LAS unsigned char* lds, const Gemm g, const Sched& S, const Epi& E, const int tid) {
;     ...
;             PG8_WAIT_V(6); PG8_BAR; PG8_MMA(1, 1, At, B1); PG8_BAR;
	v_mfma_f32_16x16x32_bf16 v[46:49], v[192:195], v[160:163], v[46:49]
	v_mfma_f32_16x16x32_bf16 v[42:45], v[200:203], v[160:163], v[42:45]
	v_mfma_f32_16x16x32_bf16 v[30:33], v[192:195], v[168:171], v[30:33]
	v_mfma_f32_16x16x32_bf16 v[26:29], v[200:203], v[168:171], v[26:29]
	v_mfma_f32_16x16x32_bf16 v[14:17], v[192:195], v[176:179], v[14:17]
	v_mfma_f32_16x16x32_bf16 v[10:13], v[200:203], v[176:179], v[10:13]
	v_mfma_f32_16x16x32_bf16 v[6:9], v[192:195], v[184:187], v[6:9]
	v_mfma_f32_16x16x32_bf16 v[2:5], v[200:203], v[184:187], v[2:5]
	v_mfma_f32_16x16x32_bf16 v[46:49], v[196:199], v[164:167], v[46:49]
	v_mfma_f32_16x16x32_bf16 v[42:45], v[204:207], v[164:167], v[42:45]
	v_mfma_f32_16x16x32_bf16 v[30:33], v[196:199], v[172:175], v[30:33]
	v_mfma_f32_16x16x32_bf16 v[26:29], v[204:207], v[172:175], v[26:29]
	v_mfma_f32_16x16x32_bf16 v[14:17], v[196:199], v[180:183], v[14:17]
	v_mfma_f32_16x16x32_bf16 v[10:13], v[204:207], v[180:183], v[10:13]
	v_mfma_f32_16x16x32_bf16 v[6:9], v[196:199], v[188:191], v[6:9]
	v_mfma_f32_16x16x32_bf16 v[2:5], v[204:207], v[188:191], v[2:5]
	s_add_i32 s52, s52, 2
	s_add_u32 s16, s16, 0x100
	s_addc_u32 s17, s17, 0
	s_add_u32 s50, s50, 0x100
	s_addc_u32 s51, s51, 0
	s_cmp_gt_u32 s52, 29
	s_barrier
	s_cbranch_scc0 .LBB0_277
	v_lshl_or_b32 v144, s24, 8, v142
	v_lshl_add_u32 v150, s4, 8, v140
	v_ashrrev_i32_e32 v145, 31, v144
	v_mov_b64_e32 v[146:147], s[2:3]
	s_movk_i32 s4, 0x2e00
	v_cvt_pk_bf16_f32 v70, v70, v71
	v_cvt_pk_bf16_f32 v71, v72, v73
	v_cvt_pk_bf16_f32 v72, v66, v67
	v_add_u32_e32 v66, 0x80, v150
	v_mad_i64_i32 v[148:149], s[16:17], v150, s4, v[146:147]
	v_lshlrev_b64 v[144:145], 1, v[144:145]
	v_cvt_pk_bf16_f32 v110, v110, v111
	v_cvt_pk_bf16_f32 v111, v112, v113
	v_cvt_pk_bf16_f32 v112, v106, v107
	v_or_b32_e32 v106, 16, v150
	v_mad_i64_i32 v[66:67], s[16:17], v66, s4, v[146:147]
	v_cvt_pk_bf16_f32 v46, v46, v47
	v_cvt_pk_bf16_f32 v47, v48, v49
	v_cvt_pk_bf16_f32 v48, v42, v43
	v_add_u32_e32 v42, 0x90, v150
	v_lshl_add_u64 v[148:149], v[148:149], 0, v[144:145]
	v_cvt_pk_bf16_f32 v113, v108, v109
	v_mad_i64_i32 v[106:107], s[16:17], v106, s4, v[146:147]
	v_cvt_pk_bf16_f32 v94, v94, v95
	v_cvt_pk_bf16_f32 v95, v96, v97
	v_cvt_pk_bf16_f32 v96, v90, v91
	v_or_b32_e32 v90, 32, v150
	v_lshl_add_u64 v[66:67], v[66:67], 0, v[144:145]
	v_cvt_pk_bf16_f32 v49, v44, v45
	v_mad_i64_i32 v[42:43], s[16:17], v42, s4, v[146:147]
	v_cvt_pk_bf16_f32 v30, v30, v31
	v_cvt_pk_bf16_f32 v31, v32, v33
	v_cvt_pk_bf16_f32 v32, v26, v27
	v_add_u32_e32 v26, 0xa0, v150
	global_store_dwordx4 v[148:149], v[110:113], off offset:256
	v_cvt_pk_bf16_f32 v97, v92, v93
	v_mad_i64_i32 v[90:91], s[16:17], v90, s4, v[146:147]
	v_lshl_add_u64 v[110:111], v[106:107], 0, v[144:145]
	v_cvt_pk_bf16_f32 v78, v78, v79
	v_cvt_pk_bf16_f32 v79, v80, v81
	v_cvt_pk_bf16_f32 v80, v74, v75
	v_or_b32_e32 v74, 48, v150
	global_store_dwordx4 v[66:67], v[46:49], off offset:256
	v_cvt_pk_bf16_f32 v33, v28, v29
	v_mad_i64_i32 v[26:27], s[16:17], v26, s4, v[146:147]
	v_lshl_add_u64 v[46:47], v[42:43], 0, v[144:145]
	v_cvt_pk_bf16_f32 v14, v14, v15
	v_cvt_pk_bf16_f32 v15, v16, v17
	v_cvt_pk_bf16_f32 v16, v10, v11
	v_add_u32_e32 v10, 0xb0, v150
	global_store_dwordx4 v[110:111], v[94:97], off offset:256
	v_cvt_pk_bf16_f32 v81, v76, v77
	v_mad_i64_i32 v[74:75], s[16:17], v74, s4, v[146:147]
	v_lshl_add_u64 v[94:95], v[90:91], 0, v[144:145]
	global_store_dwordx4 v[46:47], v[30:33], off offset:256
	v_cvt_pk_bf16_f32 v17, v12, v13
	v_mad_i64_i32 v[10:11], s[16:17], v10, s4, v[146:147]
	v_lshl_add_u64 v[30:31], v[26:27], 0, v[144:145]
	v_cvt_pk_bf16_f32 v126, v126, v127
	v_cvt_pk_bf16_f32 v127, v128, v129
	v_cvt_pk_bf16_f32 v128, v122, v123
	v_cvt_pk_bf16_f32 v129, v124, v125
	v_cvt_pk_bf16_f32 v106, v118, v119
	v_cvt_pk_bf16_f32 v107, v120, v121
	v_cvt_pk_bf16_f32 v108, v114, v115
	v_cvt_pk_bf16_f32 v109, v116, v117
	v_cvt_pk_bf16_f32 v90, v102, v103
	v_cvt_pk_bf16_f32 v91, v104, v105
	v_cvt_pk_bf16_f32 v92, v98, v99
	v_cvt_pk_bf16_f32 v93, v100, v101
	global_store_dwordx4 v[94:95], v[78:81], off offset:256
	v_cvt_pk_bf16_f32 v76, v82, v83
	v_cvt_pk_bf16_f32 v77, v84, v85
	v_lshl_add_u64 v[78:79], v[74:75], 0, v[144:145]
	v_cvt_pk_bf16_f32 v74, v86, v87
	v_cvt_pk_bf16_f32 v75, v88, v89
	v_cvt_pk_bf16_f32 v73, v68, v69
	v_cvt_pk_bf16_f32 v62, v62, v63
	v_cvt_pk_bf16_f32 v63, v64, v65
	v_cvt_pk_bf16_f32 v64, v58, v59
	v_cvt_pk_bf16_f32 v65, v60, v61
	v_cvt_pk_bf16_f32 v42, v54, v55
	v_cvt_pk_bf16_f32 v43, v56, v57
	v_cvt_pk_bf16_f32 v44, v50, v51
	v_cvt_pk_bf16_f32 v45, v52, v53
	v_cvt_pk_bf16_f32 v26, v38, v39
	v_cvt_pk_bf16_f32 v27, v40, v41
	v_cvt_pk_bf16_f32 v28, v34, v35
	v_cvt_pk_bf16_f32 v29, v36, v37
	global_store_dwordx4 v[30:31], v[14:17], off offset:256
	v_cvt_pk_bf16_f32 v12, v18, v19
	v_cvt_pk_bf16_f32 v13, v20, v21
	v_lshl_add_u64 v[14:15], v[10:11], 0, v[144:145]
	v_cvt_pk_bf16_f32 v10, v22, v23
	v_cvt_pk_bf16_f32 v11, v24, v25
	v_cvt_pk_bf16_f32 v6, v6, v7
	v_cvt_pk_bf16_f32 v7, v8, v9
	v_cvt_pk_bf16_f32 v8, v2, v3
	v_cvt_pk_bf16_f32 v9, v4, v5
	s_and_b64 vcc, exec, s[0:1]
	s_mov_b32 s24, s6
	s_mov_b32 s4, s10
	s_mov_b64 s[18:19], s[14:15]
	s_mov_b64 s[16:17], s[12:13]
	s_mov_b64 s[52:53], 0xc000
	s_mov_b64 s[54:55], 0x8000
	global_store_dwordx4 v[148:149], v[126:129], off
	global_store_dwordx4 v[110:111], v[106:109], off
	global_store_dwordx4 v[94:95], v[90:93], off
	global_store_dwordx4 v[78:79], v[74:77], off
	global_store_dwordx4 v[78:79], v[70:73], off offset:256
	global_store_dwordx4 v[66:67], v[62:65], off
	global_store_dwordx4 v[46:47], v[42:45], off
	global_store_dwordx4 v[30:31], v[26:29], off
	global_store_dwordx4 v[14:15], v[10:13], off
	global_store_dwordx4 v[14:15], v[6:9], off offset:256
	s_cbranch_vccz .LBB0_270
	s_waitcnt vmcnt(0)
	s_cmpk_gt_u32 s22, 0xff
	s_cbranch_scc1 .LBB0_281
	s_barrier

; #define PG8_STAGE(bufoff, gbase, voff) do { _Pragma("unroll") for (int _i = 0; _i < 2; ++_i) \
;         __builtin_amdgcn_global_load_lds((const unsigned*)((const char*)(gbase) + (voff)[_i]), (LAS unsigned*)(lds + (bufoff) + ldsw + _i * 8192), 16, 0, 0); } while (0)
; #define PG8_LDA(dst, b, h) do { _Pragma("unroll") for (int m = 0; m < 4; ++m) _Pragma("unroll") for (int k = 0; k < 2; ++k) dst[m][k] = *(const LAS bf16x8*)(lds + PG8_SA(b, h) + aoff + m * 2048 + k * 1024); } while (0)
; #define PG8_LDB(dst, b, h) do { _Pragma("unroll") for (int n = 0; n < 2; ++n) _Pragma("unroll") for (int k = 0; k < 2; ++k) dst[n][k] = *(const LAS bf16x8*)(lds + PG8_SB(b, h) + boff + n * 2048 + k * 1024); } while (0)
; #define PG8_WAIT_L(n) asm volatile("s_waitcnt lgkmcnt(" #n ")" ::: "memory")
; #define PG8_BAR __builtin_amdgcn_s_barrier()
; template <class Epi, class Sched>
; __device__ __forceinline__ void gemm_phase(LAS unsigned char* lds, const Gemm g, const Sched& S, const Epi& E, const int tid) {
;     ...
;         const bool has_next = S.next(ui + 1, nxt);
;         const char* nA = has_next ? (const char*)g.A + (size_t)nxt.pm * tstep + (size_t)nxt.ks * nxt.nt * kstep : cA; const char* nB = has_next ? (const char*)g.Bt + (size_t)nxt.pn * tstep + (size_t)nxt.ks * nxt.nt * kstep : cB;
;         const int nt = cur.nt;
;         for (int t = 0; t < nt; t += 2) {
;             const bool last = (t == nt - 2);
;             const char* a1 = cA + (size_t)(t + 1) * kstep;
;             const char* a2 = last ? nA : cA + (size_t)(t + 2) * kstep; const char* b2 = last ? nB : cB + (size_t)(t + 2) * kstep;
;             const char* a3 = a2 + kstep; const char* b3 = b2 + kstep;
;             if (last && has_next) S.a_ready(nxt);
;             if constexpr (Epi::PRELOAD) { if (last) E.preload(cur, lds, wid, lane); }
;             PG8_LDB(B0, 0, 0); PG8_SCHED; PG8_LDA(At, 0, 0); PG8_STAGE(PG8_SA(1, 1), a1 + hstep, voffA);
;             PG8_WAIT_L(8); PG8_BAR; PG8_WAIT_L(0); PG8_MMA(0, 0, At, B0); PG8_BAR; PG8_SCHED;
;     ...
; #pragma unroll
;         for (int a = 0; a < 2; ++a)
; #pragma unroll
;             for (int b = 0; b < 2; ++b)
; #pragma unroll
;                 for (int m = 0; m < 4; ++m)
; #pragma unroll
;                     for (int n = 0; n < 2; ++n) acc[a][b][m][n] = (f32x4){0.f, 0.f, 0.f, 0.f};
;         cur = nxt; cA = nA; cB = nB; ++ui;
.LBB0_537:
	s_add_i32 s24, s63, -2
	s_add_u32 s2, s38, 0x80
	s_addc_u32 s3, s39, 0
	s_add_u32 s25, s22, 0x100
	v_mov_b32_e32 v2, 0
	s_addc_u32 s29, s23, 0
	s_mov_b32 s22, 0
	v_mov_b32_e32 v3, v2
	v_mov_b32_e32 v4, v2
	v_mov_b32_e32 v5, v2
	v_mov_b32_e32 v6, v2
	v_mov_b32_e32 v7, v2
	v_mov_b32_e32 v8, v2
	v_mov_b32_e32 v9, v2
	v_mov_b32_e32 v18, v2
	v_mov_b32_e32 v19, v2
	v_mov_b32_e32 v20, v2
	v_mov_b32_e32 v21, v2
	v_mov_b32_e32 v22, v2
	v_mov_b32_e32 v23, v2
	v_mov_b32_e32 v24, v2
	v_mov_b32_e32 v25, v2
	v_mov_b32_e32 v34, v2
	v_mov_b32_e32 v35, v2
	v_mov_b32_e32 v36, v2
	v_mov_b32_e32 v37, v2
	v_mov_b32_e32 v38, v2
	v_mov_b32_e32 v39, v2
	v_mov_b32_e32 v40, v2
	v_mov_b32_e32 v41, v2
	v_mov_b32_e32 v50, v2
	v_mov_b32_e32 v51, v2
	v_mov_b32_e32 v52, v2
	v_mov_b32_e32 v53, v2
	v_mov_b32_e32 v54, v2
	v_mov_b32_e32 v55, v2
	v_mov_b32_e32 v56, v2
	v_mov_b32_e32 v57, v2
	v_mov_b32_e32 v10, v2
	v_mov_b32_e32 v11, v2
	v_mov_b32_e32 v12, v2
	v_mov_b32_e32 v13, v2
	v_mov_b32_e32 v14, v2
	v_mov_b32_e32 v15, v2
	v_mov_b32_e32 v16, v2
	v_mov_b32_e32 v17, v2
	v_mov_b32_e32 v26, v2
	v_mov_b32_e32 v27, v2
	v_mov_b32_e32 v28, v2
	v_mov_b32_e32 v29, v2
	v_mov_b32_e32 v30, v2
	v_mov_b32_e32 v31, v2
	v_mov_b32_e32 v32, v2
	v_mov_b32_e32 v33, v2
	v_mov_b32_e32 v42, v2
	v_mov_b32_e32 v43, v2
	v_mov_b32_e32 v44, v2
	v_mov_b32_e32 v45, v2
	v_mov_b32_e32 v46, v2
	v_mov_b32_e32 v47, v2
	v_mov_b32_e32 v48, v2
	v_mov_b32_e32 v49, v2
	v_mov_b32_e32 v58, v2
	v_mov_b32_e32 v59, v2
	v_mov_b32_e32 v60, v2
	v_mov_b32_e32 v61, v2
	v_mov_b32_e32 v62, v2
	v_mov_b32_e32 v63, v2
	v_mov_b32_e32 v64, v2
	v_mov_b32_e32 v65, v2
	v_mov_b32_e32 v66, v2
	v_mov_b32_e32 v67, v2
	v_mov_b32_e32 v68, v2
	v_mov_b32_e32 v69, v2
	v_mov_b32_e32 v70, v2
	v_mov_b32_e32 v71, v2
	v_mov_b32_e32 v72, v2
	v_mov_b32_e32 v73, v2
	v_mov_b32_e32 v82, v2
	v_mov_b32_e32 v83, v2
	v_mov_b32_e32 v84, v2
	v_mov_b32_e32 v85, v2
	v_mov_b32_e32 v86, v2
	v_mov_b32_e32 v87, v2
	v_mov_b32_e32 v88, v2
	v_mov_b32_e32 v89, v2
	v_mov_b32_e32 v98, v2
	v_mov_b32_e32 v99, v2
	v_mov_b32_e32 v100, v2
	v_mov_b32_e32 v101, v2
	v_mov_b32_e32 v102, v2
	v_mov_b32_e32 v103, v2
	v_mov_b32_e32 v104, v2
	v_mov_b32_e32 v105, v2
	v_mov_b32_e32 v114, v2
	v_mov_b32_e32 v115, v2
	v_mov_b32_e32 v116, v2
	v_mov_b32_e32 v117, v2
	v_mov_b32_e32 v118, v2
	v_mov_b32_e32 v119, v2
	v_mov_b32_e32 v120, v2
	v_mov_b32_e32 v121, v2
	v_mov_b32_e32 v74, v2
	v_mov_b32_e32 v75, v2
	v_mov_b32_e32 v76, v2
	v_mov_b32_e32 v77, v2
	v_mov_b32_e32 v78, v2
	v_mov_b32_e32 v79, v2
	v_mov_b32_e32 v80, v2
	v_mov_b32_e32 v81, v2
	v_mov_b32_e32 v90, v2
	v_mov_b32_e32 v91, v2
	v_mov_b32_e32 v92, v2
	v_mov_b32_e32 v93, v2
	v_mov_b32_e32 v94, v2
	v_mov_b32_e32 v95, v2
	v_mov_b32_e32 v96, v2
	v_mov_b32_e32 v97, v2
	v_mov_b32_e32 v106, v2
	v_mov_b32_e32 v107, v2
	v_mov_b32_e32 v108, v2
	v_mov_b32_e32 v109, v2
	v_mov_b32_e32 v110, v2
	v_mov_b32_e32 v111, v2
	v_mov_b32_e32 v112, v2
	v_mov_b32_e32 v113, v2
	v_mov_b32_e32 v122, v2
	v_mov_b32_e32 v123, v2
	v_mov_b32_e32 v124, v2
	v_mov_b32_e32 v125, v2
	v_mov_b32_e32 v126, v2
	v_mov_b32_e32 v127, v2
	v_mov_b32_e32 v128, v2
	v_mov_b32_e32 v129, v2
	v_add_u32_e32 v252, 0x10000, v160
	v_add_u32_e32 v251, 0x14000, v160
	v_add_u32_e32 v250, 0x18000, v160
	v_add_u32_e32 v249, 0x1c000, v160
.LBB0_538:
	s_add_i32 s74, s22, 2
	s_add_u32 s38, s2, 0x80
	s_addc_u32 s23, s3, 0
	s_add_i32 s75, 0, 0x10000
	ds_read_b128 v[144:147], v252
	ds_read_b128 v[164:167], v252 offset:1024
	ds_read_b128 v[168:171], v252 offset:2048
	ds_read_b128 v[172:175], v252 offset:3072
	s_cmp_eq_u32 s24, s22
	s_cselect_b32 s22, s20, s38
	s_cselect_b32 s23, s21, s23
	s_cselect_b32 s39, s5, s29
	s_cselect_b32 s38, s4, s25
	v_lshl_add_u64 v[148:149], s[2:3], 0, v[138:139]
	s_add_i32 m0, s56, 0xc000
	ds_read_b128 v[176:179], v162
	ds_read_b128 v[180:183], v162 offset:1024
	ds_read_b128 v[184:187], v162 offset:2048
	ds_read_b128 v[188:191], v162 offset:3072
	ds_read_b128 v[192:195], v162 offset:4096
	ds_read_b128 v[196:199], v162 offset:5120
	ds_read_b128 v[200:203], v162 offset:6144
	ds_read_b128 v[204:207], v162 offset:7168
	global_load_lds_dwordx4 v[148:149], off
	s_add_i32 m0, s56, 0xe000
	v_lshl_add_u64 v[148:149], s[2:3], 0, v[140:141]
	global_load_lds_dwordx4 v[148:149], off
	s_waitcnt lgkmcnt(8)
	s_barrier
	s_waitcnt lgkmcnt(0)
	v_mfma_f32_16x16x32_bf16 v[126:129], v[144:147], v[176:179], v[126:129]
	v_mfma_f32_16x16x32_bf16 v[122:125], v[168:171], v[176:179], v[122:125]
	v_mfma_f32_16x16x32_bf16 v[110:113], v[144:147], v[184:187], v[110:113]
	v_mfma_f32_16x16x32_bf16 v[106:109], v[168:171], v[184:187], v[106:109]
	v_mfma_f32_16x16x32_bf16 v[94:97], v[144:147], v[192:195], v[94:97]
	v_mfma_f32_16x16x32_bf16 v[90:93], v[168:171], v[192:195], v[90:93]
	v_mfma_f32_16x16x32_bf16 v[78:81], v[144:147], v[200:203], v[78:81]
	v_mfma_f32_16x16x32_bf16 v[74:77], v[168:171], v[200:203], v[74:77]
	v_mfma_f32_16x16x32_bf16 v[126:129], v[164:167], v[180:183], v[126:129]
	v_mfma_f32_16x16x32_bf16 v[122:125], v[172:175], v[180:183], v[122:125]
	v_mfma_f32_16x16x32_bf16 v[110:113], v[164:167], v[188:191], v[110:113]
	v_mfma_f32_16x16x32_bf16 v[106:109], v[172:175], v[188:191], v[106:109]
	v_mfma_f32_16x16x32_bf16 v[94:97], v[164:167], v[196:199], v[94:97]
	v_mfma_f32_16x16x32_bf16 v[90:93], v[172:175], v[196:199], v[90:93]
	v_mfma_f32_16x16x32_bf16 v[78:81], v[164:167], v[204:207], v[78:81]
	v_mfma_f32_16x16x32_bf16 v[74:77], v[172:175], v[204:207], v[74:77]
	s_barrier
; #define PG8_STAGE(bufoff, gbase, voff) do { _Pragma("unroll") for (int _i = 0; _i < 2; ++_i) \
;         __builtin_amdgcn_global_load_lds((const unsigned*)((const char*)(gbase) + (voff)[_i]), (LAS unsigned*)(lds + (bufoff) + ldsw + _i * 8192), 16, 0, 0); } while (0)
; #define PG8_LDA(dst, b, h) do { _Pragma("unroll") for (int m = 0; m < 4; ++m) _Pragma("unroll") for (int k = 0; k < 2; ++k) dst[m][k] = *(const LAS bf16x8*)(lds + PG8_SA(b, h) + aoff + m * 2048 + k * 1024); } while (0)
; #define PG8_LDB(dst, b, h) do { _Pragma("unroll") for (int n = 0; n < 2; ++n) _Pragma("unroll") for (int k = 0; k < 2; ++k) dst[n][k] = *(const LAS bf16x8*)(lds + PG8_SB(b, h) + boff + n * 2048 + k * 1024); } while (0)
; #define PG8_MMA(ai, bj, At, Bt) do { __builtin_amdgcn_s_setprio(1); _Pragma("unroll") for (int m = 0; m < 4; ++m) _Pragma("unroll") for (int n = 0; n < 2; ++n) _Pragma("unroll") for (int k = 0; k < 2; ++k) \
;         acc[ai][bj][m][n] = __builtin_amdgcn_mfma_f32_16x16x32_bf16(Bt[n][k], At[m][k], acc[ai][bj][m][n], 0, 0, 0); __builtin_amdgcn_s_setprio(0); } while (0)
; #define PG8_WAIT_V(n) asm volatile("s_waitcnt vmcnt(" #n ")" ::: "memory")
; #define PG8_WAIT_L(n) asm volatile("s_waitcnt lgkmcnt(" #n ")" ::: "memory")
; template <class Epi, class Sched>
; __device__ __forceinline__ void gemm_phase(LAS unsigned char* lds, const Gemm g, const Sched& S, const Epi& E, const int tid) {
;     ...
;             PG8_LDB(B1, 0, 1); PG8_STAGE(PG8_SB(0, 0), b2, voffB);
;             PG8_BAR; PG8_WAIT_L(0); PG8_MMA(0, 1, At, B1); PG8_BAR;
;             PG8_LDA(At, 0, 1); PG8_STAGE(PG8_SA(0, 0), a2, voffA);
;             PG8_BAR; PG8_WAIT_L(0); PG8_MMA(1, 0, At, B0); PG8_BAR; PG8_SCHED;
;             PG8_STAGE(PG8_SB(0, 1), b2 + hstep, voffB);
;             PG8_WAIT_V(6); PG8_BAR; PG8_MMA(1, 1, At, B1); PG8_BAR;
;             PG8_LDB(B0, 1, 0); PG8_SCHED; PG8_LDA(At, 1, 0); PG8_STAGE(PG8_SA(0, 1), a2 + hstep, voffA);
;             PG8_WAIT_L(8); PG8_BAR; PG8_WAIT_L(0); PG8_MMA(0, 0, At, B0); PG8_BAR; PG8_SCHED;
;             PG8_LDB(B1, 1, 1); PG8_STAGE(PG8_SB(1, 0), b3, voffB);
;             PG8_BAR; PG8_WAIT_L(0); PG8_MMA(0, 1, At, B1); PG8_BAR;
;             PG8_LDA(At, 1, 1); PG8_STAGE(PG8_SA(1, 0), a3, voffA);
;             PG8_BAR; PG8_WAIT_L(0); PG8_MMA(1, 0, At, B0); PG8_BAR; PG8_SCHED;
;             PG8_STAGE(PG8_SB(1, 1), b3 + hstep, voffB);
	s_add_i32 s76, 0, 0x14000
	s_add_i32 s75, s75, s51
	v_lshl_add_u64 v[148:149], s[38:39], 0, v[132:133]
	s_mov_b32 m0, s75
	ds_read_b128 v[208:211], v251
	ds_read_b128 v[214:217], v251 offset:1024
	ds_read_b128 v[218:221], v251 offset:2048
	ds_read_b128 v[222:225], v251 offset:3072
	global_load_lds_dwordx4 v[148:149], off
	s_add_i32 m0, s75, 0x2000
	v_lshl_add_u64 v[226:227], s[38:39], 0, v[136:137]
	global_load_lds_dwordx4 v[226:227], off
	s_barrier
	s_waitcnt lgkmcnt(0)
	v_mfma_f32_16x16x32_bf16 v[118:121], v[208:211], v[176:179], v[118:121]
	v_mfma_f32_16x16x32_bf16 v[114:117], v[218:221], v[176:179], v[114:117]
	v_mfma_f32_16x16x32_bf16 v[102:105], v[208:211], v[184:187], v[102:105]
	v_mfma_f32_16x16x32_bf16 v[98:101], v[218:221], v[184:187], v[98:101]
	v_mfma_f32_16x16x32_bf16 v[86:89], v[208:211], v[192:195], v[86:89]
	v_mfma_f32_16x16x32_bf16 v[82:85], v[218:221], v[192:195], v[82:85]
	v_mfma_f32_16x16x32_bf16 v[70:73], v[208:211], v[200:203], v[70:73]
	v_mfma_f32_16x16x32_bf16 v[66:69], v[218:221], v[200:203], v[66:69]
	v_mfma_f32_16x16x32_bf16 v[118:121], v[214:217], v[180:183], v[118:121]
	v_mfma_f32_16x16x32_bf16 v[114:117], v[222:225], v[180:183], v[114:117]
	v_mfma_f32_16x16x32_bf16 v[102:105], v[214:217], v[188:191], v[102:105]
	v_mfma_f32_16x16x32_bf16 v[98:101], v[222:225], v[188:191], v[98:101]
	v_mfma_f32_16x16x32_bf16 v[86:89], v[214:217], v[196:199], v[86:89]
	v_mfma_f32_16x16x32_bf16 v[82:85], v[222:225], v[196:199], v[82:85]
	v_mfma_f32_16x16x32_bf16 v[70:73], v[214:217], v[204:207], v[70:73]
	v_mfma_f32_16x16x32_bf16 v[66:69], v[222:225], v[204:207], v[66:69]
	s_mov_b32 m0, s56
	v_lshl_add_u64 v[228:229], s[22:23], 0, v[130:131]
	s_barrier
	ds_read_b128 v[176:179], v162 offset:16384
	ds_read_b128 v[180:183], v162 offset:17408
	ds_read_b128 v[184:187], v162 offset:18432
	ds_read_b128 v[188:191], v162 offset:19456
	ds_read_b128 v[192:195], v162 offset:20480
	ds_read_b128 v[196:199], v162 offset:21504
	ds_read_b128 v[200:203], v162 offset:22528
	ds_read_b128 v[204:207], v162 offset:23552
	global_load_lds_dwordx4 v[228:229], off
	s_mov_b32 m0, s57
	v_lshl_add_u64 v[230:231], s[22:23], 0, v[134:135]
	global_load_lds_dwordx4 v[230:231], off
	s_barrier
	s_waitcnt lgkmcnt(0)
	v_mfma_f32_16x16x32_bf16 v[62:65], v[144:147], v[176:179], v[62:65]
	v_mfma_f32_16x16x32_bf16 v[58:61], v[168:171], v[176:179], v[58:61]
	v_mfma_f32_16x16x32_bf16 v[46:49], v[144:147], v[184:187], v[46:49]
	v_mfma_f32_16x16x32_bf16 v[42:45], v[168:171], v[184:187], v[42:45]
	v_mfma_f32_16x16x32_bf16 v[30:33], v[144:147], v[192:195], v[30:33]
	v_mfma_f32_16x16x32_bf16 v[26:29], v[168:171], v[192:195], v[26:29]
	v_mfma_f32_16x16x32_bf16 v[14:17], v[144:147], v[200:203], v[14:17]
	v_mfma_f32_16x16x32_bf16 v[10:13], v[168:171], v[200:203], v[10:13]
	v_mfma_f32_16x16x32_bf16 v[62:65], v[164:167], v[180:183], v[62:65]
	v_mfma_f32_16x16x32_bf16 v[58:61], v[172:175], v[180:183], v[58:61]
	v_mfma_f32_16x16x32_bf16 v[46:49], v[164:167], v[188:191], v[46:49]
	v_mfma_f32_16x16x32_bf16 v[42:45], v[172:175], v[188:191], v[42:45]
	v_mfma_f32_16x16x32_bf16 v[30:33], v[164:167], v[196:199], v[30:33]
	v_mfma_f32_16x16x32_bf16 v[26:29], v[172:175], v[196:199], v[26:29]
	v_mfma_f32_16x16x32_bf16 v[14:17], v[164:167], v[204:207], v[14:17]
	v_mfma_f32_16x16x32_bf16 v[10:13], v[172:175], v[204:207], v[10:13]
	s_barrier
	s_add_u32 s38, s38, s8
	s_addc_u32 s39, s39, 0
	s_add_i32 s75, s76, s51
	v_lshl_add_u64 v[244:245], s[38:39], 0, v[132:133]
	s_mov_b32 m0, s75
	v_lshl_add_u64 v[246:247], s[38:39], 0, v[136:137]
	global_load_lds_dwordx4 v[244:245], off
	s_add_i32 m0, s75, 0x2000
	s_nop 0
	global_load_lds_dwordx4 v[246:247], off
	s_waitcnt vmcnt(6)
	s_barrier
	v_mfma_f32_16x16x32_bf16 v[54:57], v[208:211], v[176:179], v[54:57]
	v_mfma_f32_16x16x32_bf16 v[50:53], v[218:221], v[176:179], v[50:53]
	v_mfma_f32_16x16x32_bf16 v[38:41], v[208:211], v[184:187], v[38:41]
	v_mfma_f32_16x16x32_bf16 v[34:37], v[218:221], v[184:187], v[34:37]
	v_mfma_f32_16x16x32_bf16 v[22:25], v[208:211], v[192:195], v[22:25]
	v_mfma_f32_16x16x32_bf16 v[18:21], v[218:221], v[192:195], v[18:21]
	v_mfma_f32_16x16x32_bf16 v[6:9], v[208:211], v[200:203], v[6:9]
	v_mfma_f32_16x16x32_bf16 v[2:5], v[218:221], v[200:203], v[2:5]
	v_mfma_f32_16x16x32_bf16 v[54:57], v[214:217], v[180:183], v[54:57]
	v_mfma_f32_16x16x32_bf16 v[50:53], v[222:225], v[180:183], v[50:53]
	v_mfma_f32_16x16x32_bf16 v[38:41], v[214:217], v[188:191], v[38:41]
	v_mfma_f32_16x16x32_bf16 v[34:37], v[222:225], v[188:191], v[34:37]
	v_mfma_f32_16x16x32_bf16 v[22:25], v[214:217], v[196:199], v[22:25]
	v_mfma_f32_16x16x32_bf16 v[18:21], v[222:225], v[196:199], v[18:21]
	v_mfma_f32_16x16x32_bf16 v[6:9], v[214:217], v[204:207], v[6:9]
	v_mfma_f32_16x16x32_bf16 v[2:5], v[222:225], v[204:207], v[2:5]
	s_add_i32 s38, 0, 0x18000
	s_barrier
	ds_read_b128 v[144:147], v250
	ds_read_b128 v[164:167], v250 offset:1024
	ds_read_b128 v[168:171], v250 offset:2048
	ds_read_b128 v[172:175], v250 offset:3072
	s_add_u32 s22, s22, s8
	s_addc_u32 s23, s23, 0
	s_mov_b32 m0, s58
	ds_read_b128 v[176:179], v162 offset:32768
	ds_read_b128 v[180:183], v162 offset:33792
	ds_read_b128 v[184:187], v162 offset:34816
	ds_read_b128 v[188:191], v162 offset:35840
	ds_read_b128 v[192:195], v162 offset:36864
	ds_read_b128 v[196:199], v162 offset:37888
	ds_read_b128 v[200:203], v162 offset:38912
	global_load_lds_dwordx4 v130, s[22:23]
	s_mov_b32 m0, s59
	ds_read_b128 v[204:207], v162 offset:39936
	global_load_lds_dwordx4 v134, s[22:23]
	s_waitcnt lgkmcnt(8)
	s_barrier
; #define PG8_STAGE(bufoff, gbase, voff) do { _Pragma("unroll") for (int _i = 0; _i < 2; ++_i) \
;         __builtin_amdgcn_global_load_lds((const unsigned*)((const char*)(gbase) + (voff)[_i]), (LAS unsigned*)(lds + (bufoff) + ldsw + _i * 8192), 16, 0, 0); } while (0)
; #define PG8_LDA(dst, b, h) do { _Pragma("unroll") for (int m = 0; m < 4; ++m) _Pragma("unroll") for (int k = 0; k < 2; ++k) dst[m][k] = *(const LAS bf16x8*)(lds + PG8_SA(b, h) + aoff + m * 2048 + k * 1024); } while (0)
; #define PG8_LDB(dst, b, h) do { _Pragma("unroll") for (int n = 0; n < 2; ++n) _Pragma("unroll") for (int k = 0; k < 2; ++k) dst[n][k] = *(const LAS bf16x8*)(lds + PG8_SB(b, h) + boff + n * 2048 + k * 1024); } while (0)
; #define PG8_MMA(ai, bj, At, Bt) do { __builtin_amdgcn_s_setprio(1); _Pragma("unroll") for (int m = 0; m < 4; ++m) _Pragma("unroll") for (int n = 0; n < 2; ++n) _Pragma("unroll") for (int k = 0; k < 2; ++k) \
;         acc[ai][bj][m][n] = __builtin_amdgcn_mfma_f32_16x16x32_bf16(Bt[n][k], At[m][k], acc[ai][bj][m][n], 0, 0, 0); __builtin_amdgcn_s_setprio(0); } while (0)
; #define PG8_WAIT_L(n) asm volatile("s_waitcnt lgkmcnt(" #n ")" ::: "memory")
; #define PG8_BAR __builtin_amdgcn_s_barrier()
; #define PG8_SCHED __builtin_amdgcn_sched_barrier(0)
; template <class Epi, class Sched>
; __device__ __forceinline__ void gemm_phase(LAS unsigned char* lds, const Gemm g, const Sched& S, const Epi& E, const int tid) {
;     ...
;             PG8_LDB(B0, 1, 0); PG8_SCHED; PG8_LDA(At, 1, 0); PG8_STAGE(PG8_SA(0, 1), a2 + hstep, voffA);
;             PG8_WAIT_L(8); PG8_BAR; PG8_WAIT_L(0); PG8_MMA(0, 0, At, B0); PG8_BAR; PG8_SCHED;
;             PG8_LDB(B1, 1, 1); PG8_STAGE(PG8_SB(1, 0), b3, voffB);
;             PG8_BAR; PG8_WAIT_L(0); PG8_MMA(0, 1, At, B1); PG8_BAR;
;             PG8_LDA(At, 1, 1); PG8_STAGE(PG8_SA(1, 0), a3, voffA);
;             PG8_BAR; PG8_WAIT_L(0); PG8_MMA(1, 0, At, B0); PG8_BAR; PG8_SCHED;
;             PG8_STAGE(PG8_SB(1, 1), b3 + hstep, voffB);
	s_waitcnt lgkmcnt(0)
	v_mfma_f32_16x16x32_bf16 v[126:129], v[144:147], v[176:179], v[126:129]
	v_mfma_f32_16x16x32_bf16 v[122:125], v[168:171], v[176:179], v[122:125]
	v_mfma_f32_16x16x32_bf16 v[110:113], v[144:147], v[184:187], v[110:113]
	v_mfma_f32_16x16x32_bf16 v[106:109], v[168:171], v[184:187], v[106:109]
	v_mfma_f32_16x16x32_bf16 v[94:97], v[144:147], v[192:195], v[94:97]
	v_mfma_f32_16x16x32_bf16 v[90:93], v[168:171], v[192:195], v[90:93]
	v_mfma_f32_16x16x32_bf16 v[78:81], v[144:147], v[200:203], v[78:81]
	v_mfma_f32_16x16x32_bf16 v[74:77], v[168:171], v[200:203], v[74:77]
	v_mfma_f32_16x16x32_bf16 v[126:129], v[164:167], v[180:183], v[126:129]
	v_mfma_f32_16x16x32_bf16 v[122:125], v[172:175], v[180:183], v[122:125]
	v_mfma_f32_16x16x32_bf16 v[110:113], v[164:167], v[188:191], v[110:113]
	v_mfma_f32_16x16x32_bf16 v[106:109], v[172:175], v[188:191], v[106:109]
	v_mfma_f32_16x16x32_bf16 v[94:97], v[164:167], v[196:199], v[94:97]
	v_mfma_f32_16x16x32_bf16 v[90:93], v[172:175], v[196:199], v[90:93]
	v_mfma_f32_16x16x32_bf16 v[78:81], v[164:167], v[204:207], v[78:81]
	v_mfma_f32_16x16x32_bf16 v[74:77], v[172:175], v[204:207], v[74:77]
	s_barrier
	s_add_i32 s22, 0, 0x1c000
	s_add_i32 s23, s38, s51
	v_lshl_add_u64 v[148:149], v[148:149], 0, s[36:37]
	s_mov_b32 m0, s23
	ds_read_b128 v[208:211], v249
	ds_read_b128 v[214:217], v249 offset:1024
	ds_read_b128 v[218:221], v249 offset:2048
	ds_read_b128 v[222:225], v249 offset:3072
	global_load_lds_dwordx4 v[148:149], off
	s_add_i32 m0, s23, 0x2000
	v_lshl_add_u64 v[148:149], v[226:227], 0, s[36:37]
	global_load_lds_dwordx4 v[148:149], off
	s_barrier
	s_waitcnt lgkmcnt(0)
	v_mfma_f32_16x16x32_bf16 v[118:121], v[208:211], v[176:179], v[118:121]
	v_mfma_f32_16x16x32_bf16 v[114:117], v[218:221], v[176:179], v[114:117]
	v_mfma_f32_16x16x32_bf16 v[102:105], v[208:211], v[184:187], v[102:105]
	v_mfma_f32_16x16x32_bf16 v[98:101], v[218:221], v[184:187], v[98:101]
	v_mfma_f32_16x16x32_bf16 v[86:89], v[208:211], v[192:195], v[86:89]
	v_mfma_f32_16x16x32_bf16 v[82:85], v[218:221], v[192:195], v[82:85]
	v_mfma_f32_16x16x32_bf16 v[70:73], v[208:211], v[200:203], v[70:73]
	v_mfma_f32_16x16x32_bf16 v[66:69], v[218:221], v[200:203], v[66:69]
	v_mfma_f32_16x16x32_bf16 v[118:121], v[214:217], v[180:183], v[118:121]
	v_mfma_f32_16x16x32_bf16 v[114:117], v[222:225], v[180:183], v[114:117]
	v_mfma_f32_16x16x32_bf16 v[102:105], v[214:217], v[188:191], v[102:105]
	v_mfma_f32_16x16x32_bf16 v[98:101], v[222:225], v[188:191], v[98:101]
	v_mfma_f32_16x16x32_bf16 v[86:89], v[214:217], v[196:199], v[86:89]
	v_mfma_f32_16x16x32_bf16 v[82:85], v[222:225], v[196:199], v[82:85]
	v_mfma_f32_16x16x32_bf16 v[70:73], v[214:217], v[204:207], v[70:73]
	v_mfma_f32_16x16x32_bf16 v[66:69], v[222:225], v[204:207], v[66:69]
	s_mov_b32 m0, s61
	v_lshl_add_u64 v[148:149], v[228:229], 0, s[36:37]
	s_barrier
	ds_read_b128 v[176:179], v162 offset:49152
	ds_read_b128 v[180:183], v162 offset:50176
	ds_read_b128 v[184:187], v162 offset:51200
	ds_read_b128 v[188:191], v162 offset:52224
	ds_read_b128 v[192:195], v162 offset:53248
	ds_read_b128 v[196:199], v162 offset:54272
	ds_read_b128 v[200:203], v162 offset:55296
	ds_read_b128 v[204:207], v162 offset:56320
	global_load_lds_dwordx4 v[148:149], off
	s_mov_b32 m0, s62
	v_lshl_add_u64 v[148:149], v[230:231], 0, s[36:37]
	global_load_lds_dwordx4 v[148:149], off
	s_barrier
; #define PG8_STAGE(bufoff, gbase, voff) do { _Pragma("unroll") for (int _i = 0; _i < 2; ++_i) \
;         __builtin_amdgcn_global_load_lds((const unsigned*)((const char*)(gbase) + (voff)[_i]), (LAS unsigned*)(lds + (bufoff) + ldsw + _i * 8192), 16, 0, 0); } while (0)
; #define PG8_LDA(dst, b, h) do { _Pragma("unroll") for (int m = 0; m < 4; ++m) _Pragma("unroll") for (int k = 0; k < 2; ++k) dst[m][k] = *(const LAS bf16x8*)(lds + PG8_SA(b, h) + aoff + m * 2048 + k * 1024); } while (0)
; #define PG8_MMA(ai, bj, At, Bt) do { __builtin_amdgcn_s_setprio(1); _Pragma("unroll") for (int m = 0; m < 4; ++m) _Pragma("unroll") for (int n = 0; n < 2; ++n) _Pragma("unroll") for (int k = 0; k < 2; ++k) \
;         acc[ai][bj][m][n] = __builtin_amdgcn_mfma_f32_16x16x32_bf16(Bt[n][k], At[m][k], acc[ai][bj][m][n], 0, 0, 0); __builtin_amdgcn_s_setprio(0); } while (0)
; #define PG8_WAIT_V(n) asm volatile("s_waitcnt vmcnt(" #n ")" ::: "memory")
; #define PG8_WAIT_L(n) asm volatile("s_waitcnt lgkmcnt(" #n ")" ::: "memory")
; #define PG8_BAR __builtin_amdgcn_s_barrier()
;     __device__ __forceinline__ void operator()(const f32x4 (&acc)[2][2][4][2], const Unit& u, int wr, int wc, int fr, int fq) const {
;     ...
;             for (int m = 0; m < 4; ++m) { const int row = row0 + ai * HALF + m * 16; int b, tok; if (row < MLAT) { b = row >> 13; tok = CTX + (row & (SEQ - 1)); } else { b = (row - MLAT) >> 8; tok = (row - MLAT) & (CTX - 1); }
; #pragma unroll
;                 for (int bj = 0; bj < 2; ++bj) { const int col = col0 + bj * HALF; bf16_t* dst;
;                     if (mode == 0) { const int h = col / 192, d = col - h * 192; dst = Q + ((size_t)(b * 4 + h) * LTOT + tok) * 192 + d; }
;                     else { const int h = col >> 8, d = col & 255; dst = d < 128 ? K + ((size_t)(b * 4 + h) * LTOT + tok) * 192 + d : V + ((size_t)(b * 4 + h) * LTOT + tok) * 128 + (d - 128); }
; template <class Epi, class Sched>
; __device__ __forceinline__ void gemm_phase(LAS unsigned char* lds, const Gemm g, const Sched& S, const Epi& E, const int tid) {
;     ...
;             PG8_BAR; PG8_WAIT_L(0); PG8_MMA(0, 1, At, B1); PG8_BAR;
;             PG8_LDA(At, 1, 1); PG8_STAGE(PG8_SA(1, 0), a3, voffA);
;             PG8_BAR; PG8_WAIT_L(0); PG8_MMA(1, 0, At, B0); PG8_BAR; PG8_SCHED;
;             PG8_STAGE(PG8_SB(1, 1), b3 + hstep, voffB);
;             PG8_WAIT_V(6); PG8_BAR; PG8_MMA(1, 1, At, B1); PG8_BAR;
	s_waitcnt lgkmcnt(0)
	v_mfma_f32_16x16x32_bf16 v[62:65], v[144:147], v[176:179], v[62:65]
	v_mfma_f32_16x16x32_bf16 v[58:61], v[168:171], v[176:179], v[58:61]
	v_mfma_f32_16x16x32_bf16 v[46:49], v[144:147], v[184:187], v[46:49]
	v_mfma_f32_16x16x32_bf16 v[42:45], v[168:171], v[184:187], v[42:45]
	v_mfma_f32_16x16x32_bf16 v[30:33], v[144:147], v[192:195], v[30:33]
	v_mfma_f32_16x16x32_bf16 v[26:29], v[168:171], v[192:195], v[26:29]
	v_mfma_f32_16x16x32_bf16 v[14:17], v[144:147], v[200:203], v[14:17]
	v_mfma_f32_16x16x32_bf16 v[10:13], v[168:171], v[200:203], v[10:13]
	v_mfma_f32_16x16x32_bf16 v[62:65], v[164:167], v[180:183], v[62:65]
	v_mfma_f32_16x16x32_bf16 v[58:61], v[172:175], v[180:183], v[58:61]
	v_mfma_f32_16x16x32_bf16 v[46:49], v[164:167], v[188:191], v[46:49]
	v_mfma_f32_16x16x32_bf16 v[42:45], v[172:175], v[188:191], v[42:45]
	v_mfma_f32_16x16x32_bf16 v[30:33], v[164:167], v[196:199], v[30:33]
	v_mfma_f32_16x16x32_bf16 v[26:29], v[172:175], v[196:199], v[26:29]
	v_mfma_f32_16x16x32_bf16 v[14:17], v[164:167], v[204:207], v[14:17]
	v_mfma_f32_16x16x32_bf16 v[10:13], v[172:175], v[204:207], v[10:13]
	s_barrier
	s_add_i32 s22, s22, s51
	s_mov_b32 m0, s22
	v_lshl_add_u64 v[144:145], v[244:245], 0, s[36:37]
	global_load_lds_dwordx4 v[144:145], off
	s_add_i32 m0, s22, 0x2000
	v_lshl_add_u64 v[144:145], v[246:247], 0, s[36:37]
	global_load_lds_dwordx4 v[144:145], off
	s_waitcnt vmcnt(6)
	s_barrier
	v_mfma_f32_16x16x32_bf16 v[54:57], v[208:211], v[176:179], v[54:57]
	v_mfma_f32_16x16x32_bf16 v[50:53], v[218:221], v[176:179], v[50:53]
	v_mfma_f32_16x16x32_bf16 v[38:41], v[208:211], v[184:187], v[38:41]
	v_mfma_f32_16x16x32_bf16 v[34:37], v[218:221], v[184:187], v[34:37]
	v_mfma_f32_16x16x32_bf16 v[22:25], v[208:211], v[192:195], v[22:25]
	v_mfma_f32_16x16x32_bf16 v[18:21], v[218:221], v[192:195], v[18:21]
	v_mfma_f32_16x16x32_bf16 v[6:9], v[208:211], v[200:203], v[6:9]
	v_mfma_f32_16x16x32_bf16 v[2:5], v[218:221], v[200:203], v[2:5]
	v_mfma_f32_16x16x32_bf16 v[54:57], v[214:217], v[180:183], v[54:57]
	v_mfma_f32_16x16x32_bf16 v[50:53], v[222:225], v[180:183], v[50:53]
	v_mfma_f32_16x16x32_bf16 v[38:41], v[214:217], v[188:191], v[38:41]
	v_mfma_f32_16x16x32_bf16 v[34:37], v[222:225], v[188:191], v[34:37]
	v_mfma_f32_16x16x32_bf16 v[22:25], v[214:217], v[196:199], v[22:25]
	v_mfma_f32_16x16x32_bf16 v[18:21], v[222:225], v[196:199], v[18:21]
	v_mfma_f32_16x16x32_bf16 v[6:9], v[214:217], v[204:207], v[6:9]
	v_mfma_f32_16x16x32_bf16 v[2:5], v[222:225], v[204:207], v[2:5]
	s_add_u32 s2, s2, 0x100
	s_addc_u32 s3, s3, 0
	s_add_u32 s25, s25, 0x100
	s_addc_u32 s29, s29, 0
	s_cmp_ge_i32 s74, s63
	s_mov_b32 s22, s74
	s_barrier
	s_cbranch_scc0 .LBB0_538
	s_lshl_b32 s24, s28, 8
	s_add_i32 s24, s24, s64
	s_add_i32 s2, s24, 0xffffc000
	v_mov_b32_e32 v0, 0x1fcf
	v_or_b32_e32 v163, s24, v156
	s_lshr_b32 s25, s2, 8
	v_bitop3_b32 v0, s24, v0, v156 bitop3:0xc8
	v_mov_b32_e32 v144, 0xcf
	s_movk_i32 s2, 0x4000
	s_ashr_i32 s28, s24, 13
	v_add_u32_e32 v0, 0x100, v0
	v_bitop3_b32 v144, s24, v144, v156 bitop3:0xc8
	v_cmp_gt_i32_e32 vcc, s2, v163
	v_mov_b32_e32 v145, s28
	v_lshl_or_b32 v142, s60, 8, v161
	v_cndmask_b32_e32 v0, v144, v0, vcc
	v_mov_b32_e32 v144, s25
	v_cndmask_b32_e32 v144, v144, v145, vcc
	v_lshlrev_b32_e32 v166, 2, v144
	v_add_u32_e32 v144, s60, v166
	v_mad_i64_i32 v[146:147], s[2:3], v144, s33, v[0:1]
	v_and_b32_e32 v144, 0x78, v142
	s_mov_b64 s[2:3], -1
	s_and_b64 vcc, exec, s[14:15]
	v_lshlrev_b32_e32 v144, 1, v144
	s_cbranch_vccz .LBB0_541
	v_mov_b64_e32 v[148:149], s[10:11]
	v_mad_u64_u32 v[148:149], s[2:3], v146, s27, v[148:149]
	v_mov_b32_e32 v164, v149
	v_mad_u64_u32 v[164:165], s[2:3], v147, s27, v[164:165]
	v_mov_b32_e32 v149, v164
	v_mov_b32_e32 v145, v1
	v_lshl_add_u64 v[148:149], v[148:149], 0, v[144:145]
	s_mov_b64 s[2:3], 0

; #define PG8_STAGE(bufoff, gbase, voff) do { _Pragma("unroll") for (int _i = 0; _i < 2; ++_i) \
;         __builtin_amdgcn_global_load_lds((const unsigned*)((const char*)(gbase) + (voff)[_i]), (LAS unsigned*)(lds + (bufoff) + ldsw + _i * 8192), 16, 0, 0); } while (0)
; #define PG8_WAIT_V(n) asm volatile("s_waitcnt vmcnt(" #n ")" ::: "memory")
; #define PG8_BAR __builtin_amdgcn_s_barrier()
; template <class Epi, class Sched>
; __device__ __forceinline__ void gemm_phase(LAS unsigned char* lds, const Gemm g, const Sched& S, const Epi& E, const int tid) {
;     ...
;     f32x4 acc[2][2][4][2];
; #pragma unroll
;     for (int a = 0; a < 2; ++a)
; #pragma unroll
;         for (int b = 0; b < 2; ++b)
; #pragma unroll
;             for (int m = 0; m < 4; ++m)
; #pragma unroll
;                 for (int n = 0; n < 2; ++n) acc[a][b][m][n] = (f32x4){0.f, 0.f, 0.f, 0.f};
;     bf16x8 At[4][2], B0[2][2], B1[2][2];
;     const char* cA = (const char*)g.A + (size_t)cur.pm * tstep + (size_t)cur.ks * cur.nt * kstep; const char* cB = (const char*)g.Bt + (size_t)cur.pn * tstep + (size_t)cur.ks * cur.nt * kstep;
;     S.a_ready(cur);
;     PG8_STAGE(PG8_SB(0, 0), cB, voffB); PG8_STAGE(PG8_SA(0, 0), cA, voffA); PG8_STAGE(PG8_SB(0, 1), cB + hstep, voffB); PG8_STAGE(PG8_SA(0, 1), cA + hstep, voffA);
;     if (wr == 1) PG8_BAR;
;     PG8_WAIT_V(4); PG8_BAR;
;     PG8_STAGE(PG8_SB(1, 0), cB + kstep, voffB); PG8_STAGE(PG8_SA(1, 0), cA + kstep, voffA); PG8_STAGE(PG8_SB(1, 1), cB + hstep + kstep, voffB);
;     PG8_WAIT_V(6); PG8_BAR;
.LBB0_1207:
	v_and_b32_e32 v222, 15, v221
	v_and_b32_e32 v16, 48, v221
	v_lshlrev_b32_e32 v17, 2, v221
	s_and_b32 s17, s39, 3
	s_lshl_b32 s22, s41, 13
	v_lshl_or_b32 v16, v222, 6, v16
	v_and_b32_e32 v17, 32, v17
	s_add_i32 m0, s25, 0x18000
	v_lshl_add_u64 v[8:9], v[8:9], 0, s[36:37]
	v_bitop3_b32 v18, v16, s22, v17 bitop3:0xde
	s_lshl_b32 s22, s17, 12
	s_waitcnt vmcnt(4)
	s_barrier
	global_load_lds_dwordx4 v[8:9], off
	v_lshl_add_u64 v[6:7], v[6:7], 0, s[36:37]
	s_add_i32 m0, s25, 0x1a000
	s_add_i32 s43, s25, 0x8000
	s_add_i32 s44, s25, 0xa000
	v_bitop3_b32 v140, s22, v16, v17 bitop3:0xf6
	global_load_lds_dwordx4 v[6:7], off
	v_lshl_add_u64 v[4:5], v[4:5], 0, s[36:37]
	s_mov_b32 m0, s43
	s_add_u32 s22, s0, 0x80080
	global_load_lds_dwordx4 v[4:5], off
	v_lshl_add_u64 v[2:3], v[2:3], 0, s[36:37]
	s_mov_b32 m0, s44
	s_addc_u32 s23, s1, 0
	global_load_lds_dwordx4 v[2:3], off
	s_add_i32 m0, s25, 0x1c000
	v_lshl_add_u64 v[2:3], s[22:23], 0, v[0:1]
	global_load_lds_dwordx4 v[2:3], off
	v_lshl_add_u64 v[2:3], s[22:23], 0, v[134:135]
	s_add_i32 m0, s25, 0x1e000
	s_add_i32 s19, s19, s18
	global_load_lds_dwordx4 v[2:3], off
	s_sub_i32 s18, s19, s21
	s_mul_i32 s20, s20, 28
	s_sub_i32 s18, s18, s20
	v_lshlrev_b32_e32 v2, 15, v10
	s_ashr_i32 s19, s18, 31
	v_and_b32_e32 v2, 0xffff0000, v2
	s_lshl_b64 s[18:19], s[18:19], 20
	v_lshl_add_u32 v2, v11, 12, v2
	v_and_b32_e32 v3, 1, v10
	v_lshl_or_b32 v2, v3, 6, v2
	s_add_u32 s18, s14, s18
	v_lshl_add_u32 v2, v12, 1, v2
	v_mov_b32_e32 v3, v1
	s_addc_u32 s19, s15, s19
	v_lshl_add_u64 v[136:137], s[18:19], 0, v[2:3]
	v_lshlrev_b32_e32 v2, 15, v13
	v_and_b32_e32 v2, 0xffff0000, v2
	v_lshl_add_u32 v2, v14, 12, v2
	v_and_b32_e32 v3, 1, v13
	v_lshl_or_b32 v2, v3, 6, v2
	s_waitcnt vmcnt(6)
	v_lshl_add_u32 v2, v15, 1, v2
	v_mov_b32_e32 v3, v1
	v_lshl_add_u64 v[138:139], s[18:19], 0, v[2:3]
	v_mov_b32_e32 v2, 0
	v_lshl_or_b32 v220, s41, 6, v222
	s_mov_b32 s45, -2
	s_mov_b64 s[18:19], 0x19e44080
	v_add_u32_e32 v141, 0, v18
	v_mov_b32_e32 v3, v2
	v_mov_b32_e32 v4, v2
	v_mov_b32_e32 v5, v2
	v_mov_b32_e32 v6, v2
	v_mov_b32_e32 v7, v2
	v_mov_b32_e32 v8, v2
	v_mov_b32_e32 v9, v2
	v_mov_b32_e32 v14, v2
	v_mov_b32_e32 v15, v2
	v_mov_b32_e32 v16, v2
	v_mov_b32_e32 v17, v2
	v_mov_b32_e32 v22, v2
	v_mov_b32_e32 v23, v2
	v_mov_b32_e32 v24, v2
	v_mov_b32_e32 v25, v2
	v_mov_b32_e32 v30, v2
	v_mov_b32_e32 v31, v2
	v_mov_b32_e32 v32, v2
	v_mov_b32_e32 v33, v2
	v_mov_b32_e32 v38, v2
	v_mov_b32_e32 v39, v2
	v_mov_b32_e32 v40, v2
	v_mov_b32_e32 v41, v2
	v_mov_b32_e32 v46, v2
	v_mov_b32_e32 v47, v2
	v_mov_b32_e32 v48, v2
	v_mov_b32_e32 v49, v2
	v_mov_b32_e32 v54, v2
	v_mov_b32_e32 v55, v2
	v_mov_b32_e32 v56, v2
	v_mov_b32_e32 v57, v2
	v_mov_b32_e32 v10, v2
	v_mov_b32_e32 v11, v2
	v_mov_b32_e32 v12, v2
	v_mov_b32_e32 v13, v2
	v_mov_b32_e32 v18, v2
	v_mov_b32_e32 v19, v2
	v_mov_b32_e32 v20, v2
	v_mov_b32_e32 v21, v2
	v_mov_b32_e32 v26, v2
	v_mov_b32_e32 v27, v2
	v_mov_b32_e32 v28, v2
	v_mov_b32_e32 v29, v2
	v_mov_b32_e32 v34, v2
	v_mov_b32_e32 v35, v2
	v_mov_b32_e32 v36, v2
	v_mov_b32_e32 v37, v2
	v_mov_b32_e32 v42, v2
	v_mov_b32_e32 v43, v2
	v_mov_b32_e32 v44, v2
	v_mov_b32_e32 v45, v2
	v_mov_b32_e32 v50, v2
	v_mov_b32_e32 v51, v2
	v_mov_b32_e32 v52, v2
	v_mov_b32_e32 v53, v2
	v_mov_b32_e32 v58, v2
	v_mov_b32_e32 v59, v2
	v_mov_b32_e32 v60, v2
	v_mov_b32_e32 v61, v2
	v_mov_b32_e32 v62, v2
	v_mov_b32_e32 v63, v2
	v_mov_b32_e32 v64, v2
	v_mov_b32_e32 v65, v2
	v_mov_b32_e32 v66, v2
	v_mov_b32_e32 v67, v2
	v_mov_b32_e32 v68, v2
	v_mov_b32_e32 v69, v2
	v_mov_b32_e32 v70, v2
	v_mov_b32_e32 v71, v2
	v_mov_b32_e32 v72, v2
	v_mov_b32_e32 v73, v2
	v_mov_b32_e32 v78, v2
	v_mov_b32_e32 v79, v2
	v_mov_b32_e32 v80, v2
	v_mov_b32_e32 v81, v2
	v_mov_b32_e32 v86, v2
	v_mov_b32_e32 v87, v2
	v_mov_b32_e32 v88, v2
	v_mov_b32_e32 v89, v2
	v_mov_b32_e32 v94, v2
	v_mov_b32_e32 v95, v2
	v_mov_b32_e32 v96, v2
	v_mov_b32_e32 v97, v2
	v_mov_b32_e32 v102, v2
	v_mov_b32_e32 v103, v2
	v_mov_b32_e32 v104, v2
	v_mov_b32_e32 v105, v2
	v_mov_b32_e32 v106, v2
	v_mov_b32_e32 v107, v2
	v_mov_b32_e32 v108, v2
	v_mov_b32_e32 v109, v2
	v_mov_b32_e32 v114, v2
	v_mov_b32_e32 v115, v2
	v_mov_b32_e32 v116, v2
	v_mov_b32_e32 v117, v2
	v_mov_b32_e32 v74, v2
	v_mov_b32_e32 v75, v2
	v_mov_b32_e32 v76, v2
	v_mov_b32_e32 v77, v2
	v_mov_b32_e32 v82, v2
	v_mov_b32_e32 v83, v2
	v_mov_b32_e32 v84, v2
	v_mov_b32_e32 v85, v2
	v_mov_b32_e32 v90, v2
	v_mov_b32_e32 v91, v2
	v_mov_b32_e32 v92, v2
	v_mov_b32_e32 v93, v2
	v_mov_b32_e32 v98, v2
	v_mov_b32_e32 v99, v2
	v_mov_b32_e32 v100, v2
	v_mov_b32_e32 v101, v2
	v_mov_b32_e32 v110, v2
	v_mov_b32_e32 v111, v2
	v_mov_b32_e32 v112, v2
	v_mov_b32_e32 v113, v2
	v_mov_b32_e32 v118, v2
	v_mov_b32_e32 v119, v2
	v_mov_b32_e32 v120, v2
	v_mov_b32_e32 v121, v2
	v_mov_b32_e32 v122, v2
	v_mov_b32_e32 v123, v2
	v_mov_b32_e32 v124, v2
	v_mov_b32_e32 v125, v2
	v_mov_b32_e32 v126, v2
	v_mov_b32_e32 v127, v2
	v_mov_b32_e32 v128, v2
	v_mov_b32_e32 v129, v2
	s_barrier
	v_add_u32_e32 v252, 0x10000, v140
	v_add_u32_e32 v251, 0x14000, v140
	v_add_u32_e32 v250, 0x18000, v140
	v_add_u32_e32 v249, 0x1c000, v140
; #define PG8_STAGE(bufoff, gbase, voff) do { _Pragma("unroll") for (int _i = 0; _i < 2; ++_i) \
;         __builtin_amdgcn_global_load_lds((const unsigned*)((const char*)(gbase) + (voff)[_i]), (LAS unsigned*)(lds + (bufoff) + ldsw + _i * 8192), 16, 0, 0); } while (0)
; #define PG8_LDA(dst, b, h) do { _Pragma("unroll") for (int m = 0; m < 4; ++m) _Pragma("unroll") for (int k = 0; k < 2; ++k) dst[m][k] = *(const LAS bf16x8*)(lds + PG8_SA(b, h) + aoff + m * 2048 + k * 1024); } while (0)
; #define PG8_LDB(dst, b, h) do { _Pragma("unroll") for (int n = 0; n < 2; ++n) _Pragma("unroll") for (int k = 0; k < 2; ++k) dst[n][k] = *(const LAS bf16x8*)(lds + PG8_SB(b, h) + boff + n * 2048 + k * 1024); } while (0)
; #define PG8_MMA(ai, bj, At, Bt) do { __builtin_amdgcn_s_setprio(1); _Pragma("unroll") for (int m = 0; m < 4; ++m) _Pragma("unroll") for (int n = 0; n < 2; ++n) _Pragma("unroll") for (int k = 0; k < 2; ++k) \
;         acc[ai][bj][m][n] = __builtin_amdgcn_mfma_f32_16x16x32_bf16(Bt[n][k], At[m][k], acc[ai][bj][m][n], 0, 0, 0); __builtin_amdgcn_s_setprio(0); } while (0)
; template <class Epi, class Sched>
; __device__ __forceinline__ void gemm_phase(LAS unsigned char* lds, const Gemm g, const Sched& S, const Epi& E, const int tid) {
;     ...
;         for (int t = 0; t < nt; t += 2) {
;             const bool last = (t == nt - 2);
;             const char* a1 = cA + (size_t)(t + 1) * kstep;
;             const char* a2 = last ? nA : cA + (size_t)(t + 2) * kstep; const char* b2 = last ? nB : cB + (size_t)(t + 2) * kstep;
;             const char* a3 = a2 + kstep; const char* b3 = b2 + kstep;
;             if (last && has_next) S.a_ready(nxt);
;             if constexpr (Epi::PRELOAD) { if (last) E.preload(cur, lds, wid, lane); }
;             PG8_LDB(B0, 0, 0); PG8_SCHED; PG8_LDA(At, 0, 0); PG8_STAGE(PG8_SA(1, 1), a1 + hstep, voffA);
;             PG8_WAIT_L(8); PG8_BAR; PG8_WAIT_L(0); PG8_MMA(0, 0, At, B0); PG8_BAR; PG8_SCHED;
;             PG8_LDB(B1, 0, 1); PG8_STAGE(PG8_SB(0, 0), b2, voffB);
;             PG8_BAR; PG8_WAIT_L(0); PG8_MMA(0, 1, At, B1); PG8_BAR;
;             PG8_LDA(At, 0, 1); PG8_STAGE(PG8_SA(0, 0), a2, voffA);
;             PG8_BAR; PG8_WAIT_L(0); PG8_MMA(1, 0, At, B0); PG8_BAR; PG8_SCHED;
;             PG8_STAGE(PG8_SB(0, 1), b2 + hstep, voffB);
;             PG8_WAIT_V(6); PG8_BAR; PG8_MMA(1, 1, At, B1); PG8_BAR;
.LBB0_1208:
	s_add_u32 s20, s18, 0xe61bc080
	s_addc_u32 s21, s19, -1
	s_cmp_lg_u32 s45, 28
	s_cselect_b32 s20, s20, 0
	s_cselect_b32 s21, s21, 0
	s_add_u32 s22, s4, s20
	s_addc_u32 s23, s5, s21
	s_add_i32 s46, 0, 0x10000
	ds_read_b128 v[142:145], v252
	ds_read_b128 v[146:149], v252 offset:1024
	ds_read_b128 v[150:153], v252 offset:2048
	ds_read_b128 v[154:157], v252 offset:3072
	s_add_u32 s20, s0, s20
	s_addc_u32 s21, s1, s21
	v_lshl_add_u64 v[190:191], v[136:137], 0, s[18:19]
	s_add_i32 m0, s25, 0xc000
	ds_read_b128 v[158:161], v141
	ds_read_b128 v[162:165], v141 offset:1024
	ds_read_b128 v[166:169], v141 offset:2048
	ds_read_b128 v[170:173], v141 offset:3072
	ds_read_b128 v[174:177], v141 offset:4096
	ds_read_b128 v[178:181], v141 offset:5120
	ds_read_b128 v[182:185], v141 offset:6144
	ds_read_b128 v[186:189], v141 offset:7168
	global_load_lds_dwordx4 v[190:191], off
	s_add_i32 m0, s25, 0xe000
	v_lshl_add_u64 v[190:191], v[138:139], 0, s[18:19]
	global_load_lds_dwordx4 v[190:191], off
	s_waitcnt lgkmcnt(8)
	s_barrier
	s_waitcnt lgkmcnt(0)
	v_mfma_f32_16x16x32_bf16 v[126:129], v[142:145], v[158:161], v[126:129]
	v_mfma_f32_16x16x32_bf16 v[122:125], v[150:153], v[158:161], v[122:125]
	v_mfma_f32_16x16x32_bf16 v[118:121], v[142:145], v[166:169], v[118:121]
	v_mfma_f32_16x16x32_bf16 v[110:113], v[150:153], v[166:169], v[110:113]
	v_mfma_f32_16x16x32_bf16 v[98:101], v[142:145], v[174:177], v[98:101]
	v_mfma_f32_16x16x32_bf16 v[90:93], v[150:153], v[174:177], v[90:93]
	v_mfma_f32_16x16x32_bf16 v[82:85], v[142:145], v[182:185], v[82:85]
	v_mfma_f32_16x16x32_bf16 v[74:77], v[150:153], v[182:185], v[74:77]
	v_mfma_f32_16x16x32_bf16 v[126:129], v[146:149], v[162:165], v[126:129]
	v_mfma_f32_16x16x32_bf16 v[122:125], v[154:157], v[162:165], v[122:125]
	v_mfma_f32_16x16x32_bf16 v[118:121], v[146:149], v[170:173], v[118:121]
	v_mfma_f32_16x16x32_bf16 v[110:113], v[154:157], v[170:173], v[110:113]
	v_mfma_f32_16x16x32_bf16 v[98:101], v[146:149], v[178:181], v[98:101]
	v_mfma_f32_16x16x32_bf16 v[90:93], v[154:157], v[178:181], v[90:93]
	v_mfma_f32_16x16x32_bf16 v[82:85], v[146:149], v[186:189], v[82:85]
	v_mfma_f32_16x16x32_bf16 v[74:77], v[154:157], v[186:189], v[74:77]
	s_barrier
	s_add_i32 s48, 0, 0x14000
	s_add_i32 s46, s46, s24
	s_mov_b32 m0, s46
	ds_read_b128 v[190:193], v251
	ds_read_b128 v[194:197], v251 offset:1024
	ds_read_b128 v[198:201], v251 offset:2048
	ds_read_b128 v[202:205], v251 offset:3072
	global_load_lds_dwordx4 v0, s[20:21]
	s_add_i32 m0, s46, 0x2000
	s_nop 0
	global_load_lds_dwordx4 v134, s[20:21]
	s_barrier
	s_waitcnt lgkmcnt(0)
	v_mfma_f32_16x16x32_bf16 v[114:117], v[190:193], v[158:161], v[114:117]
	v_mfma_f32_16x16x32_bf16 v[106:109], v[198:201], v[158:161], v[106:109]
	v_mfma_f32_16x16x32_bf16 v[102:105], v[190:193], v[166:169], v[102:105]
	v_mfma_f32_16x16x32_bf16 v[94:97], v[198:201], v[166:169], v[94:97]
	v_mfma_f32_16x16x32_bf16 v[86:89], v[190:193], v[174:177], v[86:89]
	v_mfma_f32_16x16x32_bf16 v[78:81], v[198:201], v[174:177], v[78:81]
	v_mfma_f32_16x16x32_bf16 v[70:73], v[190:193], v[182:185], v[70:73]
	v_mfma_f32_16x16x32_bf16 v[66:69], v[198:201], v[182:185], v[66:69]
	v_mfma_f32_16x16x32_bf16 v[114:117], v[194:197], v[162:165], v[114:117]
	v_mfma_f32_16x16x32_bf16 v[106:109], v[202:205], v[162:165], v[106:109]
	v_mfma_f32_16x16x32_bf16 v[102:105], v[194:197], v[170:173], v[102:105]
	v_mfma_f32_16x16x32_bf16 v[94:97], v[202:205], v[170:173], v[94:97]
	v_mfma_f32_16x16x32_bf16 v[86:89], v[194:197], v[178:181], v[86:89]
	v_mfma_f32_16x16x32_bf16 v[78:81], v[202:205], v[178:181], v[78:81]
	v_mfma_f32_16x16x32_bf16 v[70:73], v[194:197], v[186:189], v[70:73]
	v_mfma_f32_16x16x32_bf16 v[66:69], v[202:205], v[186:189], v[66:69]
	s_mov_b32 m0, s25
	v_lshl_add_u64 v[210:211], s[22:23], 0, v[130:131]
	s_barrier
	ds_read_b128 v[158:161], v141 offset:16384
	ds_read_b128 v[162:165], v141 offset:17408
	ds_read_b128 v[166:169], v141 offset:18432
	ds_read_b128 v[170:173], v141 offset:19456
	ds_read_b128 v[174:177], v141 offset:20480
	ds_read_b128 v[178:181], v141 offset:21504
	ds_read_b128 v[182:185], v141 offset:22528
	ds_read_b128 v[186:189], v141 offset:23552
	global_load_lds_dwordx4 v[210:211], off
	s_mov_b32 m0, s28
	v_lshl_add_u64 v[214:215], s[22:23], 0, v[132:133]
	global_load_lds_dwordx4 v[214:215], off
	s_barrier
	s_waitcnt lgkmcnt(0)
	v_mfma_f32_16x16x32_bf16 v[62:65], v[142:145], v[158:161], v[62:65]
	v_mfma_f32_16x16x32_bf16 v[58:61], v[150:153], v[158:161], v[58:61]
	v_mfma_f32_16x16x32_bf16 v[50:53], v[142:145], v[166:169], v[50:53]
	v_mfma_f32_16x16x32_bf16 v[42:45], v[150:153], v[166:169], v[42:45]
	v_mfma_f32_16x16x32_bf16 v[34:37], v[142:145], v[174:177], v[34:37]
	v_mfma_f32_16x16x32_bf16 v[26:29], v[150:153], v[174:177], v[26:29]
	v_mfma_f32_16x16x32_bf16 v[18:21], v[142:145], v[182:185], v[18:21]
	v_mfma_f32_16x16x32_bf16 v[10:13], v[150:153], v[182:185], v[10:13]
	v_mfma_f32_16x16x32_bf16 v[62:65], v[146:149], v[162:165], v[62:65]
	v_mfma_f32_16x16x32_bf16 v[58:61], v[154:157], v[162:165], v[58:61]
	v_mfma_f32_16x16x32_bf16 v[50:53], v[146:149], v[170:173], v[50:53]
	v_mfma_f32_16x16x32_bf16 v[42:45], v[154:157], v[170:173], v[42:45]
	v_mfma_f32_16x16x32_bf16 v[34:37], v[146:149], v[178:181], v[34:37]
	v_mfma_f32_16x16x32_bf16 v[26:29], v[154:157], v[178:181], v[26:29]
	v_mfma_f32_16x16x32_bf16 v[18:21], v[146:149], v[186:189], v[18:21]
	v_mfma_f32_16x16x32_bf16 v[10:13], v[154:157], v[186:189], v[10:13]
	s_barrier
	s_add_u32 s46, s20, 0x80000
	s_addc_u32 s47, s21, 0
	s_add_i32 s48, s48, s24
	s_mov_b32 m0, s48
	s_nop 0
	global_load_lds_dwordx4 v0, s[46:47]
	s_add_i32 m0, s48, 0x2000
	s_nop 0
	global_load_lds_dwordx4 v134, s[46:47]
	s_waitcnt vmcnt(6)
	s_barrier
; #define PG8_STAGE(bufoff, gbase, voff) do { _Pragma("unroll") for (int _i = 0; _i < 2; ++_i) \
;         __builtin_amdgcn_global_load_lds((const unsigned*)((const char*)(gbase) + (voff)[_i]), (LAS unsigned*)(lds + (bufoff) + ldsw + _i * 8192), 16, 0, 0); } while (0)
; #define PG8_LDA(dst, b, h) do { _Pragma("unroll") for (int m = 0; m < 4; ++m) _Pragma("unroll") for (int k = 0; k < 2; ++k) dst[m][k] = *(const LAS bf16x8*)(lds + PG8_SA(b, h) + aoff + m * 2048 + k * 1024); } while (0)
; #define PG8_LDB(dst, b, h) do { _Pragma("unroll") for (int n = 0; n < 2; ++n) _Pragma("unroll") for (int k = 0; k < 2; ++k) dst[n][k] = *(const LAS bf16x8*)(lds + PG8_SB(b, h) + boff + n * 2048 + k * 1024); } while (0)
; #define PG8_WAIT_V(n) asm volatile("s_waitcnt vmcnt(" #n ")" ::: "memory")
; #define PG8_WAIT_L(n) asm volatile("s_waitcnt lgkmcnt(" #n ")" ::: "memory")
; #define PG8_BAR __builtin_amdgcn_s_barrier()
; #define PG8_SCHED __builtin_amdgcn_sched_barrier(0)
; template <class Epi, class Sched>
; __device__ __forceinline__ void gemm_phase(LAS unsigned char* lds, const Gemm g, const Sched& S, const Epi& E, const int tid) {
;     ...
;             PG8_LDB(B0, 0, 0); PG8_SCHED; PG8_LDA(At, 0, 0); PG8_STAGE(PG8_SA(1, 1), a1 + hstep, voffA);
;             PG8_WAIT_L(8); PG8_BAR; PG8_WAIT_L(0); PG8_MMA(0, 0, At, B0); PG8_BAR; PG8_SCHED;
;             PG8_LDB(B1, 0, 1); PG8_STAGE(PG8_SB(0, 0), b2, voffB);
;             PG8_BAR; PG8_WAIT_L(0); PG8_MMA(0, 1, At, B1); PG8_BAR;
;             PG8_LDA(At, 0, 1); PG8_STAGE(PG8_SA(0, 0), a2, voffA);
;             PG8_BAR; PG8_WAIT_L(0); PG8_MMA(1, 0, At, B0); PG8_BAR; PG8_SCHED;
;             PG8_STAGE(PG8_SB(0, 1), b2 + hstep, voffB);
;             PG8_WAIT_V(6); PG8_BAR; PG8_MMA(1, 1, At, B1); PG8_BAR;
;             PG8_LDB(B0, 1, 0); PG8_SCHED; PG8_LDA(At, 1, 0); PG8_STAGE(PG8_SA(0, 1), a2 + hstep, voffA);
;             PG8_WAIT_L(8); PG8_BAR; PG8_WAIT_L(0); PG8_MMA(0, 0, At, B0); PG8_BAR; PG8_SCHED;
;             PG8_LDB(B1, 1, 1); PG8_STAGE(PG8_SB(1, 0), b3, voffB);
;             PG8_BAR; PG8_WAIT_L(0); PG8_MMA(0, 1, At, B1); PG8_BAR;
;             PG8_LDA(At, 1, 1); PG8_STAGE(PG8_SA(1, 0), a3, voffA);
;             PG8_BAR; PG8_WAIT_L(0); PG8_MMA(1, 0, At, B0); PG8_BAR; PG8_SCHED;
;             PG8_STAGE(PG8_SB(1, 1), b3 + hstep, voffB);
;             PG8_WAIT_V(6); PG8_BAR; PG8_MMA(1, 1, At, B1); PG8_BAR;
	v_mfma_f32_16x16x32_bf16 v[54:57], v[190:193], v[158:161], v[54:57]
	v_mfma_f32_16x16x32_bf16 v[46:49], v[198:201], v[158:161], v[46:49]
	v_mfma_f32_16x16x32_bf16 v[38:41], v[190:193], v[166:169], v[38:41]
	v_mfma_f32_16x16x32_bf16 v[30:33], v[198:201], v[166:169], v[30:33]
	v_mfma_f32_16x16x32_bf16 v[22:25], v[190:193], v[174:177], v[22:25]
	v_mfma_f32_16x16x32_bf16 v[14:17], v[198:201], v[174:177], v[14:17]
	v_mfma_f32_16x16x32_bf16 v[6:9], v[190:193], v[182:185], v[6:9]
	v_mfma_f32_16x16x32_bf16 v[2:5], v[198:201], v[182:185], v[2:5]
	v_mfma_f32_16x16x32_bf16 v[54:57], v[194:197], v[162:165], v[54:57]
	v_mfma_f32_16x16x32_bf16 v[46:49], v[202:205], v[162:165], v[46:49]
	v_mfma_f32_16x16x32_bf16 v[38:41], v[194:197], v[170:173], v[38:41]
	v_mfma_f32_16x16x32_bf16 v[30:33], v[202:205], v[170:173], v[30:33]
	v_mfma_f32_16x16x32_bf16 v[22:25], v[194:197], v[178:181], v[22:25]
	v_mfma_f32_16x16x32_bf16 v[14:17], v[202:205], v[178:181], v[14:17]
	v_mfma_f32_16x16x32_bf16 v[6:9], v[194:197], v[186:189], v[6:9]
	v_mfma_f32_16x16x32_bf16 v[2:5], v[202:205], v[186:189], v[2:5]
	s_add_i32 s46, 0, 0x18000
	s_barrier
	ds_read_b128 v[142:145], v250
	ds_read_b128 v[146:149], v250 offset:1024
	ds_read_b128 v[150:153], v250 offset:2048
	ds_read_b128 v[154:157], v250 offset:3072
	s_add_u32 s22, s22, 0x80000
	s_addc_u32 s23, s23, 0
	s_mov_b32 m0, s29
	ds_read_b128 v[158:161], v141 offset:32768
	ds_read_b128 v[162:165], v141 offset:33792
	ds_read_b128 v[166:169], v141 offset:34816
	ds_read_b128 v[170:173], v141 offset:35840
	ds_read_b128 v[174:177], v141 offset:36864
	ds_read_b128 v[178:181], v141 offset:37888
	ds_read_b128 v[182:185], v141 offset:38912
	global_load_lds_dwordx4 v130, s[22:23]
	s_mov_b32 m0, s42
	ds_read_b128 v[186:189], v141 offset:39936
	global_load_lds_dwordx4 v132, s[22:23]
	s_waitcnt lgkmcnt(8)
	s_barrier
	s_waitcnt lgkmcnt(0)
	v_mfma_f32_16x16x32_bf16 v[126:129], v[142:145], v[158:161], v[126:129]
	v_mfma_f32_16x16x32_bf16 v[122:125], v[150:153], v[158:161], v[122:125]
	v_mfma_f32_16x16x32_bf16 v[118:121], v[142:145], v[166:169], v[118:121]
	v_mfma_f32_16x16x32_bf16 v[110:113], v[150:153], v[166:169], v[110:113]
	v_mfma_f32_16x16x32_bf16 v[98:101], v[142:145], v[174:177], v[98:101]
	v_mfma_f32_16x16x32_bf16 v[90:93], v[150:153], v[174:177], v[90:93]
	v_mfma_f32_16x16x32_bf16 v[82:85], v[142:145], v[182:185], v[82:85]
	v_mfma_f32_16x16x32_bf16 v[74:77], v[150:153], v[182:185], v[74:77]
	v_mfma_f32_16x16x32_bf16 v[126:129], v[146:149], v[162:165], v[126:129]
	v_mfma_f32_16x16x32_bf16 v[122:125], v[154:157], v[162:165], v[122:125]
	v_mfma_f32_16x16x32_bf16 v[118:121], v[146:149], v[170:173], v[118:121]
	v_mfma_f32_16x16x32_bf16 v[110:113], v[154:157], v[170:173], v[110:113]
	v_mfma_f32_16x16x32_bf16 v[98:101], v[146:149], v[178:181], v[98:101]
	v_mfma_f32_16x16x32_bf16 v[90:93], v[154:157], v[178:181], v[90:93]
	v_mfma_f32_16x16x32_bf16 v[82:85], v[146:149], v[186:189], v[82:85]
	v_mfma_f32_16x16x32_bf16 v[74:77], v[154:157], v[186:189], v[74:77]
	s_barrier
	s_add_i32 s22, 0, 0x1c000
	s_add_i32 s23, s46, s24
	s_add_u32 s98, s20, s36
	s_addc_u32 s99, s21, s37
	s_mov_b32 m0, s23
	ds_read_b128 v[190:193], v249
	ds_read_b128 v[194:197], v249 offset:1024
	ds_read_b128 v[198:201], v249 offset:2048
	ds_read_b128 v[202:205], v249 offset:3072
	global_load_lds_dwordx4 v0, s[98:99]
	s_add_i32 m0, s23, 0x2000
	s_add_u32 s98, s20, s36
	s_addc_u32 s99, s21, s37
	global_load_lds_dwordx4 v134, s[98:99]
	s_barrier
; #define PG8_STAGE(bufoff, gbase, voff) do { _Pragma("unroll") for (int _i = 0; _i < 2; ++_i) \
;         __builtin_amdgcn_global_load_lds((const unsigned*)((const char*)(gbase) + (voff)[_i]), (LAS unsigned*)(lds + (bufoff) + ldsw + _i * 8192), 16, 0, 0); } while (0)
; #define PG8_LDA(dst, b, h) do { _Pragma("unroll") for (int m = 0; m < 4; ++m) _Pragma("unroll") for (int k = 0; k < 2; ++k) dst[m][k] = *(const LAS bf16x8*)(lds + PG8_SA(b, h) + aoff + m * 2048 + k * 1024); } while (0)
; #define PG8_LDB(dst, b, h) do { _Pragma("unroll") for (int n = 0; n < 2; ++n) _Pragma("unroll") for (int k = 0; k < 2; ++k) dst[n][k] = *(const LAS bf16x8*)(lds + PG8_SB(b, h) + boff + n * 2048 + k * 1024); } while (0)
; #define PG8_WAIT_V(n) asm volatile("s_waitcnt vmcnt(" #n ")" ::: "memory")
; #define PG8_WAIT_L(n) asm volatile("s_waitcnt lgkmcnt(" #n ")" ::: "memory")
; #define PG8_BAR __builtin_amdgcn_s_barrier()
; template <class Epi, class Sched>
; __device__ __forceinline__ void gemm_phase(LAS unsigned char* lds, const Gemm g, const Sched& S, const Epi& E, const int tid) {
;     ...
;             PG8_WAIT_V(6); PG8_BAR; PG8_MMA(1, 1, At, B1); PG8_BAR;
;             PG8_LDB(B0, 1, 0); PG8_SCHED; PG8_LDA(At, 1, 0); PG8_STAGE(PG8_SA(0, 1), a2 + hstep, voffA);
;             PG8_WAIT_L(8); PG8_BAR; PG8_WAIT_L(0); PG8_MMA(0, 0, At, B0); PG8_BAR; PG8_SCHED;
;             PG8_LDB(B1, 1, 1); PG8_STAGE(PG8_SB(1, 0), b3, voffB);
;             PG8_BAR; PG8_WAIT_L(0); PG8_MMA(0, 1, At, B1); PG8_BAR;
;             PG8_LDA(At, 1, 1); PG8_STAGE(PG8_SA(1, 0), a3, voffA);
;             PG8_BAR; PG8_WAIT_L(0); PG8_MMA(1, 0, At, B0); PG8_BAR; PG8_SCHED;
;             PG8_STAGE(PG8_SB(1, 1), b3 + hstep, voffB);
;             PG8_WAIT_V(6); PG8_BAR; PG8_MMA(1, 1, At, B1); PG8_BAR;
;         }
;         if constexpr (!Epi::AFTER_DRAIN) { if constexpr (Epi::PRELOAD) E(acc, cur, wr, wc, fr, fq, lds); else E(acc, cur, wr, wc, fr, fq); S.done(cur); }
;         if (!has_next) break;
; #pragma unroll
;         for (int a = 0; a < 2; ++a)
; #pragma unroll
;             for (int b = 0; b < 2; ++b)
; #pragma unroll
;                 for (int m = 0; m < 4; ++m)
; #pragma unroll
;                     for (int n = 0; n < 2; ++n) acc[a][b][m][n] = (f32x4){0.f, 0.f, 0.f, 0.f};
;         cur = nxt; cA = nA; cB = nB; ++ui;
;     }
;     PG8_WAIT_V(0);
;     if (wr == 0) PG8_BAR;
;     PG8_BAR;
	s_waitcnt lgkmcnt(0)
	v_mfma_f32_16x16x32_bf16 v[114:117], v[190:193], v[158:161], v[114:117]
	v_mfma_f32_16x16x32_bf16 v[106:109], v[198:201], v[158:161], v[106:109]
	v_mfma_f32_16x16x32_bf16 v[102:105], v[190:193], v[166:169], v[102:105]
	v_mfma_f32_16x16x32_bf16 v[94:97], v[198:201], v[166:169], v[94:97]
	v_mfma_f32_16x16x32_bf16 v[86:89], v[190:193], v[174:177], v[86:89]
	v_mfma_f32_16x16x32_bf16 v[78:81], v[198:201], v[174:177], v[78:81]
	v_mfma_f32_16x16x32_bf16 v[70:73], v[190:193], v[182:185], v[70:73]
	v_mfma_f32_16x16x32_bf16 v[66:69], v[198:201], v[182:185], v[66:69]
	v_mfma_f32_16x16x32_bf16 v[114:117], v[194:197], v[162:165], v[114:117]
	v_mfma_f32_16x16x32_bf16 v[106:109], v[202:205], v[162:165], v[106:109]
	v_mfma_f32_16x16x32_bf16 v[102:105], v[194:197], v[170:173], v[102:105]
	v_mfma_f32_16x16x32_bf16 v[94:97], v[202:205], v[170:173], v[94:97]
	v_mfma_f32_16x16x32_bf16 v[86:89], v[194:197], v[178:181], v[86:89]
	v_mfma_f32_16x16x32_bf16 v[78:81], v[202:205], v[178:181], v[78:81]
	v_mfma_f32_16x16x32_bf16 v[70:73], v[194:197], v[186:189], v[70:73]
	v_mfma_f32_16x16x32_bf16 v[66:69], v[202:205], v[186:189], v[66:69]
	s_mov_b32 m0, s43
	v_lshl_add_u64 v[206:207], v[210:211], 0, s[36:37]
	s_barrier
	ds_read_b128 v[158:161], v141 offset:49152
	ds_read_b128 v[162:165], v141 offset:50176
	ds_read_b128 v[166:169], v141 offset:51200
	ds_read_b128 v[170:173], v141 offset:52224
	ds_read_b128 v[174:177], v141 offset:53248
	ds_read_b128 v[178:181], v141 offset:54272
	ds_read_b128 v[182:185], v141 offset:55296
	ds_read_b128 v[186:189], v141 offset:56320
	global_load_lds_dwordx4 v[206:207], off
	s_mov_b32 m0, s44
	v_lshl_add_u64 v[206:207], v[214:215], 0, s[36:37]
	global_load_lds_dwordx4 v[206:207], off
	s_barrier
	s_waitcnt lgkmcnt(0)
	v_mfma_f32_16x16x32_bf16 v[62:65], v[142:145], v[158:161], v[62:65]
	v_mfma_f32_16x16x32_bf16 v[58:61], v[150:153], v[158:161], v[58:61]
	v_mfma_f32_16x16x32_bf16 v[50:53], v[142:145], v[166:169], v[50:53]
	v_mfma_f32_16x16x32_bf16 v[42:45], v[150:153], v[166:169], v[42:45]
	v_mfma_f32_16x16x32_bf16 v[34:37], v[142:145], v[174:177], v[34:37]
	v_mfma_f32_16x16x32_bf16 v[26:29], v[150:153], v[174:177], v[26:29]
	v_mfma_f32_16x16x32_bf16 v[18:21], v[142:145], v[182:185], v[18:21]
	v_mfma_f32_16x16x32_bf16 v[10:13], v[150:153], v[182:185], v[10:13]
	v_mfma_f32_16x16x32_bf16 v[62:65], v[146:149], v[162:165], v[62:65]
	v_mfma_f32_16x16x32_bf16 v[58:61], v[154:157], v[162:165], v[58:61]
	v_mfma_f32_16x16x32_bf16 v[50:53], v[146:149], v[170:173], v[50:53]
	v_mfma_f32_16x16x32_bf16 v[42:45], v[154:157], v[170:173], v[42:45]
	v_mfma_f32_16x16x32_bf16 v[34:37], v[146:149], v[178:181], v[34:37]
	v_mfma_f32_16x16x32_bf16 v[26:29], v[154:157], v[178:181], v[26:29]
	v_mfma_f32_16x16x32_bf16 v[18:21], v[146:149], v[186:189], v[18:21]
	v_mfma_f32_16x16x32_bf16 v[10:13], v[154:157], v[186:189], v[10:13]
	s_barrier
	s_add_u32 s20, s20, 0x80080
	s_addc_u32 s21, s21, 0
	s_add_i32 s22, s22, s24
	s_mov_b32 m0, s22
	s_nop 0
	global_load_lds_dwordx4 v0, s[20:21]
	s_add_i32 m0, s22, 0x2000
	s_nop 0
	global_load_lds_dwordx4 v134, s[20:21]
	s_waitcnt vmcnt(6)
	s_barrier
	v_mfma_f32_16x16x32_bf16 v[54:57], v[190:193], v[158:161], v[54:57]
	v_mfma_f32_16x16x32_bf16 v[46:49], v[198:201], v[158:161], v[46:49]
	v_mfma_f32_16x16x32_bf16 v[38:41], v[190:193], v[166:169], v[38:41]
	v_mfma_f32_16x16x32_bf16 v[30:33], v[198:201], v[166:169], v[30:33]
	v_mfma_f32_16x16x32_bf16 v[22:25], v[190:193], v[174:177], v[22:25]
	v_mfma_f32_16x16x32_bf16 v[14:17], v[198:201], v[174:177], v[14:17]
	v_mfma_f32_16x16x32_bf16 v[6:9], v[190:193], v[182:185], v[6:9]
	v_mfma_f32_16x16x32_bf16 v[2:5], v[198:201], v[182:185], v[2:5]
	v_mfma_f32_16x16x32_bf16 v[54:57], v[194:197], v[162:165], v[54:57]
	v_mfma_f32_16x16x32_bf16 v[46:49], v[202:205], v[162:165], v[46:49]
	v_mfma_f32_16x16x32_bf16 v[38:41], v[194:197], v[170:173], v[38:41]
	v_mfma_f32_16x16x32_bf16 v[30:33], v[202:205], v[170:173], v[30:33]
	v_mfma_f32_16x16x32_bf16 v[22:25], v[194:197], v[178:181], v[22:25]
	v_mfma_f32_16x16x32_bf16 v[14:17], v[202:205], v[178:181], v[14:17]
	v_mfma_f32_16x16x32_bf16 v[6:9], v[194:197], v[186:189], v[6:9]
	v_mfma_f32_16x16x32_bf16 v[2:5], v[202:205], v[186:189], v[2:5]
	s_add_i32 s45, s45, 2
	s_add_u32 s18, s18, 0x100
	s_addc_u32 s19, s19, 0
	s_cmp_lt_u32 s45, 30
	s_barrier
	s_cbranch_scc1 .LBB0_1208
	s_waitcnt vmcnt(0)
	s_cmpk_gt_u32 s38, 0xff
	s_cbranch_scc1 .LBB0_1211
	s_barrier

; #define PG8_STAGE(bufoff, gbase, voff) do { _Pragma("unroll") for (int _i = 0; _i < 2; ++_i) \
;         __builtin_amdgcn_global_load_lds((const unsigned*)((const char*)(gbase) + (voff)[_i]), (LAS unsigned*)(lds + (bufoff) + ldsw + _i * 8192), 16, 0, 0); } while (0)
; #define PG8_LDA(dst, b, h) do { _Pragma("unroll") for (int m = 0; m < 4; ++m) _Pragma("unroll") for (int k = 0; k < 2; ++k) dst[m][k] = *(const LAS bf16x8*)(lds + PG8_SA(b, h) + aoff + m * 2048 + k * 1024); } while (0)
; #define PG8_LDB(dst, b, h) do { _Pragma("unroll") for (int n = 0; n < 2; ++n) _Pragma("unroll") for (int k = 0; k < 2; ++k) dst[n][k] = *(const LAS bf16x8*)(lds + PG8_SB(b, h) + boff + n * 2048 + k * 1024); } while (0)
; #define PG8_MMA(ai, bj, At, Bt) do { __builtin_amdgcn_s_setprio(1); _Pragma("unroll") for (int m = 0; m < 4; ++m) _Pragma("unroll") for (int n = 0; n < 2; ++n) _Pragma("unroll") for (int k = 0; k < 2; ++k) \
;         acc[ai][bj][m][n] = __builtin_amdgcn_mfma_f32_16x16x32_bf16(Bt[n][k], At[m][k], acc[ai][bj][m][n], 0, 0, 0); __builtin_amdgcn_s_setprio(0); } while (0)
; #define PG8_WAIT_L(n) asm volatile("s_waitcnt lgkmcnt(" #n ")" ::: "memory")
; #define PG8_BAR __builtin_amdgcn_s_barrier()
; #define PG8_SCHED __builtin_amdgcn_sched_barrier(0)
; template <class Epi, class Sched>
; __device__ __forceinline__ void gemm_phase(LAS unsigned char* lds, const Gemm g, const Sched& S, const Epi& E, const int tid) {
;     ...
;             if constexpr (Epi::PRELOAD) { if (last) E.preload(cur, lds, wid, lane); }
;             PG8_LDB(B0, 0, 0); PG8_SCHED; PG8_LDA(At, 0, 0); PG8_STAGE(PG8_SA(1, 1), a1 + hstep, voffA);
;             PG8_WAIT_L(8); PG8_BAR; PG8_WAIT_L(0); PG8_MMA(0, 0, At, B0); PG8_BAR; PG8_SCHED;
;     ...
; #pragma unroll
;         for (int a = 0; a < 2; ++a)
; #pragma unroll
;             for (int b = 0; b < 2; ++b)
; #pragma unroll
;                 for (int m = 0; m < 4; ++m)
; #pragma unroll
;                     for (int n = 0; n < 2; ++n) acc[a][b][m][n] = (f32x4){0.f, 0.f, 0.f, 0.f};
;         cur = nxt; cA = nA; cB = nB; ++ui;
.LBB0_1392:
	s_lshl_b32 s46, s10, 7
	s_ashr_i32 s47, s46, 31
	s_add_u32 s5, s50, 0x100
	v_mov_b32_e32 v2, 0
	s_mov_b32 s21, 2
	v_lshl_add_u64 v[130:131], s[46:47], 2, v[184:185]
	s_addc_u32 s23, s51, 0
	v_mov_b32_e32 v3, v2
	v_mov_b32_e32 v4, v2
	v_mov_b32_e32 v5, v2
	v_mov_b32_e32 v6, v2
	v_mov_b32_e32 v7, v2
	v_mov_b32_e32 v8, v2
	v_mov_b32_e32 v9, v2
	v_mov_b32_e32 v10, v2
	v_mov_b32_e32 v11, v2
	v_mov_b32_e32 v12, v2
	v_mov_b32_e32 v13, v2
	v_mov_b32_e32 v14, v2
	v_mov_b32_e32 v15, v2
	v_mov_b32_e32 v16, v2
	v_mov_b32_e32 v17, v2
	v_mov_b32_e32 v26, v2
	v_mov_b32_e32 v27, v2
	v_mov_b32_e32 v28, v2
	v_mov_b32_e32 v29, v2
	v_mov_b32_e32 v30, v2
	v_mov_b32_e32 v31, v2
	v_mov_b32_e32 v32, v2
	v_mov_b32_e32 v33, v2
	v_mov_b32_e32 v42, v2
	v_mov_b32_e32 v43, v2
	v_mov_b32_e32 v44, v2
	v_mov_b32_e32 v45, v2
	v_mov_b32_e32 v46, v2
	v_mov_b32_e32 v47, v2
	v_mov_b32_e32 v48, v2
	v_mov_b32_e32 v49, v2
	v_mov_b32_e32 v18, v2
	v_mov_b32_e32 v19, v2
	v_mov_b32_e32 v20, v2
	v_mov_b32_e32 v21, v2
	v_mov_b32_e32 v22, v2
	v_mov_b32_e32 v23, v2
	v_mov_b32_e32 v24, v2
	v_mov_b32_e32 v25, v2
	v_mov_b32_e32 v34, v2
	v_mov_b32_e32 v35, v2
	v_mov_b32_e32 v36, v2
	v_mov_b32_e32 v37, v2
	v_mov_b32_e32 v38, v2
	v_mov_b32_e32 v39, v2
	v_mov_b32_e32 v40, v2
	v_mov_b32_e32 v41, v2
	v_mov_b32_e32 v50, v2
	v_mov_b32_e32 v51, v2
	v_mov_b32_e32 v52, v2
	v_mov_b32_e32 v53, v2
	v_mov_b32_e32 v54, v2
	v_mov_b32_e32 v55, v2
	v_mov_b32_e32 v56, v2
	v_mov_b32_e32 v57, v2
	v_mov_b32_e32 v58, v2
	v_mov_b32_e32 v59, v2
	v_mov_b32_e32 v60, v2
	v_mov_b32_e32 v61, v2
	v_mov_b32_e32 v62, v2
	v_mov_b32_e32 v63, v2
	v_mov_b32_e32 v64, v2
	v_mov_b32_e32 v65, v2
	v_mov_b32_e32 v66, v2
	v_mov_b32_e32 v67, v2
	v_mov_b32_e32 v68, v2
	v_mov_b32_e32 v69, v2
	v_mov_b32_e32 v70, v2
	v_mov_b32_e32 v71, v2
	v_mov_b32_e32 v72, v2
	v_mov_b32_e32 v73, v2
	v_mov_b32_e32 v74, v2
	v_mov_b32_e32 v75, v2
	v_mov_b32_e32 v76, v2
	v_mov_b32_e32 v77, v2
	v_mov_b32_e32 v78, v2
	v_mov_b32_e32 v79, v2
	v_mov_b32_e32 v80, v2
	v_mov_b32_e32 v81, v2
	v_mov_b32_e32 v90, v2
	v_mov_b32_e32 v91, v2
	v_mov_b32_e32 v92, v2
	v_mov_b32_e32 v93, v2
	v_mov_b32_e32 v94, v2
	v_mov_b32_e32 v95, v2
	v_mov_b32_e32 v96, v2
	v_mov_b32_e32 v97, v2
	v_mov_b32_e32 v106, v2
	v_mov_b32_e32 v107, v2
	v_mov_b32_e32 v108, v2
	v_mov_b32_e32 v109, v2
	v_mov_b32_e32 v110, v2
	v_mov_b32_e32 v111, v2
	v_mov_b32_e32 v112, v2
	v_mov_b32_e32 v113, v2
	v_mov_b32_e32 v82, v2
	v_mov_b32_e32 v83, v2
	v_mov_b32_e32 v84, v2
	v_mov_b32_e32 v85, v2
	v_mov_b32_e32 v86, v2
	v_mov_b32_e32 v87, v2
	v_mov_b32_e32 v88, v2
	v_mov_b32_e32 v89, v2
	v_mov_b32_e32 v98, v2
	v_mov_b32_e32 v99, v2
	v_mov_b32_e32 v100, v2
	v_mov_b32_e32 v101, v2
	v_mov_b32_e32 v102, v2
	v_mov_b32_e32 v103, v2
	v_mov_b32_e32 v104, v2
	v_mov_b32_e32 v105, v2
	v_mov_b32_e32 v114, v2
	v_mov_b32_e32 v115, v2
	v_mov_b32_e32 v116, v2
	v_mov_b32_e32 v117, v2
	v_mov_b32_e32 v118, v2
	v_mov_b32_e32 v119, v2
	v_mov_b32_e32 v120, v2
	v_mov_b32_e32 v121, v2
	v_mov_b32_e32 v122, v2
	v_mov_b32_e32 v123, v2
	v_mov_b32_e32 v124, v2
	v_mov_b32_e32 v125, v2
	v_mov_b32_e32 v126, v2
	v_mov_b32_e32 v127, v2
	v_mov_b32_e32 v128, v2
	v_mov_b32_e32 v129, v2
	v_add_u32_e32 v252, 0x10000, v209
	v_add_u32_e32 v251, 0x14000, v209
	v_add_u32_e32 v250, 0x18000, v209
	v_add_u32_e32 v249, 0x1c000, v209
	s_branch .LBB0_1394
.LBB0_1393:
	s_add_u32 s50, s48, 0x100
	s_addc_u32 s51, s49, 0
	s_and_b64 s[24:25], s[52:53], exec
	s_cselect_b32 s55, s45, s51
	s_cselect_b32 s54, s44, s50
	s_cselect_b32 s53, s3, s23
	s_cselect_b32 s52, s2, s5
	s_add_i32 s24, 0, 0x10000
	ds_read_b128 v[132:135], v252
	ds_read_b128 v[136:139], v252 offset:1024
	ds_read_b128 v[140:143], v252 offset:2048
	ds_read_b128 v[144:147], v252 offset:3072
	v_lshl_add_u64 v[176:177], s[48:49], 0, v[186:187]
	s_add_i32 m0, s7, 0xc000
	ds_read_b128 v[148:151], v216
	ds_read_b128 v[152:155], v216 offset:1024
	ds_read_b128 v[156:159], v216 offset:2048
	ds_read_b128 v[160:163], v216 offset:3072
	ds_read_b128 v[164:167], v216 offset:4096
	ds_read_b128 v[168:171], v216 offset:5120
	ds_read_b128 v[172:175], v216 offset:6144
	ds_read_b128 v[190:193], v216 offset:7168
	global_load_lds_dwordx4 v[176:177], off
	s_add_i32 m0, s7, 0xe000
	v_lshl_add_u64 v[176:177], s[48:49], 0, v[188:189]
	global_load_lds_dwordx4 v[176:177], off
	s_waitcnt lgkmcnt(8)
	s_barrier
	s_waitcnt lgkmcnt(0)
	v_mfma_f32_16x16x32_bf16 v[126:129], v[132:135], v[148:151], v[126:129]
	v_mfma_f32_16x16x32_bf16 v[122:125], v[140:143], v[148:151], v[122:125]
	v_mfma_f32_16x16x32_bf16 v[118:121], v[132:135], v[156:159], v[118:121]
	v_mfma_f32_16x16x32_bf16 v[114:117], v[140:143], v[156:159], v[114:117]
	v_mfma_f32_16x16x32_bf16 v[102:105], v[132:135], v[164:167], v[102:105]
	v_mfma_f32_16x16x32_bf16 v[98:101], v[140:143], v[164:167], v[98:101]
	v_mfma_f32_16x16x32_bf16 v[86:89], v[132:135], v[172:175], v[86:89]
	v_mfma_f32_16x16x32_bf16 v[82:85], v[140:143], v[172:175], v[82:85]
	v_mfma_f32_16x16x32_bf16 v[126:129], v[136:139], v[152:155], v[126:129]
	v_mfma_f32_16x16x32_bf16 v[122:125], v[144:147], v[152:155], v[122:125]
	v_mfma_f32_16x16x32_bf16 v[118:121], v[136:139], v[160:163], v[118:121]
	v_mfma_f32_16x16x32_bf16 v[114:117], v[144:147], v[160:163], v[114:117]
	v_mfma_f32_16x16x32_bf16 v[102:105], v[136:139], v[168:171], v[102:105]
	v_mfma_f32_16x16x32_bf16 v[98:101], v[144:147], v[168:171], v[98:101]
	v_mfma_f32_16x16x32_bf16 v[86:89], v[136:139], v[190:193], v[86:89]
	v_mfma_f32_16x16x32_bf16 v[82:85], v[144:147], v[190:193], v[82:85]
	s_barrier
; #define PG8_STAGE(bufoff, gbase, voff) do { _Pragma("unroll") for (int _i = 0; _i < 2; ++_i) \
;         __builtin_amdgcn_global_load_lds((const unsigned*)((const char*)(gbase) + (voff)[_i]), (LAS unsigned*)(lds + (bufoff) + ldsw + _i * 8192), 16, 0, 0); } while (0)
; #define PG8_LDA(dst, b, h) do { _Pragma("unroll") for (int m = 0; m < 4; ++m) _Pragma("unroll") for (int k = 0; k < 2; ++k) dst[m][k] = *(const LAS bf16x8*)(lds + PG8_SA(b, h) + aoff + m * 2048 + k * 1024); } while (0)
; #define PG8_LDB(dst, b, h) do { _Pragma("unroll") for (int n = 0; n < 2; ++n) _Pragma("unroll") for (int k = 0; k < 2; ++k) dst[n][k] = *(const LAS bf16x8*)(lds + PG8_SB(b, h) + boff + n * 2048 + k * 1024); } while (0)
; #define PG8_MMA(ai, bj, At, Bt) do { __builtin_amdgcn_s_setprio(1); _Pragma("unroll") for (int m = 0; m < 4; ++m) _Pragma("unroll") for (int n = 0; n < 2; ++n) _Pragma("unroll") for (int k = 0; k < 2; ++k) \
;         acc[ai][bj][m][n] = __builtin_amdgcn_mfma_f32_16x16x32_bf16(Bt[n][k], At[m][k], acc[ai][bj][m][n], 0, 0, 0); __builtin_amdgcn_s_setprio(0); } while (0)
; #define PG8_WAIT_V(n) asm volatile("s_waitcnt vmcnt(" #n ")" ::: "memory")
; #define PG8_WAIT_L(n) asm volatile("s_waitcnt lgkmcnt(" #n ")" ::: "memory")
; #define PG8_BAR __builtin_amdgcn_s_barrier()
; #define PG8_SCHED __builtin_amdgcn_sched_barrier(0)
; template <class Epi, class Sched>
; __device__ __forceinline__ void gemm_phase(LAS unsigned char* lds, const Gemm g, const Sched& S, const Epi& E, const int tid) {
;     ...
;             PG8_LDB(B1, 0, 1); PG8_STAGE(PG8_SB(0, 0), b2, voffB);
;             PG8_BAR; PG8_WAIT_L(0); PG8_MMA(0, 1, At, B1); PG8_BAR;
;             PG8_LDA(At, 0, 1); PG8_STAGE(PG8_SA(0, 0), a2, voffA);
;             PG8_BAR; PG8_WAIT_L(0); PG8_MMA(1, 0, At, B0); PG8_BAR; PG8_SCHED;
;             PG8_STAGE(PG8_SB(0, 1), b2 + hstep, voffB);
;             PG8_WAIT_V(6); PG8_BAR; PG8_MMA(1, 1, At, B1); PG8_BAR;
;             PG8_LDB(B0, 1, 0); PG8_SCHED; PG8_LDA(At, 1, 0); PG8_STAGE(PG8_SA(0, 1), a2 + hstep, voffA);
;             PG8_WAIT_L(8); PG8_BAR; PG8_WAIT_L(0); PG8_MMA(0, 0, At, B0); PG8_BAR; PG8_SCHED;
;             PG8_LDB(B1, 1, 1); PG8_STAGE(PG8_SB(1, 0), b3, voffB);
;             PG8_BAR; PG8_WAIT_L(0); PG8_MMA(0, 1, At, B1); PG8_BAR;
	s_add_i32 s28, 0, 0x14000
	s_add_i32 s24, s24, s66
	ds_read_b128 v[194:197], v251
	ds_read_b128 v[198:201], v251 offset:1024
	ds_read_b128 v[202:205], v251 offset:2048
	ds_read_b128 v[218:221], v251 offset:3072
	s_mov_b32 m0, s24
	v_lshl_add_u64 v[206:207], s[52:53], 0, v[182:183]
	global_load_lds_dwordx4 v0, s[52:53]
	s_add_i32 m0, s24, 0x2000
	s_nop 0
	global_load_lds_dwordx4 v[206:207], off
	s_barrier
	s_waitcnt lgkmcnt(0)
	v_mfma_f32_16x16x32_bf16 v[110:113], v[194:197], v[148:151], v[110:113]
	v_mfma_f32_16x16x32_bf16 v[106:109], v[202:205], v[148:151], v[106:109]
	v_mfma_f32_16x16x32_bf16 v[94:97], v[194:197], v[156:159], v[94:97]
	v_mfma_f32_16x16x32_bf16 v[90:93], v[202:205], v[156:159], v[90:93]
	v_mfma_f32_16x16x32_bf16 v[78:81], v[194:197], v[164:167], v[78:81]
	v_mfma_f32_16x16x32_bf16 v[74:77], v[202:205], v[164:167], v[74:77]
	v_mfma_f32_16x16x32_bf16 v[70:73], v[194:197], v[172:175], v[70:73]
	v_mfma_f32_16x16x32_bf16 v[66:69], v[202:205], v[172:175], v[66:69]
	v_mfma_f32_16x16x32_bf16 v[110:113], v[198:201], v[152:155], v[110:113]
	v_mfma_f32_16x16x32_bf16 v[106:109], v[218:221], v[152:155], v[106:109]
	v_mfma_f32_16x16x32_bf16 v[94:97], v[198:201], v[160:163], v[94:97]
	v_mfma_f32_16x16x32_bf16 v[90:93], v[218:221], v[160:163], v[90:93]
	v_mfma_f32_16x16x32_bf16 v[78:81], v[198:201], v[168:171], v[78:81]
	v_mfma_f32_16x16x32_bf16 v[74:77], v[218:221], v[168:171], v[74:77]
	v_mfma_f32_16x16x32_bf16 v[70:73], v[198:201], v[190:193], v[70:73]
	v_mfma_f32_16x16x32_bf16 v[66:69], v[218:221], v[190:193], v[66:69]
	s_mov_b32 m0, s7
	s_barrier
	ds_read_b128 v[148:151], v216 offset:16384
	ds_read_b128 v[152:155], v216 offset:17408
	ds_read_b128 v[156:159], v216 offset:18432
	ds_read_b128 v[160:163], v216 offset:19456
	ds_read_b128 v[164:167], v216 offset:20480
	ds_read_b128 v[168:171], v216 offset:21504
	ds_read_b128 v[172:175], v216 offset:22528
	ds_read_b128 v[190:193], v216 offset:23552
	global_load_lds_dwordx4 v178, s[54:55]
	s_mov_b32 m0, s11
	s_nop 0
	global_load_lds_dwordx4 v180, s[54:55]
	s_barrier
	s_waitcnt lgkmcnt(0)
	v_mfma_f32_16x16x32_bf16 v[62:65], v[132:135], v[148:151], v[62:65]
	v_mfma_f32_16x16x32_bf16 v[58:61], v[140:143], v[148:151], v[58:61]
	v_mfma_f32_16x16x32_bf16 v[54:57], v[132:135], v[156:159], v[54:57]
	v_mfma_f32_16x16x32_bf16 v[50:53], v[140:143], v[156:159], v[50:53]
	v_mfma_f32_16x16x32_bf16 v[38:41], v[132:135], v[164:167], v[38:41]
	v_mfma_f32_16x16x32_bf16 v[34:37], v[140:143], v[164:167], v[34:37]
	v_mfma_f32_16x16x32_bf16 v[22:25], v[132:135], v[172:175], v[22:25]
	v_mfma_f32_16x16x32_bf16 v[18:21], v[140:143], v[172:175], v[18:21]
	v_mfma_f32_16x16x32_bf16 v[62:65], v[136:139], v[152:155], v[62:65]
	v_mfma_f32_16x16x32_bf16 v[58:61], v[144:147], v[152:155], v[58:61]
	v_mfma_f32_16x16x32_bf16 v[54:57], v[136:139], v[160:163], v[54:57]
	v_mfma_f32_16x16x32_bf16 v[50:53], v[144:147], v[160:163], v[50:53]
	v_mfma_f32_16x16x32_bf16 v[38:41], v[136:139], v[168:171], v[38:41]
	v_mfma_f32_16x16x32_bf16 v[34:37], v[144:147], v[168:171], v[34:37]
	v_mfma_f32_16x16x32_bf16 v[22:25], v[136:139], v[190:193], v[22:25]
	v_mfma_f32_16x16x32_bf16 v[18:21], v[144:147], v[190:193], v[18:21]
	s_barrier
	s_add_u32 s24, s52, 0x80000
	s_addc_u32 s25, s53, 0
	s_add_i32 s28, s28, s66
	s_mov_b32 m0, s28
	s_nop 0
	global_load_lds_dwordx4 v0, s[24:25]
	s_add_i32 m0, s28, 0x2000
	s_nop 0
	global_load_lds_dwordx4 v182, s[24:25]
	s_waitcnt vmcnt(6)
	s_barrier
	v_mfma_f32_16x16x32_bf16 v[46:49], v[194:197], v[148:151], v[46:49]
	v_mfma_f32_16x16x32_bf16 v[42:45], v[202:205], v[148:151], v[42:45]
	v_mfma_f32_16x16x32_bf16 v[30:33], v[194:197], v[156:159], v[30:33]
	v_mfma_f32_16x16x32_bf16 v[26:29], v[202:205], v[156:159], v[26:29]
	v_mfma_f32_16x16x32_bf16 v[14:17], v[194:197], v[164:167], v[14:17]
	v_mfma_f32_16x16x32_bf16 v[10:13], v[202:205], v[164:167], v[10:13]
	v_mfma_f32_16x16x32_bf16 v[6:9], v[194:197], v[172:175], v[6:9]
	v_mfma_f32_16x16x32_bf16 v[2:5], v[202:205], v[172:175], v[2:5]
	v_mfma_f32_16x16x32_bf16 v[46:49], v[198:201], v[152:155], v[46:49]
	v_mfma_f32_16x16x32_bf16 v[42:45], v[218:221], v[152:155], v[42:45]
	v_mfma_f32_16x16x32_bf16 v[30:33], v[198:201], v[160:163], v[30:33]
	v_mfma_f32_16x16x32_bf16 v[26:29], v[218:221], v[160:163], v[26:29]
	v_mfma_f32_16x16x32_bf16 v[14:17], v[198:201], v[168:171], v[14:17]
	v_mfma_f32_16x16x32_bf16 v[10:13], v[218:221], v[168:171], v[10:13]
	v_mfma_f32_16x16x32_bf16 v[6:9], v[198:201], v[190:193], v[6:9]
	v_mfma_f32_16x16x32_bf16 v[2:5], v[218:221], v[190:193], v[2:5]
	s_add_i32 s28, 0, 0x18000
	s_barrier
	ds_read_b128 v[132:135], v250
	ds_read_b128 v[136:139], v250 offset:1024
	ds_read_b128 v[140:143], v250 offset:2048
	ds_read_b128 v[144:147], v250 offset:3072
	s_add_u32 s24, s54, 0x80000
	s_addc_u32 s25, s55, 0
	s_mov_b32 m0, s67
	ds_read_b128 v[148:151], v216 offset:32768
	ds_read_b128 v[152:155], v216 offset:33792
	ds_read_b128 v[156:159], v216 offset:34816
	ds_read_b128 v[160:163], v216 offset:35840
	ds_read_b128 v[164:167], v216 offset:36864
	ds_read_b128 v[168:171], v216 offset:37888
	ds_read_b128 v[172:175], v216 offset:38912
	global_load_lds_dwordx4 v178, s[24:25]
	s_mov_b32 m0, s68
	ds_read_b128 v[190:193], v216 offset:39936
	global_load_lds_dwordx4 v180, s[24:25]
	s_waitcnt lgkmcnt(8)
	s_barrier
; #define PG8_STAGE(bufoff, gbase, voff) do { _Pragma("unroll") for (int _i = 0; _i < 2; ++_i) \
;         __builtin_amdgcn_global_load_lds((const unsigned*)((const char*)(gbase) + (voff)[_i]), (LAS unsigned*)(lds + (bufoff) + ldsw + _i * 8192), 16, 0, 0); } while (0)
; #define PG8_LDA(dst, b, h) do { _Pragma("unroll") for (int m = 0; m < 4; ++m) _Pragma("unroll") for (int k = 0; k < 2; ++k) dst[m][k] = *(const LAS bf16x8*)(lds + PG8_SA(b, h) + aoff + m * 2048 + k * 1024); } while (0)
; #define PG8_LDB(dst, b, h) do { _Pragma("unroll") for (int n = 0; n < 2; ++n) _Pragma("unroll") for (int k = 0; k < 2; ++k) dst[n][k] = *(const LAS bf16x8*)(lds + PG8_SB(b, h) + boff + n * 2048 + k * 1024); } while (0)
; #define PG8_MMA(ai, bj, At, Bt) do { __builtin_amdgcn_s_setprio(1); _Pragma("unroll") for (int m = 0; m < 4; ++m) _Pragma("unroll") for (int n = 0; n < 2; ++n) _Pragma("unroll") for (int k = 0; k < 2; ++k) \
;         acc[ai][bj][m][n] = __builtin_amdgcn_mfma_f32_16x16x32_bf16(Bt[n][k], At[m][k], acc[ai][bj][m][n], 0, 0, 0); __builtin_amdgcn_s_setprio(0); } while (0)
; #define PG8_WAIT_V(n) asm volatile("s_waitcnt vmcnt(" #n ")" ::: "memory")
; #define PG8_WAIT_L(n) asm volatile("s_waitcnt lgkmcnt(" #n ")" ::: "memory")
; #define PG8_BAR __builtin_amdgcn_s_barrier()
; #define PG8_SCHED __builtin_amdgcn_sched_barrier(0)
; template <class Epi, class Sched>
; __device__ __forceinline__ void gemm_phase(LAS unsigned char* lds, const Gemm g, const Sched& S, const Epi& E, const int tid) {
;     ...
;             PG8_WAIT_L(8); PG8_BAR; PG8_WAIT_L(0); PG8_MMA(0, 0, At, B0); PG8_BAR; PG8_SCHED;
;             PG8_LDB(B1, 1, 1); PG8_STAGE(PG8_SB(1, 0), b3, voffB);
;             PG8_BAR; PG8_WAIT_L(0); PG8_MMA(0, 1, At, B1); PG8_BAR;
;             PG8_LDA(At, 1, 1); PG8_STAGE(PG8_SA(1, 0), a3, voffA);
;             PG8_BAR; PG8_WAIT_L(0); PG8_MMA(1, 0, At, B0); PG8_BAR; PG8_SCHED;
;             PG8_STAGE(PG8_SB(1, 1), b3 + hstep, voffB);
;             PG8_WAIT_V(6); PG8_BAR; PG8_MMA(1, 1, At, B1); PG8_BAR;
;         }
	s_waitcnt lgkmcnt(0)
	v_mfma_f32_16x16x32_bf16 v[126:129], v[132:135], v[148:151], v[126:129]
	v_mfma_f32_16x16x32_bf16 v[122:125], v[140:143], v[148:151], v[122:125]
	v_mfma_f32_16x16x32_bf16 v[118:121], v[132:135], v[156:159], v[118:121]
	v_mfma_f32_16x16x32_bf16 v[114:117], v[140:143], v[156:159], v[114:117]
	v_mfma_f32_16x16x32_bf16 v[102:105], v[132:135], v[164:167], v[102:105]
	v_mfma_f32_16x16x32_bf16 v[98:101], v[140:143], v[164:167], v[98:101]
	v_mfma_f32_16x16x32_bf16 v[86:89], v[132:135], v[172:175], v[86:89]
	v_mfma_f32_16x16x32_bf16 v[82:85], v[140:143], v[172:175], v[82:85]
	v_mfma_f32_16x16x32_bf16 v[126:129], v[136:139], v[152:155], v[126:129]
	v_mfma_f32_16x16x32_bf16 v[122:125], v[144:147], v[152:155], v[122:125]
	v_mfma_f32_16x16x32_bf16 v[118:121], v[136:139], v[160:163], v[118:121]
	v_mfma_f32_16x16x32_bf16 v[114:117], v[144:147], v[160:163], v[114:117]
	v_mfma_f32_16x16x32_bf16 v[102:105], v[136:139], v[168:171], v[102:105]
	v_mfma_f32_16x16x32_bf16 v[98:101], v[144:147], v[168:171], v[98:101]
	v_mfma_f32_16x16x32_bf16 v[86:89], v[136:139], v[190:193], v[86:89]
	v_mfma_f32_16x16x32_bf16 v[82:85], v[144:147], v[190:193], v[82:85]
	s_barrier
	s_add_i32 s29, 0, 0x1c000
	s_add_i32 s24, s28, s66
	s_add_u32 s98, s52, s36
	s_addc_u32 s99, s53, s37
	s_mov_b32 m0, s24
	ds_read_b128 v[194:197], v249
	ds_read_b128 v[198:201], v249 offset:1024
	ds_read_b128 v[202:205], v249 offset:2048
	ds_read_b128 v[218:221], v249 offset:3072
	global_load_lds_dwordx4 v0, s[98:99]
	s_add_i32 m0, s24, 0x2000
	s_add_u32 s98, s52, s36
	s_addc_u32 s99, s53, s37
	global_load_lds_dwordx4 v182, s[98:99]
	s_barrier
	s_waitcnt lgkmcnt(0)
	v_mfma_f32_16x16x32_bf16 v[110:113], v[194:197], v[148:151], v[110:113]
	v_mfma_f32_16x16x32_bf16 v[106:109], v[202:205], v[148:151], v[106:109]
	v_mfma_f32_16x16x32_bf16 v[94:97], v[194:197], v[156:159], v[94:97]
	v_mfma_f32_16x16x32_bf16 v[90:93], v[202:205], v[156:159], v[90:93]
	v_mfma_f32_16x16x32_bf16 v[78:81], v[194:197], v[164:167], v[78:81]
	v_mfma_f32_16x16x32_bf16 v[74:77], v[202:205], v[164:167], v[74:77]
	v_mfma_f32_16x16x32_bf16 v[70:73], v[194:197], v[172:175], v[70:73]
	v_mfma_f32_16x16x32_bf16 v[66:69], v[202:205], v[172:175], v[66:69]
	v_mfma_f32_16x16x32_bf16 v[110:113], v[198:201], v[152:155], v[110:113]
	v_mfma_f32_16x16x32_bf16 v[106:109], v[218:221], v[152:155], v[106:109]
	v_mfma_f32_16x16x32_bf16 v[94:97], v[198:201], v[160:163], v[94:97]
	v_mfma_f32_16x16x32_bf16 v[90:93], v[218:221], v[160:163], v[90:93]
	v_mfma_f32_16x16x32_bf16 v[78:81], v[198:201], v[168:171], v[78:81]
	v_mfma_f32_16x16x32_bf16 v[74:77], v[218:221], v[168:171], v[74:77]
	v_mfma_f32_16x16x32_bf16 v[70:73], v[198:201], v[190:193], v[70:73]
	v_mfma_f32_16x16x32_bf16 v[66:69], v[218:221], v[190:193], v[66:69]
	s_mov_b32 m0, s72
	s_add_u32 s98, s54, s36
	s_addc_u32 s99, s55, s37
	s_barrier
	ds_read_b128 v[148:151], v216 offset:49152
	ds_read_b128 v[152:155], v216 offset:50176
	ds_read_b128 v[156:159], v216 offset:51200
	ds_read_b128 v[160:163], v216 offset:52224
	ds_read_b128 v[164:167], v216 offset:53248
	ds_read_b128 v[168:171], v216 offset:54272
	ds_read_b128 v[172:175], v216 offset:55296
	ds_read_b128 v[190:193], v216 offset:56320
	global_load_lds_dwordx4 v178, s[98:99]
	s_mov_b32 m0, s73
	s_add_u32 s98, s54, s36
	s_addc_u32 s99, s55, s37
	global_load_lds_dwordx4 v180, s[98:99]
	s_barrier
	s_waitcnt lgkmcnt(0)
	v_mfma_f32_16x16x32_bf16 v[62:65], v[132:135], v[148:151], v[62:65]
	v_mfma_f32_16x16x32_bf16 v[58:61], v[140:143], v[148:151], v[58:61]
	v_mfma_f32_16x16x32_bf16 v[54:57], v[132:135], v[156:159], v[54:57]
	v_mfma_f32_16x16x32_bf16 v[50:53], v[140:143], v[156:159], v[50:53]
	v_mfma_f32_16x16x32_bf16 v[38:41], v[132:135], v[164:167], v[38:41]
	v_mfma_f32_16x16x32_bf16 v[34:37], v[140:143], v[164:167], v[34:37]
	v_mfma_f32_16x16x32_bf16 v[22:25], v[132:135], v[172:175], v[22:25]
	v_mfma_f32_16x16x32_bf16 v[18:21], v[140:143], v[172:175], v[18:21]
	v_mfma_f32_16x16x32_bf16 v[62:65], v[136:139], v[152:155], v[62:65]
	v_mfma_f32_16x16x32_bf16 v[58:61], v[144:147], v[152:155], v[58:61]
	v_mfma_f32_16x16x32_bf16 v[54:57], v[136:139], v[160:163], v[54:57]
	v_mfma_f32_16x16x32_bf16 v[50:53], v[144:147], v[160:163], v[50:53]
	v_mfma_f32_16x16x32_bf16 v[38:41], v[136:139], v[168:171], v[38:41]
	v_mfma_f32_16x16x32_bf16 v[34:37], v[144:147], v[168:171], v[34:37]
	v_mfma_f32_16x16x32_bf16 v[22:25], v[136:139], v[190:193], v[22:25]
	v_mfma_f32_16x16x32_bf16 v[18:21], v[144:147], v[190:193], v[18:21]
	s_barrier
	s_add_u32 s24, s52, 0x80080
	s_addc_u32 s25, s53, 0
	s_add_i32 s28, s29, s66
	s_mov_b32 m0, s28
	s_nop 0
	global_load_lds_dwordx4 v0, s[24:25]
	s_add_i32 m0, s28, 0x2000
	s_nop 0
	global_load_lds_dwordx4 v182, s[24:25]
	s_waitcnt vmcnt(6)
	s_barrier
	v_mfma_f32_16x16x32_bf16 v[46:49], v[194:197], v[148:151], v[46:49]
	v_mfma_f32_16x16x32_bf16 v[42:45], v[202:205], v[148:151], v[42:45]
	v_mfma_f32_16x16x32_bf16 v[30:33], v[194:197], v[156:159], v[30:33]
	v_mfma_f32_16x16x32_bf16 v[26:29], v[202:205], v[156:159], v[26:29]
	v_mfma_f32_16x16x32_bf16 v[14:17], v[194:197], v[164:167], v[14:17]
	v_mfma_f32_16x16x32_bf16 v[10:13], v[202:205], v[164:167], v[10:13]
	v_mfma_f32_16x16x32_bf16 v[6:9], v[194:197], v[172:175], v[6:9]
	v_mfma_f32_16x16x32_bf16 v[2:5], v[202:205], v[172:175], v[2:5]
	v_mfma_f32_16x16x32_bf16 v[46:49], v[198:201], v[152:155], v[46:49]
	v_mfma_f32_16x16x32_bf16 v[42:45], v[218:221], v[152:155], v[42:45]
	v_mfma_f32_16x16x32_bf16 v[30:33], v[198:201], v[160:163], v[30:33]
	v_mfma_f32_16x16x32_bf16 v[26:29], v[218:221], v[160:163], v[26:29]
	v_mfma_f32_16x16x32_bf16 v[14:17], v[198:201], v[168:171], v[14:17]
	v_mfma_f32_16x16x32_bf16 v[10:13], v[218:221], v[168:171], v[10:13]
	v_mfma_f32_16x16x32_bf16 v[6:9], v[198:201], v[190:193], v[6:9]
	v_mfma_f32_16x16x32_bf16 v[2:5], v[218:221], v[190:193], v[2:5]
	s_add_i32 s24, s21, 2
	s_add_u32 s5, s5, 0x100
	s_addc_u32 s23, s23, 0
	s_cmp_ge_i32 s21, s78
	s_mov_b64 s[48:49], s[50:51]
	s_mov_b32 s21, s24
	s_barrier
	s_cbranch_scc1 .LBB0_1396

; #define PG8_STAGE(bufoff, gbase, voff) do { _Pragma("unroll") for (int _i = 0; _i < 2; ++_i) \
;         __builtin_amdgcn_global_load_lds((const unsigned*)((const char*)(gbase) + (voff)[_i]), (LAS unsigned*)(lds + (bufoff) + ldsw + _i * 8192), 16, 0, 0); } while (0)
; #define PG8_WAIT_V(n) asm volatile("s_waitcnt vmcnt(" #n ")" ::: "memory")
; #define PG8_BAR __builtin_amdgcn_s_barrier()
; template <class Epi, class Sched>
; __device__ __forceinline__ void gemm_phase(LAS unsigned char* lds, const Gemm g, const Sched& S, const Epi& E, const int tid) {
;     ...
;     for (int i = 0; i < 2; ++i) { int R, C; stage_rc(tid * 16 + i * 8192, R, C); const int Rb = Epi::PERM ? ((R & ~31) + perm32(R & 31)) : R; const int Ra = Epi::ROWP ? ((R & ~63) + 4 * (R & 15) + ((R >> 4) & 3)) : R;
;         voffA[i] = (unsigned)(Ra * K + C) * 2u; voffB[i] = (unsigned)(Rb * K + C) * 2u; }
;     const size_t kstep = (size_t)(BK * 2);
;     const size_t hstep = (size_t)HALF * K * 2;
;     const size_t tstep = 2 * hstep;
;     const unsigned ldsw = (unsigned)wid * 1024u;
;     const int aoff = lds_byte(wr * 64 + fr, fq * 8), boff = lds_byte(wc * 32 + fr, fq * 8);
;     ...
;     f32x4 acc[2][2][4][2];
; #pragma unroll
;     for (int a = 0; a < 2; ++a)
; #pragma unroll
;         for (int b = 0; b < 2; ++b)
; #pragma unroll
;             for (int m = 0; m < 4; ++m)
; #pragma unroll
;                 for (int n = 0; n < 2; ++n) acc[a][b][m][n] = (f32x4){0.f, 0.f, 0.f, 0.f};
;     bf16x8 At[4][2], B0[2][2], B1[2][2];
;     const char* cA = (const char*)g.A + (size_t)cur.pm * tstep + (size_t)cur.ks * cur.nt * kstep; const char* cB = (const char*)g.Bt + (size_t)cur.pn * tstep + (size_t)cur.ks * cur.nt * kstep;
;     S.a_ready(cur);
;     PG8_STAGE(PG8_SB(0, 0), cB, voffB); PG8_STAGE(PG8_SA(0, 0), cA, voffA); PG8_STAGE(PG8_SB(0, 1), cB + hstep, voffB); PG8_STAGE(PG8_SA(0, 1), cA + hstep, voffA);
;     if (wr == 1) PG8_BAR;
;     PG8_WAIT_V(4); PG8_BAR;
;     PG8_STAGE(PG8_SB(1, 0), cB + kstep, voffB); PG8_STAGE(PG8_SA(1, 0), cA + kstep, voffA); PG8_STAGE(PG8_SB(1, 1), cB + hstep + kstep, voffB);
;     PG8_WAIT_V(6); PG8_BAR;
.LBB0_1572:
	v_and_b32_e32 v223, 15, v220
	v_and_b32_e32 v18, 48, v220
	v_lshlrev_b32_e32 v19, 2, v220
	s_and_b32 s61, s59, 3
	s_lshl_b32 s41, s60, 13
	v_lshl_or_b32 v18, v223, 6, v18
	v_and_b32_e32 v19, 32, v19
	s_add_i32 m0, s25, 0x18000
	v_lshl_add_u64 v[8:9], v[8:9], 0, s[36:37]
	v_bitop3_b32 v20, v18, s41, v19 bitop3:0xde
	s_lshl_b32 s41, s61, 12
	s_waitcnt vmcnt(4)
	s_barrier
	global_load_lds_dwordx4 v[8:9], off
	v_lshl_add_u64 v[6:7], v[6:7], 0, s[36:37]
	s_add_i32 m0, s25, 0x1a000
	s_add_i32 s63, s25, 0x8000
	s_add_i32 s64, s25, 0xa000
	global_load_lds_dwordx4 v[6:7], off
	v_lshl_add_u64 v[4:5], v[4:5], 0, s[36:37]
	s_mov_b32 m0, s63
	s_add_u32 s42, s0, 0x160080
	global_load_lds_dwordx4 v[4:5], off
	v_lshl_add_u64 v[2:3], v[2:3], 0, s[36:37]
	s_mov_b32 m0, s64
	s_addc_u32 s43, s1, 0
	global_load_lds_dwordx4 v[2:3], off
	s_add_i32 m0, s25, 0x1c000
	v_lshl_add_u64 v[2:3], s[42:43], 0, v[0:1]
	global_load_lds_dwordx4 v[2:3], off
	v_lshl_add_u64 v[2:3], s[42:43], 0, v[134:135]
	s_add_i32 m0, s25, 0x1e000
	s_add_i32 s38, s38, s51
	global_load_lds_dwordx4 v[2:3], off
	s_sub_i32 s38, s38, s40
	s_mul_i32 s39, s39, 28
	s_movk_i32 s43, 0x1600
	s_sub_i32 s38, s38, s39
	v_lshrrev_b32_e32 v3, 1, v10
	v_mul_lo_u32 v2, v12, s43
	s_mov_b32 s42, 0x16000
	v_bitop3_b32 v140, s41, v18, v19 bitop3:0xf6
	s_mul_hi_i32 s40, s38, 0x2c0000
	s_mul_i32 s41, s38, 0x2c0000
	v_mad_u64_u32 v[2:3], s[38:39], v3, s42, v[2:3]
	v_or_b32_e32 v2, v2, v11
	s_add_u32 s38, s22, s41
	v_add_lshl_u32 v2, v2, v13, 1
	v_mov_b32_e32 v3, v1
	s_addc_u32 s39, s23, s40
	v_lshl_add_u64 v[136:137], s[38:39], 0, v[2:3]
	v_lshrrev_b32_e32 v3, 1, v14
	v_mul_lo_u32 v2, v16, s43
	v_mad_u64_u32 v[2:3], s[40:41], v3, s42, v[2:3]
	v_or_b32_e32 v2, v2, v15
	s_waitcnt vmcnt(6)
	v_add_lshl_u32 v2, v2, v17, 1
	v_mov_b32_e32 v3, v1
	v_lshl_add_u64 v[138:139], s[38:39], 0, v[2:3]
	v_mov_b32_e32 v2, 0
	v_lshl_or_b32 v222, s60, 6, v223
	s_mov_b32 s65, -2
	s_mov_b64 s[38:39], 0x1e124080
	v_add_u32_e32 v141, 0, v20
	v_mov_b32_e32 v3, v2
	v_mov_b32_e32 v4, v2
	v_mov_b32_e32 v5, v2
	v_mov_b32_e32 v6, v2
	v_mov_b32_e32 v7, v2
	v_mov_b32_e32 v8, v2
	v_mov_b32_e32 v9, v2
	v_mov_b32_e32 v14, v2
	v_mov_b32_e32 v15, v2
	v_mov_b32_e32 v16, v2
	v_mov_b32_e32 v17, v2
	v_mov_b32_e32 v22, v2
	v_mov_b32_e32 v23, v2
	v_mov_b32_e32 v24, v2
	v_mov_b32_e32 v25, v2
	v_mov_b32_e32 v30, v2
	v_mov_b32_e32 v31, v2
	v_mov_b32_e32 v32, v2
	v_mov_b32_e32 v33, v2
	v_mov_b32_e32 v38, v2
	v_mov_b32_e32 v39, v2
	v_mov_b32_e32 v40, v2
	v_mov_b32_e32 v41, v2
	v_mov_b32_e32 v46, v2
	v_mov_b32_e32 v47, v2
	v_mov_b32_e32 v48, v2
	v_mov_b32_e32 v49, v2
	v_mov_b32_e32 v54, v2
	v_mov_b32_e32 v55, v2
	v_mov_b32_e32 v56, v2
	v_mov_b32_e32 v57, v2
	v_mov_b32_e32 v10, v2
	v_mov_b32_e32 v11, v2
	v_mov_b32_e32 v12, v2
	v_mov_b32_e32 v13, v2
	v_mov_b32_e32 v18, v2
	v_mov_b32_e32 v19, v2
	v_mov_b32_e32 v20, v2
	v_mov_b32_e32 v21, v2
	v_mov_b32_e32 v26, v2
	v_mov_b32_e32 v27, v2
	v_mov_b32_e32 v28, v2
	v_mov_b32_e32 v29, v2
	v_mov_b32_e32 v34, v2
	v_mov_b32_e32 v35, v2
	v_mov_b32_e32 v36, v2
	v_mov_b32_e32 v37, v2
	v_mov_b32_e32 v42, v2
	v_mov_b32_e32 v43, v2
	v_mov_b32_e32 v44, v2
	v_mov_b32_e32 v45, v2
	v_mov_b32_e32 v50, v2
	v_mov_b32_e32 v51, v2
	v_mov_b32_e32 v52, v2
	v_mov_b32_e32 v53, v2
	v_mov_b32_e32 v58, v2
	v_mov_b32_e32 v59, v2
	v_mov_b32_e32 v60, v2
	v_mov_b32_e32 v61, v2
	v_mov_b32_e32 v62, v2
	v_mov_b32_e32 v63, v2
	v_mov_b32_e32 v64, v2
	v_mov_b32_e32 v65, v2
	v_mov_b32_e32 v66, v2
	v_mov_b32_e32 v67, v2
	v_mov_b32_e32 v68, v2
	v_mov_b32_e32 v69, v2
	v_mov_b32_e32 v70, v2
	v_mov_b32_e32 v71, v2
	v_mov_b32_e32 v72, v2
	v_mov_b32_e32 v73, v2
	v_mov_b32_e32 v78, v2
	v_mov_b32_e32 v79, v2
	v_mov_b32_e32 v80, v2
	v_mov_b32_e32 v81, v2
	v_mov_b32_e32 v86, v2
	v_mov_b32_e32 v87, v2
	v_mov_b32_e32 v88, v2
	v_mov_b32_e32 v89, v2
	v_mov_b32_e32 v94, v2
	v_mov_b32_e32 v95, v2
	v_mov_b32_e32 v96, v2
	v_mov_b32_e32 v97, v2
	v_mov_b32_e32 v102, v2
	v_mov_b32_e32 v103, v2
	v_mov_b32_e32 v104, v2
	v_mov_b32_e32 v105, v2
	v_mov_b32_e32 v106, v2
	v_mov_b32_e32 v107, v2
	v_mov_b32_e32 v108, v2
	v_mov_b32_e32 v109, v2
	v_mov_b32_e32 v114, v2
	v_mov_b32_e32 v115, v2
	v_mov_b32_e32 v116, v2
	v_mov_b32_e32 v117, v2
	v_mov_b32_e32 v74, v2
	v_mov_b32_e32 v75, v2
	v_mov_b32_e32 v76, v2
	v_mov_b32_e32 v77, v2
	v_mov_b32_e32 v82, v2
	v_mov_b32_e32 v83, v2
	v_mov_b32_e32 v84, v2
	v_mov_b32_e32 v85, v2
	v_mov_b32_e32 v90, v2
	v_mov_b32_e32 v91, v2
	v_mov_b32_e32 v92, v2
	v_mov_b32_e32 v93, v2
	v_mov_b32_e32 v98, v2
	v_mov_b32_e32 v99, v2
	v_mov_b32_e32 v100, v2
	v_mov_b32_e32 v101, v2
	v_mov_b32_e32 v110, v2
	v_mov_b32_e32 v111, v2
	v_mov_b32_e32 v112, v2
	v_mov_b32_e32 v113, v2
	v_mov_b32_e32 v118, v2
	v_mov_b32_e32 v119, v2
	v_mov_b32_e32 v120, v2
	v_mov_b32_e32 v121, v2
	v_mov_b32_e32 v122, v2
	v_mov_b32_e32 v123, v2
	v_mov_b32_e32 v124, v2
	v_mov_b32_e32 v125, v2
	v_mov_b32_e32 v126, v2
	v_mov_b32_e32 v127, v2
	v_mov_b32_e32 v128, v2
	v_mov_b32_e32 v129, v2
	s_barrier
	v_add_u32_e32 v252, 0x10000, v140
	v_add_u32_e32 v251, 0x14000, v140
	v_add_u32_e32 v250, 0x18000, v140
	v_add_u32_e32 v249, 0x1c000, v140
; #define PG8_STAGE(bufoff, gbase, voff) do { _Pragma("unroll") for (int _i = 0; _i < 2; ++_i) \
;         __builtin_amdgcn_global_load_lds((const unsigned*)((const char*)(gbase) + (voff)[_i]), (LAS unsigned*)(lds + (bufoff) + ldsw + _i * 8192), 16, 0, 0); } while (0)
; #define PG8_LDA(dst, b, h) do { _Pragma("unroll") for (int m = 0; m < 4; ++m) _Pragma("unroll") for (int k = 0; k < 2; ++k) dst[m][k] = *(const LAS bf16x8*)(lds + PG8_SA(b, h) + aoff + m * 2048 + k * 1024); } while (0)
; #define PG8_LDB(dst, b, h) do { _Pragma("unroll") for (int n = 0; n < 2; ++n) _Pragma("unroll") for (int k = 0; k < 2; ++k) dst[n][k] = *(const LAS bf16x8*)(lds + PG8_SB(b, h) + boff + n * 2048 + k * 1024); } while (0)
; #define PG8_MMA(ai, bj, At, Bt) do { __builtin_amdgcn_s_setprio(1); _Pragma("unroll") for (int m = 0; m < 4; ++m) _Pragma("unroll") for (int n = 0; n < 2; ++n) _Pragma("unroll") for (int k = 0; k < 2; ++k) \
;         acc[ai][bj][m][n] = __builtin_amdgcn_mfma_f32_16x16x32_bf16(Bt[n][k], At[m][k], acc[ai][bj][m][n], 0, 0, 0); __builtin_amdgcn_s_setprio(0); } while (0)
; #define PG8_WAIT_V(n) asm volatile("s_waitcnt vmcnt(" #n ")" ::: "memory")
; #define PG8_WAIT_L(n) asm volatile("s_waitcnt lgkmcnt(" #n ")" ::: "memory")
; #define PG8_BAR __builtin_amdgcn_s_barrier()
; #define PG8_SCHED __builtin_amdgcn_sched_barrier(0)
; template <class Epi, class Sched>
; __device__ __forceinline__ void gemm_phase(LAS unsigned char* lds, const Gemm g, const Sched& S, const Epi& E, const int tid) {
;     ...
;             PG8_LDB(B0, 0, 0); PG8_SCHED; PG8_LDA(At, 0, 0); PG8_STAGE(PG8_SA(1, 1), a1 + hstep, voffA);
;             PG8_WAIT_L(8); PG8_BAR; PG8_WAIT_L(0); PG8_MMA(0, 0, At, B0); PG8_BAR; PG8_SCHED;
;             PG8_LDB(B1, 0, 1); PG8_STAGE(PG8_SB(0, 0), b2, voffB);
;             PG8_BAR; PG8_WAIT_L(0); PG8_MMA(0, 1, At, B1); PG8_BAR;
;             PG8_LDA(At, 0, 1); PG8_STAGE(PG8_SA(0, 0), a2, voffA);
;             PG8_BAR; PG8_WAIT_L(0); PG8_MMA(1, 0, At, B0); PG8_BAR; PG8_SCHED;
;             PG8_STAGE(PG8_SB(0, 1), b2 + hstep, voffB);
;             PG8_WAIT_V(6); PG8_BAR; PG8_MMA(1, 1, At, B1); PG8_BAR;
.LBB0_1573:
	s_add_u32 s40, s38, 0xe1edc080
	s_addc_u32 s41, s39, -1
	s_cmpk_lg_i32 s65, 0x54
	s_cselect_b32 s40, s40, 0
	s_cselect_b32 s41, s41, 0
	s_add_u32 s42, s4, s40
	s_addc_u32 s43, s5, s41
	s_add_i32 s66, 0, 0x10000
	ds_read_b128 v[142:145], v252
	ds_read_b128 v[146:149], v252 offset:1024
	ds_read_b128 v[150:153], v252 offset:2048
	ds_read_b128 v[154:157], v252 offset:3072
	s_add_u32 s40, s0, s40
	s_addc_u32 s41, s1, s41
	v_lshl_add_u64 v[190:191], v[136:137], 0, s[38:39]
	s_add_i32 m0, s25, 0xc000
	ds_read_b128 v[158:161], v141
	ds_read_b128 v[162:165], v141 offset:1024
	ds_read_b128 v[166:169], v141 offset:2048
	ds_read_b128 v[170:173], v141 offset:3072
	ds_read_b128 v[174:177], v141 offset:4096
	ds_read_b128 v[178:181], v141 offset:5120
	ds_read_b128 v[182:185], v141 offset:6144
	ds_read_b128 v[186:189], v141 offset:7168
	global_load_lds_dwordx4 v[190:191], off
	s_add_i32 m0, s25, 0xe000
	v_lshl_add_u64 v[190:191], v[138:139], 0, s[38:39]
	global_load_lds_dwordx4 v[190:191], off
	s_waitcnt lgkmcnt(8)
	s_barrier
	s_waitcnt lgkmcnt(0)
	v_mfma_f32_16x16x32_bf16 v[126:129], v[142:145], v[158:161], v[126:129]
	v_mfma_f32_16x16x32_bf16 v[122:125], v[150:153], v[158:161], v[122:125]
	v_mfma_f32_16x16x32_bf16 v[118:121], v[142:145], v[166:169], v[118:121]
	v_mfma_f32_16x16x32_bf16 v[110:113], v[150:153], v[166:169], v[110:113]
	v_mfma_f32_16x16x32_bf16 v[98:101], v[142:145], v[174:177], v[98:101]
	v_mfma_f32_16x16x32_bf16 v[90:93], v[150:153], v[174:177], v[90:93]
	v_mfma_f32_16x16x32_bf16 v[82:85], v[142:145], v[182:185], v[82:85]
	v_mfma_f32_16x16x32_bf16 v[74:77], v[150:153], v[182:185], v[74:77]
	v_mfma_f32_16x16x32_bf16 v[126:129], v[146:149], v[162:165], v[126:129]
	v_mfma_f32_16x16x32_bf16 v[122:125], v[154:157], v[162:165], v[122:125]
	v_mfma_f32_16x16x32_bf16 v[118:121], v[146:149], v[170:173], v[118:121]
	v_mfma_f32_16x16x32_bf16 v[110:113], v[154:157], v[170:173], v[110:113]
	v_mfma_f32_16x16x32_bf16 v[98:101], v[146:149], v[178:181], v[98:101]
	v_mfma_f32_16x16x32_bf16 v[90:93], v[154:157], v[178:181], v[90:93]
	v_mfma_f32_16x16x32_bf16 v[82:85], v[146:149], v[186:189], v[82:85]
	v_mfma_f32_16x16x32_bf16 v[74:77], v[154:157], v[186:189], v[74:77]
	s_barrier
	s_add_i32 s68, 0, 0x14000
	s_add_i32 s66, s66, s24
	s_mov_b32 m0, s66
	ds_read_b128 v[190:193], v251
	ds_read_b128 v[194:197], v251 offset:1024
	ds_read_b128 v[198:201], v251 offset:2048
	ds_read_b128 v[202:205], v251 offset:3072
	global_load_lds_dwordx4 v0, s[40:41]
	s_add_i32 m0, s66, 0x2000
	s_nop 0
	global_load_lds_dwordx4 v134, s[40:41]
	s_barrier
	s_waitcnt lgkmcnt(0)
	v_mfma_f32_16x16x32_bf16 v[114:117], v[190:193], v[158:161], v[114:117]
	v_mfma_f32_16x16x32_bf16 v[106:109], v[198:201], v[158:161], v[106:109]
	v_mfma_f32_16x16x32_bf16 v[102:105], v[190:193], v[166:169], v[102:105]
	v_mfma_f32_16x16x32_bf16 v[94:97], v[198:201], v[166:169], v[94:97]
	v_mfma_f32_16x16x32_bf16 v[86:89], v[190:193], v[174:177], v[86:89]
	v_mfma_f32_16x16x32_bf16 v[78:81], v[198:201], v[174:177], v[78:81]
	v_mfma_f32_16x16x32_bf16 v[70:73], v[190:193], v[182:185], v[70:73]
	v_mfma_f32_16x16x32_bf16 v[66:69], v[198:201], v[182:185], v[66:69]
	v_mfma_f32_16x16x32_bf16 v[114:117], v[194:197], v[162:165], v[114:117]
	v_mfma_f32_16x16x32_bf16 v[106:109], v[202:205], v[162:165], v[106:109]
	v_mfma_f32_16x16x32_bf16 v[102:105], v[194:197], v[170:173], v[102:105]
	v_mfma_f32_16x16x32_bf16 v[94:97], v[202:205], v[170:173], v[94:97]
	v_mfma_f32_16x16x32_bf16 v[86:89], v[194:197], v[178:181], v[86:89]
	v_mfma_f32_16x16x32_bf16 v[78:81], v[202:205], v[178:181], v[78:81]
	v_mfma_f32_16x16x32_bf16 v[70:73], v[194:197], v[186:189], v[70:73]
	v_mfma_f32_16x16x32_bf16 v[66:69], v[202:205], v[186:189], v[66:69]
	s_mov_b32 m0, s25
	v_lshl_add_u64 v[210:211], s[42:43], 0, v[130:131]
	s_barrier
	ds_read_b128 v[158:161], v141 offset:16384
	ds_read_b128 v[162:165], v141 offset:17408
	ds_read_b128 v[166:169], v141 offset:18432
	ds_read_b128 v[170:173], v141 offset:19456
	ds_read_b128 v[174:177], v141 offset:20480
	ds_read_b128 v[178:181], v141 offset:21504
	ds_read_b128 v[182:185], v141 offset:22528
	ds_read_b128 v[186:189], v141 offset:23552
	global_load_lds_dwordx4 v[210:211], off
	s_mov_b32 m0, s28
	v_lshl_add_u64 v[214:215], s[42:43], 0, v[132:133]
	global_load_lds_dwordx4 v[214:215], off
	s_barrier
	s_waitcnt lgkmcnt(0)
	v_mfma_f32_16x16x32_bf16 v[62:65], v[142:145], v[158:161], v[62:65]
	v_mfma_f32_16x16x32_bf16 v[58:61], v[150:153], v[158:161], v[58:61]
	v_mfma_f32_16x16x32_bf16 v[50:53], v[142:145], v[166:169], v[50:53]
	v_mfma_f32_16x16x32_bf16 v[42:45], v[150:153], v[166:169], v[42:45]
	v_mfma_f32_16x16x32_bf16 v[34:37], v[142:145], v[174:177], v[34:37]
	v_mfma_f32_16x16x32_bf16 v[26:29], v[150:153], v[174:177], v[26:29]
	v_mfma_f32_16x16x32_bf16 v[18:21], v[142:145], v[182:185], v[18:21]
	v_mfma_f32_16x16x32_bf16 v[10:13], v[150:153], v[182:185], v[10:13]
	v_mfma_f32_16x16x32_bf16 v[62:65], v[146:149], v[162:165], v[62:65]
	v_mfma_f32_16x16x32_bf16 v[58:61], v[154:157], v[162:165], v[58:61]
	v_mfma_f32_16x16x32_bf16 v[50:53], v[146:149], v[170:173], v[50:53]
	v_mfma_f32_16x16x32_bf16 v[42:45], v[154:157], v[170:173], v[42:45]
	v_mfma_f32_16x16x32_bf16 v[34:37], v[146:149], v[178:181], v[34:37]
	v_mfma_f32_16x16x32_bf16 v[26:29], v[154:157], v[178:181], v[26:29]
	v_mfma_f32_16x16x32_bf16 v[18:21], v[146:149], v[186:189], v[18:21]
	v_mfma_f32_16x16x32_bf16 v[10:13], v[154:157], v[186:189], v[10:13]
	s_barrier
	s_add_u32 s66, s40, 0x160000
	s_addc_u32 s67, s41, 0
	s_add_i32 s68, s68, s24
	s_mov_b32 m0, s68
	s_nop 0
	global_load_lds_dwordx4 v0, s[66:67]
	s_add_i32 m0, s68, 0x2000
	s_nop 0
	global_load_lds_dwordx4 v134, s[66:67]
	s_waitcnt vmcnt(6)
	s_barrier
; #define PG8_STAGE(bufoff, gbase, voff) do { _Pragma("unroll") for (int _i = 0; _i < 2; ++_i) \
;         __builtin_amdgcn_global_load_lds((const unsigned*)((const char*)(gbase) + (voff)[_i]), (LAS unsigned*)(lds + (bufoff) + ldsw + _i * 8192), 16, 0, 0); } while (0)
; #define PG8_LDA(dst, b, h) do { _Pragma("unroll") for (int m = 0; m < 4; ++m) _Pragma("unroll") for (int k = 0; k < 2; ++k) dst[m][k] = *(const LAS bf16x8*)(lds + PG8_SA(b, h) + aoff + m * 2048 + k * 1024); } while (0)
; #define PG8_LDB(dst, b, h) do { _Pragma("unroll") for (int n = 0; n < 2; ++n) _Pragma("unroll") for (int k = 0; k < 2; ++k) dst[n][k] = *(const LAS bf16x8*)(lds + PG8_SB(b, h) + boff + n * 2048 + k * 1024); } while (0)
; #define PG8_MMA(ai, bj, At, Bt) do { __builtin_amdgcn_s_setprio(1); _Pragma("unroll") for (int m = 0; m < 4; ++m) _Pragma("unroll") for (int n = 0; n < 2; ++n) _Pragma("unroll") for (int k = 0; k < 2; ++k) \
;         acc[ai][bj][m][n] = __builtin_amdgcn_mfma_f32_16x16x32_bf16(Bt[n][k], At[m][k], acc[ai][bj][m][n], 0, 0, 0); __builtin_amdgcn_s_setprio(0); } while (0)
; #define PG8_WAIT_V(n) asm volatile("s_waitcnt vmcnt(" #n ")" ::: "memory")
; #define PG8_WAIT_L(n) asm volatile("s_waitcnt lgkmcnt(" #n ")" ::: "memory")
; #define PG8_BAR __builtin_amdgcn_s_barrier()
; #define PG8_SCHED __builtin_amdgcn_sched_barrier(0)
; template <class Epi, class Sched>
; __device__ __forceinline__ void gemm_phase(LAS unsigned char* lds, const Gemm g, const Sched& S, const Epi& E, const int tid) {
;     ...
;             PG8_WAIT_V(6); PG8_BAR; PG8_MMA(1, 1, At, B1); PG8_BAR;
;             PG8_LDB(B0, 1, 0); PG8_SCHED; PG8_LDA(At, 1, 0); PG8_STAGE(PG8_SA(0, 1), a2 + hstep, voffA);
;             PG8_WAIT_L(8); PG8_BAR; PG8_WAIT_L(0); PG8_MMA(0, 0, At, B0); PG8_BAR; PG8_SCHED;
;             PG8_LDB(B1, 1, 1); PG8_STAGE(PG8_SB(1, 0), b3, voffB);
;             PG8_BAR; PG8_WAIT_L(0); PG8_MMA(0, 1, At, B1); PG8_BAR;
;             PG8_LDA(At, 1, 1); PG8_STAGE(PG8_SA(1, 0), a3, voffA);
	v_mfma_f32_16x16x32_bf16 v[54:57], v[190:193], v[158:161], v[54:57]
	v_mfma_f32_16x16x32_bf16 v[46:49], v[198:201], v[158:161], v[46:49]
	v_mfma_f32_16x16x32_bf16 v[38:41], v[190:193], v[166:169], v[38:41]
	v_mfma_f32_16x16x32_bf16 v[30:33], v[198:201], v[166:169], v[30:33]
	v_mfma_f32_16x16x32_bf16 v[22:25], v[190:193], v[174:177], v[22:25]
	v_mfma_f32_16x16x32_bf16 v[14:17], v[198:201], v[174:177], v[14:17]
	v_mfma_f32_16x16x32_bf16 v[6:9], v[190:193], v[182:185], v[6:9]
	v_mfma_f32_16x16x32_bf16 v[2:5], v[198:201], v[182:185], v[2:5]
	v_mfma_f32_16x16x32_bf16 v[54:57], v[194:197], v[162:165], v[54:57]
	v_mfma_f32_16x16x32_bf16 v[46:49], v[202:205], v[162:165], v[46:49]
	v_mfma_f32_16x16x32_bf16 v[38:41], v[194:197], v[170:173], v[38:41]
	v_mfma_f32_16x16x32_bf16 v[30:33], v[202:205], v[170:173], v[30:33]
	v_mfma_f32_16x16x32_bf16 v[22:25], v[194:197], v[178:181], v[22:25]
	v_mfma_f32_16x16x32_bf16 v[14:17], v[202:205], v[178:181], v[14:17]
	v_mfma_f32_16x16x32_bf16 v[6:9], v[194:197], v[186:189], v[6:9]
	v_mfma_f32_16x16x32_bf16 v[2:5], v[202:205], v[186:189], v[2:5]
	s_add_i32 s66, 0, 0x18000
	s_barrier
	ds_read_b128 v[142:145], v250
	ds_read_b128 v[146:149], v250 offset:1024
	ds_read_b128 v[150:153], v250 offset:2048
	ds_read_b128 v[154:157], v250 offset:3072
	s_add_u32 s42, s42, 0x160000
	s_addc_u32 s43, s43, 0
	s_mov_b32 m0, s29
	ds_read_b128 v[158:161], v141 offset:32768
	ds_read_b128 v[162:165], v141 offset:33792
	ds_read_b128 v[166:169], v141 offset:34816
	ds_read_b128 v[170:173], v141 offset:35840
	ds_read_b128 v[174:177], v141 offset:36864
	ds_read_b128 v[178:181], v141 offset:37888
	ds_read_b128 v[182:185], v141 offset:38912
	global_load_lds_dwordx4 v130, s[42:43]
	s_mov_b32 m0, s62
	ds_read_b128 v[186:189], v141 offset:39936
	global_load_lds_dwordx4 v132, s[42:43]
	s_waitcnt lgkmcnt(8)
	s_barrier
	s_waitcnt lgkmcnt(0)
	v_mfma_f32_16x16x32_bf16 v[126:129], v[142:145], v[158:161], v[126:129]
	v_mfma_f32_16x16x32_bf16 v[122:125], v[150:153], v[158:161], v[122:125]
	v_mfma_f32_16x16x32_bf16 v[118:121], v[142:145], v[166:169], v[118:121]
	v_mfma_f32_16x16x32_bf16 v[110:113], v[150:153], v[166:169], v[110:113]
	v_mfma_f32_16x16x32_bf16 v[98:101], v[142:145], v[174:177], v[98:101]
	v_mfma_f32_16x16x32_bf16 v[90:93], v[150:153], v[174:177], v[90:93]
	v_mfma_f32_16x16x32_bf16 v[82:85], v[142:145], v[182:185], v[82:85]
	v_mfma_f32_16x16x32_bf16 v[74:77], v[150:153], v[182:185], v[74:77]
	v_mfma_f32_16x16x32_bf16 v[126:129], v[146:149], v[162:165], v[126:129]
	v_mfma_f32_16x16x32_bf16 v[122:125], v[154:157], v[162:165], v[122:125]
	v_mfma_f32_16x16x32_bf16 v[118:121], v[146:149], v[170:173], v[118:121]
	v_mfma_f32_16x16x32_bf16 v[110:113], v[154:157], v[170:173], v[110:113]
	v_mfma_f32_16x16x32_bf16 v[98:101], v[146:149], v[178:181], v[98:101]
	v_mfma_f32_16x16x32_bf16 v[90:93], v[154:157], v[178:181], v[90:93]
	v_mfma_f32_16x16x32_bf16 v[82:85], v[146:149], v[186:189], v[82:85]
	v_mfma_f32_16x16x32_bf16 v[74:77], v[154:157], v[186:189], v[74:77]
	s_barrier
	s_add_i32 s42, 0, 0x1c000
	s_add_i32 s43, s66, s24
	s_add_u32 s98, s40, s36
	s_addc_u32 s99, s41, s37
	s_mov_b32 m0, s43
	ds_read_b128 v[190:193], v249
	ds_read_b128 v[194:197], v249 offset:1024
	ds_read_b128 v[198:201], v249 offset:2048
	ds_read_b128 v[202:205], v249 offset:3072
	global_load_lds_dwordx4 v0, s[98:99]
	s_add_i32 m0, s43, 0x2000
	s_add_u32 s98, s40, s36
	s_addc_u32 s99, s41, s37
	global_load_lds_dwordx4 v134, s[98:99]
	s_barrier
; #define PG8_STAGE(bufoff, gbase, voff) do { _Pragma("unroll") for (int _i = 0; _i < 2; ++_i) \
;         __builtin_amdgcn_global_load_lds((const unsigned*)((const char*)(gbase) + (voff)[_i]), (LAS unsigned*)(lds + (bufoff) + ldsw + _i * 8192), 16, 0, 0); } while (0)
; #define PG8_LDA(dst, b, h) do { _Pragma("unroll") for (int m = 0; m < 4; ++m) _Pragma("unroll") for (int k = 0; k < 2; ++k) dst[m][k] = *(const LAS bf16x8*)(lds + PG8_SA(b, h) + aoff + m * 2048 + k * 1024); } while (0)
; #define PG8_MMA(ai, bj, At, Bt) do { __builtin_amdgcn_s_setprio(1); _Pragma("unroll") for (int m = 0; m < 4; ++m) _Pragma("unroll") for (int n = 0; n < 2; ++n) _Pragma("unroll") for (int k = 0; k < 2; ++k) \
;         acc[ai][bj][m][n] = __builtin_amdgcn_mfma_f32_16x16x32_bf16(Bt[n][k], At[m][k], acc[ai][bj][m][n], 0, 0, 0); __builtin_amdgcn_s_setprio(0); } while (0)
; #define PG8_WAIT_V(n) asm volatile("s_waitcnt vmcnt(" #n ")" ::: "memory")
; #define PG8_WAIT_L(n) asm volatile("s_waitcnt lgkmcnt(" #n ")" ::: "memory")
; #define PG8_BAR __builtin_amdgcn_s_barrier()
; #define PG8_SCHED __builtin_amdgcn_sched_barrier(0)
; template <class Epi, class Sched>
; __device__ __forceinline__ void gemm_phase(LAS unsigned char* lds, const Gemm g, const Sched& S, const Epi& E, const int tid) {
;     ...
;             PG8_LDA(At, 1, 1); PG8_STAGE(PG8_SA(1, 0), a3, voffA);
;             PG8_BAR; PG8_WAIT_L(0); PG8_MMA(1, 0, At, B0); PG8_BAR; PG8_SCHED;
;             PG8_STAGE(PG8_SB(1, 1), b3 + hstep, voffB);
;             PG8_WAIT_V(6); PG8_BAR; PG8_MMA(1, 1, At, B1); PG8_BAR;
;         }
;         if constexpr (!Epi::AFTER_DRAIN) { if constexpr (Epi::PRELOAD) E(acc, cur, wr, wc, fr, fq, lds); else E(acc, cur, wr, wc, fr, fq); S.done(cur); }
;         if (!has_next) break;
; #pragma unroll
;         for (int a = 0; a < 2; ++a)
; #pragma unroll
;             for (int b = 0; b < 2; ++b)
; #pragma unroll
;                 for (int m = 0; m < 4; ++m)
; #pragma unroll
;                     for (int n = 0; n < 2; ++n) acc[a][b][m][n] = (f32x4){0.f, 0.f, 0.f, 0.f};
;         cur = nxt; cA = nA; cB = nB; ++ui;
;     }
;     PG8_WAIT_V(0);
;     if (wr == 0) PG8_BAR;
;     PG8_BAR;
	s_waitcnt lgkmcnt(0)
	v_mfma_f32_16x16x32_bf16 v[114:117], v[190:193], v[158:161], v[114:117]
	v_mfma_f32_16x16x32_bf16 v[106:109], v[198:201], v[158:161], v[106:109]
	v_mfma_f32_16x16x32_bf16 v[102:105], v[190:193], v[166:169], v[102:105]
	v_mfma_f32_16x16x32_bf16 v[94:97], v[198:201], v[166:169], v[94:97]
	v_mfma_f32_16x16x32_bf16 v[86:89], v[190:193], v[174:177], v[86:89]
	v_mfma_f32_16x16x32_bf16 v[78:81], v[198:201], v[174:177], v[78:81]
	v_mfma_f32_16x16x32_bf16 v[70:73], v[190:193], v[182:185], v[70:73]
	v_mfma_f32_16x16x32_bf16 v[66:69], v[198:201], v[182:185], v[66:69]
	v_mfma_f32_16x16x32_bf16 v[114:117], v[194:197], v[162:165], v[114:117]
	v_mfma_f32_16x16x32_bf16 v[106:109], v[202:205], v[162:165], v[106:109]
	v_mfma_f32_16x16x32_bf16 v[102:105], v[194:197], v[170:173], v[102:105]
	v_mfma_f32_16x16x32_bf16 v[94:97], v[202:205], v[170:173], v[94:97]
	v_mfma_f32_16x16x32_bf16 v[86:89], v[194:197], v[178:181], v[86:89]
	v_mfma_f32_16x16x32_bf16 v[78:81], v[202:205], v[178:181], v[78:81]
	v_mfma_f32_16x16x32_bf16 v[70:73], v[194:197], v[186:189], v[70:73]
	v_mfma_f32_16x16x32_bf16 v[66:69], v[202:205], v[186:189], v[66:69]
	s_mov_b32 m0, s63
	v_lshl_add_u64 v[206:207], v[210:211], 0, s[36:37]
	s_barrier
	ds_read_b128 v[158:161], v141 offset:49152
	ds_read_b128 v[162:165], v141 offset:50176
	ds_read_b128 v[166:169], v141 offset:51200
	ds_read_b128 v[170:173], v141 offset:52224
	ds_read_b128 v[174:177], v141 offset:53248
	ds_read_b128 v[178:181], v141 offset:54272
	ds_read_b128 v[182:185], v141 offset:55296
	ds_read_b128 v[186:189], v141 offset:56320
	global_load_lds_dwordx4 v[206:207], off
	s_mov_b32 m0, s64
	v_lshl_add_u64 v[206:207], v[214:215], 0, s[36:37]
	global_load_lds_dwordx4 v[206:207], off
	s_barrier
	s_waitcnt lgkmcnt(0)
	v_mfma_f32_16x16x32_bf16 v[62:65], v[142:145], v[158:161], v[62:65]
	v_mfma_f32_16x16x32_bf16 v[58:61], v[150:153], v[158:161], v[58:61]
	v_mfma_f32_16x16x32_bf16 v[50:53], v[142:145], v[166:169], v[50:53]
	v_mfma_f32_16x16x32_bf16 v[42:45], v[150:153], v[166:169], v[42:45]
	v_mfma_f32_16x16x32_bf16 v[34:37], v[142:145], v[174:177], v[34:37]
	v_mfma_f32_16x16x32_bf16 v[26:29], v[150:153], v[174:177], v[26:29]
	v_mfma_f32_16x16x32_bf16 v[18:21], v[142:145], v[182:185], v[18:21]
	v_mfma_f32_16x16x32_bf16 v[10:13], v[150:153], v[182:185], v[10:13]
	v_mfma_f32_16x16x32_bf16 v[62:65], v[146:149], v[162:165], v[62:65]
	v_mfma_f32_16x16x32_bf16 v[58:61], v[154:157], v[162:165], v[58:61]
	v_mfma_f32_16x16x32_bf16 v[50:53], v[146:149], v[170:173], v[50:53]
	v_mfma_f32_16x16x32_bf16 v[42:45], v[154:157], v[170:173], v[42:45]
	v_mfma_f32_16x16x32_bf16 v[34:37], v[146:149], v[178:181], v[34:37]
	v_mfma_f32_16x16x32_bf16 v[26:29], v[154:157], v[178:181], v[26:29]
	v_mfma_f32_16x16x32_bf16 v[18:21], v[146:149], v[186:189], v[18:21]
	v_mfma_f32_16x16x32_bf16 v[10:13], v[154:157], v[186:189], v[10:13]
	s_barrier
	s_add_u32 s40, s40, 0x160080
	s_addc_u32 s41, s41, 0
	s_add_i32 s42, s42, s24
	s_mov_b32 m0, s42
	s_nop 0
	global_load_lds_dwordx4 v0, s[40:41]
	s_add_i32 m0, s42, 0x2000
	s_nop 0
	global_load_lds_dwordx4 v134, s[40:41]
	s_waitcnt vmcnt(6)
	s_barrier
	v_mfma_f32_16x16x32_bf16 v[54:57], v[190:193], v[158:161], v[54:57]
	v_mfma_f32_16x16x32_bf16 v[46:49], v[198:201], v[158:161], v[46:49]
	v_mfma_f32_16x16x32_bf16 v[38:41], v[190:193], v[166:169], v[38:41]
	v_mfma_f32_16x16x32_bf16 v[30:33], v[198:201], v[166:169], v[30:33]
	v_mfma_f32_16x16x32_bf16 v[22:25], v[190:193], v[174:177], v[22:25]
	v_mfma_f32_16x16x32_bf16 v[14:17], v[198:201], v[174:177], v[14:17]
	v_mfma_f32_16x16x32_bf16 v[6:9], v[190:193], v[182:185], v[6:9]
	v_mfma_f32_16x16x32_bf16 v[2:5], v[198:201], v[182:185], v[2:5]
	v_mfma_f32_16x16x32_bf16 v[54:57], v[194:197], v[162:165], v[54:57]
	v_mfma_f32_16x16x32_bf16 v[46:49], v[202:205], v[162:165], v[46:49]
	v_mfma_f32_16x16x32_bf16 v[38:41], v[194:197], v[170:173], v[38:41]
	v_mfma_f32_16x16x32_bf16 v[30:33], v[202:205], v[170:173], v[30:33]
	v_mfma_f32_16x16x32_bf16 v[22:25], v[194:197], v[178:181], v[22:25]
	v_mfma_f32_16x16x32_bf16 v[14:17], v[202:205], v[178:181], v[14:17]
	v_mfma_f32_16x16x32_bf16 v[6:9], v[194:197], v[186:189], v[6:9]
	v_mfma_f32_16x16x32_bf16 v[2:5], v[202:205], v[186:189], v[2:5]
	s_add_i32 s65, s65, 2
	s_add_u32 s38, s38, 0x100
	s_addc_u32 s39, s39, 0
	s_cmpk_lt_u32 s65, 0x56
	s_barrier
	s_cbranch_scc1 .LBB0_1573
	s_waitcnt vmcnt(0)
	s_cmpk_gt_u32 s44, 0xff
	s_cbranch_scc1 .LBB0_1576
	s_barrier

; #define PG8_STAGE(bufoff, gbase, voff) do { _Pragma("unroll") for (int _i = 0; _i < 2; ++_i) \
;         __builtin_amdgcn_global_load_lds((const unsigned*)((const char*)(gbase) + (voff)[_i]), (LAS unsigned*)(lds + (bufoff) + ldsw + _i * 8192), 16, 0, 0); } while (0)
; #define PG8_WAIT_V(n) asm volatile("s_waitcnt vmcnt(" #n ")" ::: "memory")
; #define PG8_BAR __builtin_amdgcn_s_barrier()
; template <class Epi, class Sched>
; __device__ __forceinline__ void gemm_phase(LAS unsigned char* lds, const Gemm g, const Sched& S, const Epi& E, const int tid) {
;     ...
;     for (int i = 0; i < 2; ++i) { int R, C; stage_rc(tid * 16 + i * 8192, R, C); const int Rb = Epi::PERM ? ((R & ~31) + perm32(R & 31)) : R; const int Ra = Epi::ROWP ? ((R & ~63) + 4 * (R & 15) + ((R >> 4) & 3)) : R;
;         voffA[i] = (unsigned)(Ra * K + C) * 2u; voffB[i] = (unsigned)(Rb * K + C) * 2u; }
;     const size_t kstep = (size_t)(BK * 2);
;     const size_t hstep = (size_t)HALF * K * 2;
;     const size_t tstep = 2 * hstep;
;     const unsigned ldsw = (unsigned)wid * 1024u;
;     const int aoff = lds_byte(wr * 64 + fr, fq * 8), boff = lds_byte(wc * 32 + fr, fq * 8);
;     ...
;     f32x4 acc[2][2][4][2];
; #pragma unroll
;     for (int a = 0; a < 2; ++a)
; #pragma unroll
;         for (int b = 0; b < 2; ++b)
; #pragma unroll
;             for (int m = 0; m < 4; ++m)
; #pragma unroll
;                 for (int n = 0; n < 2; ++n) acc[a][b][m][n] = (f32x4){0.f, 0.f, 0.f, 0.f};
;     bf16x8 At[4][2], B0[2][2], B1[2][2];
;     const char* cA = (const char*)g.A + (size_t)cur.pm * tstep + (size_t)cur.ks * cur.nt * kstep; const char* cB = (const char*)g.Bt + (size_t)cur.pn * tstep + (size_t)cur.ks * cur.nt * kstep;
;     S.a_ready(cur);
;     PG8_STAGE(PG8_SB(0, 0), cB, voffB); PG8_STAGE(PG8_SA(0, 0), cA, voffA); PG8_STAGE(PG8_SB(0, 1), cB + hstep, voffB); PG8_STAGE(PG8_SA(0, 1), cA + hstep, voffA);
;     if (wr == 1) PG8_BAR;
;     PG8_WAIT_V(4); PG8_BAR;
;     PG8_STAGE(PG8_SB(1, 0), cB + kstep, voffB); PG8_STAGE(PG8_SA(1, 0), cA + kstep, voffA); PG8_STAGE(PG8_SB(1, 1), cB + hstep + kstep, voffB);
;     PG8_WAIT_V(6); PG8_BAR;
.LBB0_1626:
	v_and_b32_e32 v181, 15, v220
	v_and_b32_e32 v18, 48, v220
	v_lshlrev_b32_e32 v19, 2, v220
	s_and_b32 s52, s44, 3
	s_lshl_b32 s41, s45, 13
	v_lshl_or_b32 v18, v181, 6, v18
	v_and_b32_e32 v19, 32, v19
	s_add_i32 m0, s25, 0x18000
	v_lshl_add_u64 v[8:9], v[8:9], 0, s[36:37]
	s_lshl_b32 s28, s45, 6
	v_bitop3_b32 v20, v18, s41, v19 bitop3:0xde
	s_lshl_b32 s41, s52, 12
	s_waitcnt vmcnt(4)
	s_barrier
	global_load_lds_dwordx4 v[8:9], off
	v_lshl_add_u64 v[6:7], v[6:7], 0, s[36:37]
	s_add_i32 m0, s25, 0x1a000
	s_add_i32 s55, s25, 0x8000
	s_add_i32 s58, s25, 0xa000
	global_load_lds_dwordx4 v[6:7], off
	v_lshl_add_u64 v[4:5], v[4:5], 0, s[36:37]
	s_mov_b32 m0, s55
	s_add_u32 s60, s0, 0x160080
	global_load_lds_dwordx4 v[4:5], off
	v_lshl_add_u64 v[2:3], v[2:3], 0, s[36:37]
	s_mov_b32 m0, s58
	s_addc_u32 s61, s1, 0
	global_load_lds_dwordx4 v[2:3], off
	s_add_i32 m0, s25, 0x1c000
	v_lshl_add_u64 v[2:3], s[60:61], 0, v[0:1]
	global_load_lds_dwordx4 v[2:3], off
	v_lshl_add_u64 v[2:3], s[60:61], 0, v[134:135]
	s_add_i32 m0, s25, 0x1e000
	s_add_i32 s38, s38, s51
	global_load_lds_dwordx4 v[2:3], off
	s_sub_i32 s38, s38, s40
	s_mul_i32 s39, s39, 28
	s_movk_i32 s59, 0x1600
	s_sub_i32 s38, s38, s39
	v_lshrrev_b32_e32 v3, 1, v10
	v_mul_lo_u32 v2, v12, s59
	s_mov_b32 s51, 0x16000
	v_bitop3_b32 v140, s41, v18, v19 bitop3:0xf6
	s_mul_hi_i32 s40, s38, 0x2c0000
	s_mul_i32 s41, s38, 0x2c0000
	v_mad_u64_u32 v[2:3], s[38:39], v3, s51, v[2:3]
	v_or_b32_e32 v2, v2, v11
	s_add_u32 s22, s22, s41
	v_add_lshl_u32 v2, v2, v13, 1
	v_mov_b32_e32 v3, v1
	s_addc_u32 s23, s23, s40
	v_lshl_add_u64 v[136:137], s[22:23], 0, v[2:3]
	v_lshrrev_b32_e32 v3, 1, v14
	v_mul_lo_u32 v2, v16, s59
	v_mad_u64_u32 v[2:3], s[38:39], v3, s51, v[2:3]
	s_waitcnt vmcnt(6)
	v_or_b32_e32 v2, v2, v15
	v_add_lshl_u32 v2, v2, v17, 1
	v_mov_b32_e32 v3, v1
	v_mov_b32_e32 v98, 0
	v_or_b32_e32 v180, s28, v181
	v_lshl_add_u64 v[138:139], s[22:23], 0, v[2:3]
	s_mov_b32 s51, -2
	s_mov_b64 s[22:23], 0x1e124080
	v_add_u32_e32 v141, 0, v20
	v_mov_b32_e32 v99, v98
	v_mov_b32_e32 v100, v98
	v_mov_b32_e32 v101, v98
	v_mov_b32_e32 v110, v98
	v_mov_b32_e32 v111, v98
	v_mov_b32_e32 v112, v98
	v_mov_b32_e32 v113, v98
	v_mov_b32_e32 v118, v98
	v_mov_b32_e32 v119, v98
	v_mov_b32_e32 v120, v98
	v_mov_b32_e32 v121, v98
	v_mov_b32_e32 v114, v98
	v_mov_b32_e32 v115, v98
	v_mov_b32_e32 v116, v98
	v_mov_b32_e32 v117, v98
	v_mov_b32_e32 v94, v98
	v_mov_b32_e32 v95, v98
	v_mov_b32_e32 v96, v98
	v_mov_b32_e32 v97, v98
	v_mov_b32_e32 v90, v98
	v_mov_b32_e32 v91, v98
	v_mov_b32_e32 v92, v98
	v_mov_b32_e32 v93, v98
	v_mov_b32_e32 v78, v98
	v_mov_b32_e32 v79, v98
	v_mov_b32_e32 v80, v98
	v_mov_b32_e32 v81, v98
	v_mov_b32_e32 v74, v98
	v_mov_b32_e32 v75, v98
	v_mov_b32_e32 v76, v98
	v_mov_b32_e32 v77, v98
	v_mov_b32_e32 v126, v98
	v_mov_b32_e32 v127, v98
	v_mov_b32_e32 v128, v98
	v_mov_b32_e32 v129, v98
	v_mov_b32_e32 v122, v98
	v_mov_b32_e32 v123, v98
	v_mov_b32_e32 v124, v98
	v_mov_b32_e32 v125, v98
	v_mov_b32_e32 v106, v98
	v_mov_b32_e32 v107, v98
	v_mov_b32_e32 v108, v98
	v_mov_b32_e32 v109, v98
	v_mov_b32_e32 v102, v98
	v_mov_b32_e32 v103, v98
	v_mov_b32_e32 v104, v98
	v_mov_b32_e32 v105, v98
	v_mov_b32_e32 v86, v98
	v_mov_b32_e32 v87, v98
	v_mov_b32_e32 v88, v98
	v_mov_b32_e32 v89, v98
	v_mov_b32_e32 v82, v98
	v_mov_b32_e32 v83, v98
	v_mov_b32_e32 v84, v98
	v_mov_b32_e32 v85, v98
	v_mov_b32_e32 v70, v98
	v_mov_b32_e32 v71, v98
	v_mov_b32_e32 v72, v98
	v_mov_b32_e32 v73, v98
	v_mov_b32_e32 v66, v98
	v_mov_b32_e32 v67, v98
	v_mov_b32_e32 v68, v98
	v_mov_b32_e32 v69, v98
	v_mov_b32_e32 v62, v98
	v_mov_b32_e32 v63, v98
	v_mov_b32_e32 v64, v98
	v_mov_b32_e32 v65, v98
	v_mov_b32_e32 v58, v98
	v_mov_b32_e32 v59, v98
	v_mov_b32_e32 v60, v98
	v_mov_b32_e32 v61, v98
	v_mov_b32_e32 v46, v98
	v_mov_b32_e32 v47, v98
	v_mov_b32_e32 v48, v98
	v_mov_b32_e32 v49, v98
	v_mov_b32_e32 v42, v98
	v_mov_b32_e32 v43, v98
	v_mov_b32_e32 v44, v98
	v_mov_b32_e32 v45, v98
	v_mov_b32_e32 v30, v98
	v_mov_b32_e32 v31, v98
	v_mov_b32_e32 v32, v98
	v_mov_b32_e32 v33, v98
	v_mov_b32_e32 v26, v98
	v_mov_b32_e32 v27, v98
	v_mov_b32_e32 v28, v98
	v_mov_b32_e32 v29, v98
	v_mov_b32_e32 v10, v98
	v_mov_b32_e32 v11, v98
	v_mov_b32_e32 v12, v98
	v_mov_b32_e32 v13, v98
	v_mov_b32_e32 v2, v98
	v_mov_b32_e32 v3, v98
	v_mov_b32_e32 v4, v98
	v_mov_b32_e32 v5, v98
	v_mov_b32_e32 v54, v98
	v_mov_b32_e32 v55, v98
	v_mov_b32_e32 v56, v98
	v_mov_b32_e32 v57, v98
	v_mov_b32_e32 v50, v98
	v_mov_b32_e32 v51, v98
	v_mov_b32_e32 v52, v98
	v_mov_b32_e32 v53, v98
	v_mov_b32_e32 v38, v98
	v_mov_b32_e32 v39, v98
	v_mov_b32_e32 v40, v98
	v_mov_b32_e32 v41, v98
	v_mov_b32_e32 v34, v98
	v_mov_b32_e32 v35, v98
	v_mov_b32_e32 v36, v98
	v_mov_b32_e32 v37, v98
	v_mov_b32_e32 v22, v98
	v_mov_b32_e32 v23, v98
	v_mov_b32_e32 v24, v98
	v_mov_b32_e32 v25, v98
	v_mov_b32_e32 v18, v98
	v_mov_b32_e32 v19, v98
	v_mov_b32_e32 v20, v98
	v_mov_b32_e32 v21, v98
	v_mov_b32_e32 v14, v98
	v_mov_b32_e32 v15, v98
	v_mov_b32_e32 v16, v98
	v_mov_b32_e32 v17, v98
	v_mov_b32_e32 v6, v98
	v_mov_b32_e32 v7, v98
	v_mov_b32_e32 v8, v98
	v_mov_b32_e32 v9, v98
	s_barrier
	v_add_u32_e32 v252, 0x10000, v140
	v_add_u32_e32 v251, 0x14000, v140
	v_add_u32_e32 v250, 0x18000, v140
	v_add_u32_e32 v249, 0x1c000, v140
; #define PG8_STAGE(bufoff, gbase, voff) do { _Pragma("unroll") for (int _i = 0; _i < 2; ++_i) \
;         __builtin_amdgcn_global_load_lds((const unsigned*)((const char*)(gbase) + (voff)[_i]), (LAS unsigned*)(lds + (bufoff) + ldsw + _i * 8192), 16, 0, 0); } while (0)
; #define PG8_LDA(dst, b, h) do { _Pragma("unroll") for (int m = 0; m < 4; ++m) _Pragma("unroll") for (int k = 0; k < 2; ++k) dst[m][k] = *(const LAS bf16x8*)(lds + PG8_SA(b, h) + aoff + m * 2048 + k * 1024); } while (0)
; #define PG8_LDB(dst, b, h) do { _Pragma("unroll") for (int n = 0; n < 2; ++n) _Pragma("unroll") for (int k = 0; k < 2; ++k) dst[n][k] = *(const LAS bf16x8*)(lds + PG8_SB(b, h) + boff + n * 2048 + k * 1024); } while (0)
; #define PG8_MMA(ai, bj, At, Bt) do { __builtin_amdgcn_s_setprio(1); _Pragma("unroll") for (int m = 0; m < 4; ++m) _Pragma("unroll") for (int n = 0; n < 2; ++n) _Pragma("unroll") for (int k = 0; k < 2; ++k) \
;         acc[ai][bj][m][n] = __builtin_amdgcn_mfma_f32_16x16x32_bf16(Bt[n][k], At[m][k], acc[ai][bj][m][n], 0, 0, 0); __builtin_amdgcn_s_setprio(0); } while (0)
; #define PG8_WAIT_V(n) asm volatile("s_waitcnt vmcnt(" #n ")" ::: "memory")
; #define PG8_WAIT_L(n) asm volatile("s_waitcnt lgkmcnt(" #n ")" ::: "memory")
; #define PG8_BAR __builtin_amdgcn_s_barrier()
; #define PG8_SCHED __builtin_amdgcn_sched_barrier(0)
; template <class Epi, class Sched>
; __device__ __forceinline__ void gemm_phase(LAS unsigned char* lds, const Gemm g, const Sched& S, const Epi& E, const int tid) {
;     ...
;             PG8_LDB(B0, 0, 0); PG8_SCHED; PG8_LDA(At, 0, 0); PG8_STAGE(PG8_SA(1, 1), a1 + hstep, voffA);
;             PG8_WAIT_L(8); PG8_BAR; PG8_WAIT_L(0); PG8_MMA(0, 0, At, B0); PG8_BAR; PG8_SCHED;
;             PG8_LDB(B1, 0, 1); PG8_STAGE(PG8_SB(0, 0), b2, voffB);
;             PG8_BAR; PG8_WAIT_L(0); PG8_MMA(0, 1, At, B1); PG8_BAR;
;             PG8_LDA(At, 0, 1); PG8_STAGE(PG8_SA(0, 0), a2, voffA);
;             PG8_BAR; PG8_WAIT_L(0); PG8_MMA(1, 0, At, B0); PG8_BAR; PG8_SCHED;
;             PG8_STAGE(PG8_SB(0, 1), b2 + hstep, voffB);
;             PG8_WAIT_V(6); PG8_BAR; PG8_MMA(1, 1, At, B1); PG8_BAR;
.LBB0_1627:
	s_add_u32 s38, s22, 0xe1edc080
	s_addc_u32 s39, s23, -1
	s_cmpk_lg_i32 s51, 0x54
	s_cselect_b32 s38, s38, 0
	s_cselect_b32 s39, s39, 0
	s_add_u32 s40, s4, s38
	s_addc_u32 s41, s5, s39
	s_add_i32 s59, 0, 0x10000
	ds_read_b128 v[142:145], v252
	ds_read_b128 v[146:149], v252 offset:1024
	ds_read_b128 v[150:153], v252 offset:2048
	ds_read_b128 v[154:157], v252 offset:3072
	s_add_u32 s38, s0, s38
	s_addc_u32 s39, s1, s39
	v_lshl_add_u64 v[178:179], v[136:137], 0, s[22:23]
	s_add_i32 m0, s25, 0xc000
	ds_read_b128 v[158:161], v141
	ds_read_b128 v[162:165], v141 offset:1024
	ds_read_b128 v[166:169], v141 offset:2048
	ds_read_b128 v[170:173], v141 offset:3072
	ds_read_b128 v[174:177], v141 offset:4096
	ds_read_b128 v[182:185], v141 offset:5120
	ds_read_b128 v[186:189], v141 offset:6144
	ds_read_b128 v[190:193], v141 offset:7168
	global_load_lds_dwordx4 v[178:179], off
	s_add_i32 m0, s25, 0xe000
	v_lshl_add_u64 v[178:179], v[138:139], 0, s[22:23]
	global_load_lds_dwordx4 v[178:179], off
	s_waitcnt lgkmcnt(8)
	s_barrier
	s_waitcnt lgkmcnt(0)
	v_mfma_f32_16x16x32_bf16 v[6:9], v[142:145], v[158:161], v[6:9]
	v_mfma_f32_16x16x32_bf16 v[14:17], v[150:153], v[158:161], v[14:17]
	v_mfma_f32_16x16x32_bf16 v[18:21], v[142:145], v[166:169], v[18:21]
	v_mfma_f32_16x16x32_bf16 v[22:25], v[150:153], v[166:169], v[22:25]
	v_mfma_f32_16x16x32_bf16 v[34:37], v[142:145], v[174:177], v[34:37]
	v_mfma_f32_16x16x32_bf16 v[38:41], v[150:153], v[174:177], v[38:41]
	v_mfma_f32_16x16x32_bf16 v[50:53], v[142:145], v[186:189], v[50:53]
	v_mfma_f32_16x16x32_bf16 v[54:57], v[150:153], v[186:189], v[54:57]
	v_mfma_f32_16x16x32_bf16 v[6:9], v[146:149], v[162:165], v[6:9]
	v_mfma_f32_16x16x32_bf16 v[14:17], v[154:157], v[162:165], v[14:17]
	v_mfma_f32_16x16x32_bf16 v[18:21], v[146:149], v[170:173], v[18:21]
	v_mfma_f32_16x16x32_bf16 v[22:25], v[154:157], v[170:173], v[22:25]
	v_mfma_f32_16x16x32_bf16 v[34:37], v[146:149], v[182:185], v[34:37]
	v_mfma_f32_16x16x32_bf16 v[38:41], v[154:157], v[182:185], v[38:41]
	v_mfma_f32_16x16x32_bf16 v[50:53], v[146:149], v[190:193], v[50:53]
	v_mfma_f32_16x16x32_bf16 v[54:57], v[154:157], v[190:193], v[54:57]
	s_barrier
	s_add_i32 s62, 0, 0x14000
	s_add_i32 s59, s59, s24
	ds_read_b128 v[194:197], v251
	ds_read_b128 v[198:201], v251 offset:1024
	ds_read_b128 v[202:205], v251 offset:2048
	ds_read_b128 v[206:209], v251 offset:3072
	s_mov_b32 m0, s59
	global_load_lds_dwordx4 v0, s[38:39]
	s_add_i32 m0, s59, 0x2000
	s_nop 0
	global_load_lds_dwordx4 v134, s[38:39]
	s_barrier
	s_waitcnt lgkmcnt(0)
	v_mfma_f32_16x16x32_bf16 v[2:5], v[194:197], v[158:161], v[2:5]
	v_mfma_f32_16x16x32_bf16 v[10:13], v[202:205], v[158:161], v[10:13]
	v_mfma_f32_16x16x32_bf16 v[26:29], v[194:197], v[166:169], v[26:29]
	v_mfma_f32_16x16x32_bf16 v[30:33], v[202:205], v[166:169], v[30:33]
	v_mfma_f32_16x16x32_bf16 v[42:45], v[194:197], v[174:177], v[42:45]
	v_mfma_f32_16x16x32_bf16 v[46:49], v[202:205], v[174:177], v[46:49]
	v_mfma_f32_16x16x32_bf16 v[58:61], v[194:197], v[186:189], v[58:61]
	v_mfma_f32_16x16x32_bf16 v[62:65], v[202:205], v[186:189], v[62:65]
	v_mfma_f32_16x16x32_bf16 v[2:5], v[198:201], v[162:165], v[2:5]
	v_mfma_f32_16x16x32_bf16 v[10:13], v[206:209], v[162:165], v[10:13]
	v_mfma_f32_16x16x32_bf16 v[26:29], v[198:201], v[170:173], v[26:29]
	v_mfma_f32_16x16x32_bf16 v[30:33], v[206:209], v[170:173], v[30:33]
	v_mfma_f32_16x16x32_bf16 v[42:45], v[198:201], v[182:185], v[42:45]
	v_mfma_f32_16x16x32_bf16 v[46:49], v[206:209], v[182:185], v[46:49]
	v_mfma_f32_16x16x32_bf16 v[58:61], v[198:201], v[190:193], v[58:61]
	v_mfma_f32_16x16x32_bf16 v[62:65], v[206:209], v[190:193], v[62:65]
	s_mov_b32 m0, s25
	v_lshl_add_u64 v[214:215], s[40:41], 0, v[130:131]
	s_barrier
	ds_read_b128 v[158:161], v141 offset:16384
	ds_read_b128 v[162:165], v141 offset:17408
	ds_read_b128 v[166:169], v141 offset:18432
	ds_read_b128 v[170:173], v141 offset:19456
	ds_read_b128 v[174:177], v141 offset:20480
	ds_read_b128 v[182:185], v141 offset:21504
	ds_read_b128 v[186:189], v141 offset:22528
	ds_read_b128 v[190:193], v141 offset:23552
	global_load_lds_dwordx4 v[214:215], off
	s_mov_b32 m0, s29
	v_lshl_add_u64 v[216:217], s[40:41], 0, v[132:133]
	global_load_lds_dwordx4 v[216:217], off
	s_barrier
	s_waitcnt lgkmcnt(0)
	v_mfma_f32_16x16x32_bf16 v[66:69], v[142:145], v[158:161], v[66:69]
	v_mfma_f32_16x16x32_bf16 v[70:73], v[150:153], v[158:161], v[70:73]
	v_mfma_f32_16x16x32_bf16 v[82:85], v[142:145], v[166:169], v[82:85]
	v_mfma_f32_16x16x32_bf16 v[86:89], v[150:153], v[166:169], v[86:89]
	v_mfma_f32_16x16x32_bf16 v[102:105], v[142:145], v[174:177], v[102:105]
	v_mfma_f32_16x16x32_bf16 v[106:109], v[150:153], v[174:177], v[106:109]
	v_mfma_f32_16x16x32_bf16 v[122:125], v[142:145], v[186:189], v[122:125]
	v_mfma_f32_16x16x32_bf16 v[126:129], v[150:153], v[186:189], v[126:129]
	v_mfma_f32_16x16x32_bf16 v[66:69], v[146:149], v[162:165], v[66:69]
	v_mfma_f32_16x16x32_bf16 v[70:73], v[154:157], v[162:165], v[70:73]
	v_mfma_f32_16x16x32_bf16 v[82:85], v[146:149], v[170:173], v[82:85]
	v_mfma_f32_16x16x32_bf16 v[86:89], v[154:157], v[170:173], v[86:89]
	v_mfma_f32_16x16x32_bf16 v[102:105], v[146:149], v[182:185], v[102:105]
	v_mfma_f32_16x16x32_bf16 v[106:109], v[154:157], v[182:185], v[106:109]
	v_mfma_f32_16x16x32_bf16 v[122:125], v[146:149], v[190:193], v[122:125]
	v_mfma_f32_16x16x32_bf16 v[126:129], v[154:157], v[190:193], v[126:129]
	s_barrier
	s_add_u32 s60, s38, 0x160000
	s_addc_u32 s61, s39, 0
	s_add_i32 s59, s62, s24
	s_mov_b32 m0, s59
	s_nop 0
	global_load_lds_dwordx4 v0, s[60:61]
	s_add_i32 m0, s59, 0x2000
	s_nop 0
	global_load_lds_dwordx4 v134, s[60:61]
	s_waitcnt vmcnt(6)
	s_barrier
; #define PG8_STAGE(bufoff, gbase, voff) do { _Pragma("unroll") for (int _i = 0; _i < 2; ++_i) \
;         __builtin_amdgcn_global_load_lds((const unsigned*)((const char*)(gbase) + (voff)[_i]), (LAS unsigned*)(lds + (bufoff) + ldsw + _i * 8192), 16, 0, 0); } while (0)
; #define PG8_LDA(dst, b, h) do { _Pragma("unroll") for (int m = 0; m < 4; ++m) _Pragma("unroll") for (int k = 0; k < 2; ++k) dst[m][k] = *(const LAS bf16x8*)(lds + PG8_SA(b, h) + aoff + m * 2048 + k * 1024); } while (0)
; #define PG8_LDB(dst, b, h) do { _Pragma("unroll") for (int n = 0; n < 2; ++n) _Pragma("unroll") for (int k = 0; k < 2; ++k) dst[n][k] = *(const LAS bf16x8*)(lds + PG8_SB(b, h) + boff + n * 2048 + k * 1024); } while (0)
; #define PG8_MMA(ai, bj, At, Bt) do { __builtin_amdgcn_s_setprio(1); _Pragma("unroll") for (int m = 0; m < 4; ++m) _Pragma("unroll") for (int n = 0; n < 2; ++n) _Pragma("unroll") for (int k = 0; k < 2; ++k) \
;         acc[ai][bj][m][n] = __builtin_amdgcn_mfma_f32_16x16x32_bf16(Bt[n][k], At[m][k], acc[ai][bj][m][n], 0, 0, 0); __builtin_amdgcn_s_setprio(0); } while (0)
; #define PG8_WAIT_V(n) asm volatile("s_waitcnt vmcnt(" #n ")" ::: "memory")
; #define PG8_WAIT_L(n) asm volatile("s_waitcnt lgkmcnt(" #n ")" ::: "memory")
; #define PG8_BAR __builtin_amdgcn_s_barrier()
; #define PG8_SCHED __builtin_amdgcn_sched_barrier(0)
; template <class Epi, class Sched>
; __device__ __forceinline__ void gemm_phase(LAS unsigned char* lds, const Gemm g, const Sched& S, const Epi& E, const int tid) {
;     ...
;             PG8_WAIT_V(6); PG8_BAR; PG8_MMA(1, 1, At, B1); PG8_BAR;
;             PG8_LDB(B0, 1, 0); PG8_SCHED; PG8_LDA(At, 1, 0); PG8_STAGE(PG8_SA(0, 1), a2 + hstep, voffA);
;             PG8_WAIT_L(8); PG8_BAR; PG8_WAIT_L(0); PG8_MMA(0, 0, At, B0); PG8_BAR; PG8_SCHED;
;             PG8_LDB(B1, 1, 1); PG8_STAGE(PG8_SB(1, 0), b3, voffB);
;             PG8_BAR; PG8_WAIT_L(0); PG8_MMA(0, 1, At, B1); PG8_BAR;
;             PG8_LDA(At, 1, 1); PG8_STAGE(PG8_SA(1, 0), a3, voffA);
	v_mfma_f32_16x16x32_bf16 v[74:77], v[194:197], v[158:161], v[74:77]
	v_mfma_f32_16x16x32_bf16 v[78:81], v[202:205], v[158:161], v[78:81]
	v_mfma_f32_16x16x32_bf16 v[90:93], v[194:197], v[166:169], v[90:93]
	v_mfma_f32_16x16x32_bf16 v[94:97], v[202:205], v[166:169], v[94:97]
	v_mfma_f32_16x16x32_bf16 v[114:117], v[194:197], v[174:177], v[114:117]
	v_mfma_f32_16x16x32_bf16 v[118:121], v[202:205], v[174:177], v[118:121]
	v_mfma_f32_16x16x32_bf16 v[110:113], v[194:197], v[186:189], v[110:113]
	v_mfma_f32_16x16x32_bf16 v[98:101], v[202:205], v[186:189], v[98:101]
	v_mfma_f32_16x16x32_bf16 v[74:77], v[198:201], v[162:165], v[74:77]
	v_mfma_f32_16x16x32_bf16 v[78:81], v[206:209], v[162:165], v[78:81]
	v_mfma_f32_16x16x32_bf16 v[90:93], v[198:201], v[170:173], v[90:93]
	v_mfma_f32_16x16x32_bf16 v[94:97], v[206:209], v[170:173], v[94:97]
	v_mfma_f32_16x16x32_bf16 v[114:117], v[198:201], v[182:185], v[114:117]
	v_mfma_f32_16x16x32_bf16 v[118:121], v[206:209], v[182:185], v[118:121]
	v_mfma_f32_16x16x32_bf16 v[110:113], v[198:201], v[190:193], v[110:113]
	v_mfma_f32_16x16x32_bf16 v[98:101], v[206:209], v[190:193], v[98:101]
	s_add_i32 s59, 0, 0x18000
	s_barrier
	ds_read_b128 v[142:145], v250
	ds_read_b128 v[146:149], v250 offset:1024
	ds_read_b128 v[150:153], v250 offset:2048
	ds_read_b128 v[154:157], v250 offset:3072
	s_add_u32 s40, s40, 0x160000
	s_addc_u32 s41, s41, 0
	s_mov_b32 m0, s53
	ds_read_b128 v[158:161], v141 offset:32768
	ds_read_b128 v[162:165], v141 offset:33792
	ds_read_b128 v[166:169], v141 offset:34816
	ds_read_b128 v[170:173], v141 offset:35840
	ds_read_b128 v[174:177], v141 offset:36864
	ds_read_b128 v[182:185], v141 offset:37888
	ds_read_b128 v[186:189], v141 offset:38912
	global_load_lds_dwordx4 v130, s[40:41]
	s_mov_b32 m0, s54
	ds_read_b128 v[190:193], v141 offset:39936
	global_load_lds_dwordx4 v132, s[40:41]
	s_waitcnt lgkmcnt(8)
	s_barrier
	s_waitcnt lgkmcnt(0)
	v_mfma_f32_16x16x32_bf16 v[6:9], v[142:145], v[158:161], v[6:9]
	v_mfma_f32_16x16x32_bf16 v[14:17], v[150:153], v[158:161], v[14:17]
	v_mfma_f32_16x16x32_bf16 v[18:21], v[142:145], v[166:169], v[18:21]
	v_mfma_f32_16x16x32_bf16 v[22:25], v[150:153], v[166:169], v[22:25]
	v_mfma_f32_16x16x32_bf16 v[34:37], v[142:145], v[174:177], v[34:37]
	v_mfma_f32_16x16x32_bf16 v[38:41], v[150:153], v[174:177], v[38:41]
	v_mfma_f32_16x16x32_bf16 v[50:53], v[142:145], v[186:189], v[50:53]
	v_mfma_f32_16x16x32_bf16 v[54:57], v[150:153], v[186:189], v[54:57]
	v_mfma_f32_16x16x32_bf16 v[6:9], v[146:149], v[162:165], v[6:9]
	v_mfma_f32_16x16x32_bf16 v[14:17], v[154:157], v[162:165], v[14:17]
	v_mfma_f32_16x16x32_bf16 v[18:21], v[146:149], v[170:173], v[18:21]
	v_mfma_f32_16x16x32_bf16 v[22:25], v[154:157], v[170:173], v[22:25]
	v_mfma_f32_16x16x32_bf16 v[34:37], v[146:149], v[182:185], v[34:37]
	v_mfma_f32_16x16x32_bf16 v[38:41], v[154:157], v[182:185], v[38:41]
	v_mfma_f32_16x16x32_bf16 v[50:53], v[146:149], v[190:193], v[50:53]
	v_mfma_f32_16x16x32_bf16 v[54:57], v[154:157], v[190:193], v[54:57]
	s_barrier
	s_add_i32 s40, 0, 0x1c000
	s_add_i32 s41, s59, s24
	s_add_u32 s98, s38, s36
	s_addc_u32 s99, s39, s37
	s_mov_b32 m0, s41
	ds_read_b128 v[194:197], v249
	ds_read_b128 v[198:201], v249 offset:1024
	ds_read_b128 v[202:205], v249 offset:2048
	ds_read_b128 v[206:209], v249 offset:3072
	global_load_lds_dwordx4 v0, s[98:99]
	s_add_i32 m0, s41, 0x2000
	s_add_u32 s98, s38, s36
	s_addc_u32 s99, s39, s37
	global_load_lds_dwordx4 v134, s[98:99]
	s_barrier
; #define PG8_STAGE(bufoff, gbase, voff) do { _Pragma("unroll") for (int _i = 0; _i < 2; ++_i) \
;         __builtin_amdgcn_global_load_lds((const unsigned*)((const char*)(gbase) + (voff)[_i]), (LAS unsigned*)(lds + (bufoff) + ldsw + _i * 8192), 16, 0, 0); } while (0)
; #define PG8_LDA(dst, b, h) do { _Pragma("unroll") for (int m = 0; m < 4; ++m) _Pragma("unroll") for (int k = 0; k < 2; ++k) dst[m][k] = *(const LAS bf16x8*)(lds + PG8_SA(b, h) + aoff + m * 2048 + k * 1024); } while (0)
; #define PG8_MMA(ai, bj, At, Bt) do { __builtin_amdgcn_s_setprio(1); _Pragma("unroll") for (int m = 0; m < 4; ++m) _Pragma("unroll") for (int n = 0; n < 2; ++n) _Pragma("unroll") for (int k = 0; k < 2; ++k) \
;         acc[ai][bj][m][n] = __builtin_amdgcn_mfma_f32_16x16x32_bf16(Bt[n][k], At[m][k], acc[ai][bj][m][n], 0, 0, 0); __builtin_amdgcn_s_setprio(0); } while (0)
; #define PG8_WAIT_V(n) asm volatile("s_waitcnt vmcnt(" #n ")" ::: "memory")
; #define PG8_WAIT_L(n) asm volatile("s_waitcnt lgkmcnt(" #n ")" ::: "memory")
; #define PG8_BAR __builtin_amdgcn_s_barrier()
; #define PG8_SCHED __builtin_amdgcn_sched_barrier(0)
; template <class Epi, class Sched>
; __device__ __forceinline__ void gemm_phase(LAS unsigned char* lds, const Gemm g, const Sched& S, const Epi& E, const int tid) {
;     ...
;             PG8_LDA(At, 1, 1); PG8_STAGE(PG8_SA(1, 0), a3, voffA);
;             PG8_BAR; PG8_WAIT_L(0); PG8_MMA(1, 0, At, B0); PG8_BAR; PG8_SCHED;
;             PG8_STAGE(PG8_SB(1, 1), b3 + hstep, voffB);
;             PG8_WAIT_V(6); PG8_BAR; PG8_MMA(1, 1, At, B1); PG8_BAR;
;         }
;         if constexpr (!Epi::AFTER_DRAIN) { if constexpr (Epi::PRELOAD) E(acc, cur, wr, wc, fr, fq, lds); else E(acc, cur, wr, wc, fr, fq); S.done(cur); }
;         if (!has_next) break;
; #pragma unroll
;         for (int a = 0; a < 2; ++a)
; #pragma unroll
;             for (int b = 0; b < 2; ++b)
; #pragma unroll
;                 for (int m = 0; m < 4; ++m)
; #pragma unroll
;                     for (int n = 0; n < 2; ++n) acc[a][b][m][n] = (f32x4){0.f, 0.f, 0.f, 0.f};
;         cur = nxt; cA = nA; cB = nB; ++ui;
;     }
;     PG8_WAIT_V(0);
;     if (wr == 0) PG8_BAR;
;     PG8_BAR;
	s_waitcnt lgkmcnt(0)
	v_mfma_f32_16x16x32_bf16 v[2:5], v[194:197], v[158:161], v[2:5]
	v_mfma_f32_16x16x32_bf16 v[10:13], v[202:205], v[158:161], v[10:13]
	v_mfma_f32_16x16x32_bf16 v[26:29], v[194:197], v[166:169], v[26:29]
	v_mfma_f32_16x16x32_bf16 v[30:33], v[202:205], v[166:169], v[30:33]
	v_mfma_f32_16x16x32_bf16 v[42:45], v[194:197], v[174:177], v[42:45]
	v_mfma_f32_16x16x32_bf16 v[46:49], v[202:205], v[174:177], v[46:49]
	v_mfma_f32_16x16x32_bf16 v[58:61], v[194:197], v[186:189], v[58:61]
	v_mfma_f32_16x16x32_bf16 v[62:65], v[202:205], v[186:189], v[62:65]
	v_mfma_f32_16x16x32_bf16 v[2:5], v[198:201], v[162:165], v[2:5]
	v_mfma_f32_16x16x32_bf16 v[10:13], v[206:209], v[162:165], v[10:13]
	v_mfma_f32_16x16x32_bf16 v[26:29], v[198:201], v[170:173], v[26:29]
	v_mfma_f32_16x16x32_bf16 v[30:33], v[206:209], v[170:173], v[30:33]
	v_mfma_f32_16x16x32_bf16 v[42:45], v[198:201], v[182:185], v[42:45]
	v_mfma_f32_16x16x32_bf16 v[46:49], v[206:209], v[182:185], v[46:49]
	v_mfma_f32_16x16x32_bf16 v[58:61], v[198:201], v[190:193], v[58:61]
	v_mfma_f32_16x16x32_bf16 v[62:65], v[206:209], v[190:193], v[62:65]
	s_mov_b32 m0, s55
	v_lshl_add_u64 v[178:179], v[214:215], 0, s[36:37]
	s_barrier
	ds_read_b128 v[158:161], v141 offset:49152
	ds_read_b128 v[162:165], v141 offset:50176
	ds_read_b128 v[166:169], v141 offset:51200
	ds_read_b128 v[170:173], v141 offset:52224
	ds_read_b128 v[174:177], v141 offset:53248
	ds_read_b128 v[182:185], v141 offset:54272
	ds_read_b128 v[186:189], v141 offset:55296
	ds_read_b128 v[190:193], v141 offset:56320
	global_load_lds_dwordx4 v[178:179], off
	s_mov_b32 m0, s58
	v_lshl_add_u64 v[178:179], v[216:217], 0, s[36:37]
	global_load_lds_dwordx4 v[178:179], off
	s_barrier
	s_waitcnt lgkmcnt(0)
	v_mfma_f32_16x16x32_bf16 v[66:69], v[142:145], v[158:161], v[66:69]
	v_mfma_f32_16x16x32_bf16 v[70:73], v[150:153], v[158:161], v[70:73]
	v_mfma_f32_16x16x32_bf16 v[82:85], v[142:145], v[166:169], v[82:85]
	v_mfma_f32_16x16x32_bf16 v[86:89], v[150:153], v[166:169], v[86:89]
	v_mfma_f32_16x16x32_bf16 v[102:105], v[142:145], v[174:177], v[102:105]
	v_mfma_f32_16x16x32_bf16 v[106:109], v[150:153], v[174:177], v[106:109]
	v_mfma_f32_16x16x32_bf16 v[122:125], v[142:145], v[186:189], v[122:125]
	v_mfma_f32_16x16x32_bf16 v[126:129], v[150:153], v[186:189], v[126:129]
	v_mfma_f32_16x16x32_bf16 v[66:69], v[146:149], v[162:165], v[66:69]
	v_mfma_f32_16x16x32_bf16 v[70:73], v[154:157], v[162:165], v[70:73]
	v_mfma_f32_16x16x32_bf16 v[82:85], v[146:149], v[170:173], v[82:85]
	v_mfma_f32_16x16x32_bf16 v[86:89], v[154:157], v[170:173], v[86:89]
	v_mfma_f32_16x16x32_bf16 v[102:105], v[146:149], v[182:185], v[102:105]
	v_mfma_f32_16x16x32_bf16 v[106:109], v[154:157], v[182:185], v[106:109]
	v_mfma_f32_16x16x32_bf16 v[122:125], v[146:149], v[190:193], v[122:125]
	v_mfma_f32_16x16x32_bf16 v[126:129], v[154:157], v[190:193], v[126:129]
	s_barrier
	s_add_u32 s38, s38, 0x160080
	s_addc_u32 s39, s39, 0
	s_add_i32 s40, s40, s24
	s_mov_b32 m0, s40
	s_nop 0
	global_load_lds_dwordx4 v0, s[38:39]
	s_add_i32 m0, s40, 0x2000
	s_nop 0
	global_load_lds_dwordx4 v134, s[38:39]
	s_waitcnt vmcnt(6)
	s_barrier
	v_mfma_f32_16x16x32_bf16 v[74:77], v[194:197], v[158:161], v[74:77]
	v_mfma_f32_16x16x32_bf16 v[78:81], v[202:205], v[158:161], v[78:81]
	v_mfma_f32_16x16x32_bf16 v[90:93], v[194:197], v[166:169], v[90:93]
	v_mfma_f32_16x16x32_bf16 v[94:97], v[202:205], v[166:169], v[94:97]
	v_mfma_f32_16x16x32_bf16 v[114:117], v[194:197], v[174:177], v[114:117]
	v_mfma_f32_16x16x32_bf16 v[118:121], v[202:205], v[174:177], v[118:121]
	v_mfma_f32_16x16x32_bf16 v[110:113], v[194:197], v[186:189], v[110:113]
	v_mfma_f32_16x16x32_bf16 v[98:101], v[202:205], v[186:189], v[98:101]
	v_mfma_f32_16x16x32_bf16 v[74:77], v[198:201], v[162:165], v[74:77]
	v_mfma_f32_16x16x32_bf16 v[78:81], v[206:209], v[162:165], v[78:81]
	v_mfma_f32_16x16x32_bf16 v[90:93], v[198:201], v[170:173], v[90:93]
	v_mfma_f32_16x16x32_bf16 v[94:97], v[206:209], v[170:173], v[94:97]
	v_mfma_f32_16x16x32_bf16 v[114:117], v[198:201], v[182:185], v[114:117]
	v_mfma_f32_16x16x32_bf16 v[118:121], v[206:209], v[182:185], v[118:121]
	v_mfma_f32_16x16x32_bf16 v[110:113], v[198:201], v[190:193], v[110:113]
	v_mfma_f32_16x16x32_bf16 v[98:101], v[206:209], v[190:193], v[98:101]
	s_add_i32 s51, s51, 2
	s_add_u32 s22, s22, 0x100
	s_addc_u32 s23, s23, 0
	s_cmpk_lt_u32 s51, 0x56
	s_barrier
	s_cbranch_scc1 .LBB0_1627
	s_waitcnt vmcnt(0)
	s_cmpk_gt_u32 s42, 0xff
	s_cbranch_scc1 .LBB0_1630
	s_barrier

; #define PG8_WAIT_V(n) asm volatile("s_waitcnt vmcnt(" #n ")" ::: "memory")
; template <class Epi, class Sched>
; __device__ __forceinline__ void gemm_phase(LAS unsigned char* lds, const Gemm g, const Sched& S, const Epi& E, const int tid) {
;     ...
;     f32x4 acc[2][2][4][2];
; #pragma unroll
;     for (int a = 0; a < 2; ++a)
; #pragma unroll
;         for (int b = 0; b < 2; ++b)
; #pragma unroll
;             for (int m = 0; m < 4; ++m)
; #pragma unroll
;                 for (int n = 0; n < 2; ++n) acc[a][b][m][n] = (f32x4){0.f, 0.f, 0.f, 0.f};
;     bf16x8 At[4][2], B0[2][2], B1[2][2];
;     const char* cA = (const char*)g.A + (size_t)cur.pm * tstep + (size_t)cur.ks * cur.nt * kstep; const char* cB = (const char*)g.Bt + (size_t)cur.pn * tstep + (size_t)cur.ks * cur.nt * kstep;
;     S.a_ready(cur);
;     PG8_STAGE(PG8_SB(0, 0), cB, voffB); PG8_STAGE(PG8_SA(0, 0), cA, voffA); PG8_STAGE(PG8_SB(0, 1), cB + hstep, voffB); PG8_STAGE(PG8_SA(0, 1), cA + hstep, voffA);
;     if (wr == 1) PG8_BAR;
;     PG8_WAIT_V(4); PG8_BAR;
;     PG8_STAGE(PG8_SB(1, 0), cB + kstep, voffB); PG8_STAGE(PG8_SA(1, 0), cA + kstep, voffA); PG8_STAGE(PG8_SB(1, 1), cB + hstep + kstep, voffB);
;     PG8_WAIT_V(6); PG8_BAR;
;     for (;;) {
;         const bool has_next = S.next(ui + 1, nxt);
;         const char* nA = has_next ? (const char*)g.A + (size_t)nxt.pm * tstep + (size_t)nxt.ks * nxt.nt * kstep : cA; const char* nB = has_next ? (const char*)g.Bt + (size_t)nxt.pn * tstep + (size_t)nxt.ks * nxt.nt * kstep : cB;
;         const int nt = cur.nt;
;         for (int t = 0; t < nt; t += 2) {
;             const bool last = (t == nt - 2);
;             const char* a1 = cA + (size_t)(t + 1) * kstep;
;             const char* a2 = last ? nA : cA + (size_t)(t + 2) * kstep; const char* b2 = last ? nB : cB + (size_t)(t + 2) * kstep;
;             const char* a3 = a2 + kstep; const char* b3 = b2 + kstep;
;             if (last && has_next) S.a_ready(nxt);
;             if constexpr (Epi::PRELOAD) { if (last) E.preload(cur, lds, wid, lane); }
;             PG8_LDB(B0, 0, 0); PG8_SCHED; PG8_LDA(At, 0, 0); PG8_STAGE(PG8_SA(1, 1), a1 + hstep, voffA);
;             PG8_WAIT_L(8); PG8_BAR; PG8_WAIT_L(0); PG8_MMA(0, 0, At, B0); PG8_BAR; PG8_SCHED;
;             PG8_LDB(B1, 0, 1); PG8_STAGE(PG8_SB(0, 0), b2, voffB);
;             PG8_BAR; PG8_WAIT_L(0); PG8_MMA(0, 1, At, B1); PG8_BAR;
.LBB0_1679:
	s_add_u32 s5, s14, 0x100
	v_mov_b32_e32 v2, 0
	s_addc_u32 s11, s15, 0
	s_mov_b32 s52, -2
	v_mov_b32_e32 v3, v2
	v_mov_b32_e32 v4, v2
	v_mov_b32_e32 v5, v2
	v_mov_b32_e32 v6, v2
	v_mov_b32_e32 v7, v2
	v_mov_b32_e32 v8, v2
	v_mov_b32_e32 v9, v2
	v_mov_b32_e32 v10, v2
	v_mov_b32_e32 v11, v2
	v_mov_b32_e32 v12, v2
	v_mov_b32_e32 v13, v2
	v_mov_b32_e32 v14, v2
	v_mov_b32_e32 v15, v2
	v_mov_b32_e32 v16, v2
	v_mov_b32_e32 v17, v2
	v_mov_b32_e32 v26, v2
	v_mov_b32_e32 v27, v2
	v_mov_b32_e32 v28, v2
	v_mov_b32_e32 v29, v2
	v_mov_b32_e32 v30, v2
	v_mov_b32_e32 v31, v2
	v_mov_b32_e32 v32, v2
	v_mov_b32_e32 v33, v2
	v_mov_b32_e32 v42, v2
	v_mov_b32_e32 v43, v2
	v_mov_b32_e32 v44, v2
	v_mov_b32_e32 v45, v2
	v_mov_b32_e32 v46, v2
	v_mov_b32_e32 v47, v2
	v_mov_b32_e32 v48, v2
	v_mov_b32_e32 v49, v2
	v_mov_b32_e32 v18, v2
	v_mov_b32_e32 v19, v2
	v_mov_b32_e32 v20, v2
	v_mov_b32_e32 v21, v2
	v_mov_b32_e32 v22, v2
	v_mov_b32_e32 v23, v2
	v_mov_b32_e32 v24, v2
	v_mov_b32_e32 v25, v2
	v_mov_b32_e32 v34, v2
	v_mov_b32_e32 v35, v2
	v_mov_b32_e32 v36, v2
	v_mov_b32_e32 v37, v2
	v_mov_b32_e32 v38, v2
	v_mov_b32_e32 v39, v2
	v_mov_b32_e32 v40, v2
	v_mov_b32_e32 v41, v2
	v_mov_b32_e32 v50, v2
	v_mov_b32_e32 v51, v2
	v_mov_b32_e32 v52, v2
	v_mov_b32_e32 v53, v2
	v_mov_b32_e32 v54, v2
	v_mov_b32_e32 v55, v2
	v_mov_b32_e32 v56, v2
	v_mov_b32_e32 v57, v2
	v_mov_b32_e32 v58, v2
	v_mov_b32_e32 v59, v2
	v_mov_b32_e32 v60, v2
	v_mov_b32_e32 v61, v2
	v_mov_b32_e32 v62, v2
	v_mov_b32_e32 v63, v2
	v_mov_b32_e32 v64, v2
	v_mov_b32_e32 v65, v2
	v_mov_b32_e32 v66, v2
	v_mov_b32_e32 v67, v2
	v_mov_b32_e32 v68, v2
	v_mov_b32_e32 v69, v2
	v_mov_b32_e32 v70, v2
	v_mov_b32_e32 v71, v2
	v_mov_b32_e32 v72, v2
	v_mov_b32_e32 v73, v2
	v_mov_b32_e32 v74, v2
	v_mov_b32_e32 v75, v2
	v_mov_b32_e32 v76, v2
	v_mov_b32_e32 v77, v2
	v_mov_b32_e32 v78, v2
	v_mov_b32_e32 v79, v2
	v_mov_b32_e32 v80, v2
	v_mov_b32_e32 v81, v2
	v_mov_b32_e32 v86, v2
	v_mov_b32_e32 v87, v2
	v_mov_b32_e32 v88, v2
	v_mov_b32_e32 v89, v2
	v_mov_b32_e32 v94, v2
	v_mov_b32_e32 v95, v2
	v_mov_b32_e32 v96, v2
	v_mov_b32_e32 v97, v2
	v_mov_b32_e32 v102, v2
	v_mov_b32_e32 v103, v2
	v_mov_b32_e32 v104, v2
	v_mov_b32_e32 v105, v2
	v_mov_b32_e32 v110, v2
	v_mov_b32_e32 v111, v2
	v_mov_b32_e32 v112, v2
	v_mov_b32_e32 v113, v2
	v_mov_b32_e32 v82, v2
	v_mov_b32_e32 v83, v2
	v_mov_b32_e32 v84, v2
	v_mov_b32_e32 v85, v2
	v_mov_b32_e32 v90, v2
	v_mov_b32_e32 v91, v2
	v_mov_b32_e32 v92, v2
	v_mov_b32_e32 v93, v2
	v_mov_b32_e32 v98, v2
	v_mov_b32_e32 v99, v2
	v_mov_b32_e32 v100, v2
	v_mov_b32_e32 v101, v2
	v_mov_b32_e32 v106, v2
	v_mov_b32_e32 v107, v2
	v_mov_b32_e32 v108, v2
	v_mov_b32_e32 v109, v2
	v_mov_b32_e32 v114, v2
	v_mov_b32_e32 v115, v2
	v_mov_b32_e32 v116, v2
	v_mov_b32_e32 v117, v2
	v_mov_b32_e32 v118, v2
	v_mov_b32_e32 v119, v2
	v_mov_b32_e32 v120, v2
	v_mov_b32_e32 v121, v2
	v_mov_b32_e32 v122, v2
	v_mov_b32_e32 v123, v2
	v_mov_b32_e32 v124, v2
	v_mov_b32_e32 v125, v2
	v_mov_b32_e32 v126, v2
	v_mov_b32_e32 v127, v2
	v_mov_b32_e32 v128, v2
	v_mov_b32_e32 v129, v2
	v_add_u32_e32 v252, 0x10000, v137
	v_add_u32_e32 v251, 0x14000, v137
	v_add_u32_e32 v250, 0x18000, v137
	v_add_u32_e32 v249, 0x1c000, v137
.LBB0_1680:
	s_add_u32 s14, s12, 0x100
	s_addc_u32 s15, s13, 0
	s_add_i32 s53, 0, 0x10000
	ds_read_b128 v[140:143], v252
	ds_read_b128 v[144:147], v252 offset:1024
	ds_read_b128 v[148:151], v252 offset:2048
	ds_read_b128 v[152:155], v252 offset:3072
	s_cmp_eq_u32 s52, 4
	s_cselect_b32 s19, s7, s15
	s_cselect_b32 s18, s6, s14
	s_cselect_b32 s17, s3, s11
	s_cselect_b32 s16, s2, s5
	v_lshl_add_u64 v[188:189], s[12:13], 0, v[132:133]
	s_add_i32 m0, s28, 0xc000
	ds_read_b128 v[156:159], v139
	ds_read_b128 v[160:163], v139 offset:1024
	ds_read_b128 v[164:167], v139 offset:2048
	ds_read_b128 v[168:171], v139 offset:3072
	ds_read_b128 v[172:175], v139 offset:4096
	ds_read_b128 v[176:179], v139 offset:5120
	ds_read_b128 v[180:183], v139 offset:6144
	ds_read_b128 v[184:187], v139 offset:7168
	global_load_lds_dwordx4 v[188:189], off
	s_add_i32 m0, s28, 0xe000
	v_lshl_add_u64 v[188:189], s[12:13], 0, v[134:135]
	global_load_lds_dwordx4 v[188:189], off
	s_waitcnt lgkmcnt(8)
	s_barrier
	s_waitcnt lgkmcnt(0)
	v_mfma_f32_16x16x32_bf16 v[126:129], v[140:143], v[156:159], v[126:129]
	v_mfma_f32_16x16x32_bf16 v[122:125], v[148:151], v[156:159], v[122:125]
	v_mfma_f32_16x16x32_bf16 v[118:121], v[140:143], v[164:167], v[118:121]
	v_mfma_f32_16x16x32_bf16 v[114:117], v[148:151], v[164:167], v[114:117]
	v_mfma_f32_16x16x32_bf16 v[106:109], v[140:143], v[172:175], v[106:109]
	v_mfma_f32_16x16x32_bf16 v[98:101], v[148:151], v[172:175], v[98:101]
	v_mfma_f32_16x16x32_bf16 v[90:93], v[140:143], v[180:183], v[90:93]
	v_mfma_f32_16x16x32_bf16 v[82:85], v[148:151], v[180:183], v[82:85]
	v_mfma_f32_16x16x32_bf16 v[126:129], v[144:147], v[160:163], v[126:129]
	v_mfma_f32_16x16x32_bf16 v[122:125], v[152:155], v[160:163], v[122:125]
	v_mfma_f32_16x16x32_bf16 v[118:121], v[144:147], v[168:171], v[118:121]
	v_mfma_f32_16x16x32_bf16 v[114:117], v[152:155], v[168:171], v[114:117]
	v_mfma_f32_16x16x32_bf16 v[106:109], v[144:147], v[176:179], v[106:109]
	v_mfma_f32_16x16x32_bf16 v[98:101], v[152:155], v[176:179], v[98:101]
	v_mfma_f32_16x16x32_bf16 v[90:93], v[144:147], v[184:187], v[90:93]
	v_mfma_f32_16x16x32_bf16 v[82:85], v[152:155], v[184:187], v[82:85]
	s_barrier
	s_add_i32 s54, 0, 0x14000
	s_add_i32 s12, s53, s39
	s_mov_b32 m0, s12
	ds_read_b128 v[188:191], v251
	ds_read_b128 v[192:195], v251 offset:1024
	ds_read_b128 v[196:199], v251 offset:2048
	ds_read_b128 v[200:203], v251 offset:3072
	global_load_lds_dwordx4 v0, s[16:17]
	s_add_i32 m0, s12, 0x2000
	s_nop 0
	global_load_lds_dwordx4 v130, s[16:17]
	s_barrier
; #define PG8_STAGE(bufoff, gbase, voff) do { _Pragma("unroll") for (int _i = 0; _i < 2; ++_i) \
;         __builtin_amdgcn_global_load_lds((const unsigned*)((const char*)(gbase) + (voff)[_i]), (LAS unsigned*)(lds + (bufoff) + ldsw + _i * 8192), 16, 0, 0); } while (0)
; #define PG8_LDA(dst, b, h) do { _Pragma("unroll") for (int m = 0; m < 4; ++m) _Pragma("unroll") for (int k = 0; k < 2; ++k) dst[m][k] = *(const LAS bf16x8*)(lds + PG8_SA(b, h) + aoff + m * 2048 + k * 1024); } while (0)
; #define PG8_LDB(dst, b, h) do { _Pragma("unroll") for (int n = 0; n < 2; ++n) _Pragma("unroll") for (int k = 0; k < 2; ++k) dst[n][k] = *(const LAS bf16x8*)(lds + PG8_SB(b, h) + boff + n * 2048 + k * 1024); } while (0)
; #define PG8_MMA(ai, bj, At, Bt) do { __builtin_amdgcn_s_setprio(1); _Pragma("unroll") for (int m = 0; m < 4; ++m) _Pragma("unroll") for (int n = 0; n < 2; ++n) _Pragma("unroll") for (int k = 0; k < 2; ++k) \
;         acc[ai][bj][m][n] = __builtin_amdgcn_mfma_f32_16x16x32_bf16(Bt[n][k], At[m][k], acc[ai][bj][m][n], 0, 0, 0); __builtin_amdgcn_s_setprio(0); } while (0)
; #define PG8_WAIT_V(n) asm volatile("s_waitcnt vmcnt(" #n ")" ::: "memory")
; #define PG8_WAIT_L(n) asm volatile("s_waitcnt lgkmcnt(" #n ")" ::: "memory")
; #define PG8_BAR __builtin_amdgcn_s_barrier()
; #define PG8_SCHED __builtin_amdgcn_sched_barrier(0)
; template <class Epi, class Sched>
; __device__ __forceinline__ void gemm_phase(LAS unsigned char* lds, const Gemm g, const Sched& S, const Epi& E, const int tid) {
;     ...
;             PG8_BAR; PG8_WAIT_L(0); PG8_MMA(0, 1, At, B1); PG8_BAR;
;             PG8_LDA(At, 0, 1); PG8_STAGE(PG8_SA(0, 0), a2, voffA);
;             PG8_BAR; PG8_WAIT_L(0); PG8_MMA(1, 0, At, B0); PG8_BAR; PG8_SCHED;
;             PG8_STAGE(PG8_SB(0, 1), b2 + hstep, voffB);
;             PG8_WAIT_V(6); PG8_BAR; PG8_MMA(1, 1, At, B1); PG8_BAR;
;             PG8_LDB(B0, 1, 0); PG8_SCHED; PG8_LDA(At, 1, 0); PG8_STAGE(PG8_SA(0, 1), a2 + hstep, voffA);
;             PG8_WAIT_L(8); PG8_BAR; PG8_WAIT_L(0); PG8_MMA(0, 0, At, B0); PG8_BAR; PG8_SCHED;
;             PG8_LDB(B1, 1, 1); PG8_STAGE(PG8_SB(1, 0), b3, voffB);
	s_waitcnt lgkmcnt(0)
	v_mfma_f32_16x16x32_bf16 v[110:113], v[188:191], v[156:159], v[110:113]
	v_mfma_f32_16x16x32_bf16 v[102:105], v[196:199], v[156:159], v[102:105]
	v_mfma_f32_16x16x32_bf16 v[94:97], v[188:191], v[164:167], v[94:97]
	v_mfma_f32_16x16x32_bf16 v[86:89], v[196:199], v[164:167], v[86:89]
	v_mfma_f32_16x16x32_bf16 v[78:81], v[188:191], v[172:175], v[78:81]
	v_mfma_f32_16x16x32_bf16 v[74:77], v[196:199], v[172:175], v[74:77]
	v_mfma_f32_16x16x32_bf16 v[70:73], v[188:191], v[180:183], v[70:73]
	v_mfma_f32_16x16x32_bf16 v[66:69], v[196:199], v[180:183], v[66:69]
	v_mfma_f32_16x16x32_bf16 v[110:113], v[192:195], v[160:163], v[110:113]
	v_mfma_f32_16x16x32_bf16 v[102:105], v[200:203], v[160:163], v[102:105]
	v_mfma_f32_16x16x32_bf16 v[94:97], v[192:195], v[168:171], v[94:97]
	v_mfma_f32_16x16x32_bf16 v[86:89], v[200:203], v[168:171], v[86:89]
	v_mfma_f32_16x16x32_bf16 v[78:81], v[192:195], v[176:179], v[78:81]
	v_mfma_f32_16x16x32_bf16 v[74:77], v[200:203], v[176:179], v[74:77]
	v_mfma_f32_16x16x32_bf16 v[70:73], v[192:195], v[184:187], v[70:73]
	v_mfma_f32_16x16x32_bf16 v[66:69], v[200:203], v[184:187], v[66:69]
	s_mov_b32 m0, s28
	v_lshl_add_u64 v[208:209], s[18:19], 0, v[0:1]
	s_barrier
	ds_read_b128 v[156:159], v139 offset:16384
	ds_read_b128 v[160:163], v139 offset:17408
	ds_read_b128 v[164:167], v139 offset:18432
	ds_read_b128 v[168:171], v139 offset:19456
	ds_read_b128 v[172:175], v139 offset:20480
	ds_read_b128 v[176:179], v139 offset:21504
	ds_read_b128 v[180:183], v139 offset:22528
	ds_read_b128 v[184:187], v139 offset:23552
	global_load_lds_dwordx4 v[208:209], off
	s_mov_b32 m0, s41
	v_lshl_add_u64 v[210:211], s[18:19], 0, v[130:131]
	global_load_lds_dwordx4 v[210:211], off
	s_barrier
	s_waitcnt lgkmcnt(0)
	v_mfma_f32_16x16x32_bf16 v[62:65], v[140:143], v[156:159], v[62:65]
	v_mfma_f32_16x16x32_bf16 v[58:61], v[148:151], v[156:159], v[58:61]
	v_mfma_f32_16x16x32_bf16 v[54:57], v[140:143], v[164:167], v[54:57]
	v_mfma_f32_16x16x32_bf16 v[50:53], v[148:151], v[164:167], v[50:53]
	v_mfma_f32_16x16x32_bf16 v[38:41], v[140:143], v[172:175], v[38:41]
	v_mfma_f32_16x16x32_bf16 v[34:37], v[148:151], v[172:175], v[34:37]
	v_mfma_f32_16x16x32_bf16 v[22:25], v[140:143], v[180:183], v[22:25]
	v_mfma_f32_16x16x32_bf16 v[18:21], v[148:151], v[180:183], v[18:21]
	v_mfma_f32_16x16x32_bf16 v[62:65], v[144:147], v[160:163], v[62:65]
	v_mfma_f32_16x16x32_bf16 v[58:61], v[152:155], v[160:163], v[58:61]
	v_mfma_f32_16x16x32_bf16 v[54:57], v[144:147], v[168:171], v[54:57]
	v_mfma_f32_16x16x32_bf16 v[50:53], v[152:155], v[168:171], v[50:53]
	v_mfma_f32_16x16x32_bf16 v[38:41], v[144:147], v[176:179], v[38:41]
	v_mfma_f32_16x16x32_bf16 v[34:37], v[152:155], v[176:179], v[34:37]
	v_mfma_f32_16x16x32_bf16 v[22:25], v[144:147], v[184:187], v[22:25]
	v_mfma_f32_16x16x32_bf16 v[18:21], v[152:155], v[184:187], v[18:21]
	s_barrier
	s_add_u32 s12, s16, 0x160000
	s_addc_u32 s13, s17, 0
	s_add_i32 s53, s54, s39
	s_mov_b32 m0, s53
	s_nop 0
	global_load_lds_dwordx4 v0, s[12:13]
	s_add_i32 m0, s53, 0x2000
	s_nop 0
	global_load_lds_dwordx4 v130, s[12:13]
	s_waitcnt vmcnt(6)
	s_barrier
	v_mfma_f32_16x16x32_bf16 v[46:49], v[188:191], v[156:159], v[46:49]
	v_mfma_f32_16x16x32_bf16 v[42:45], v[196:199], v[156:159], v[42:45]
	v_mfma_f32_16x16x32_bf16 v[30:33], v[188:191], v[164:167], v[30:33]
	v_mfma_f32_16x16x32_bf16 v[26:29], v[196:199], v[164:167], v[26:29]
	v_mfma_f32_16x16x32_bf16 v[14:17], v[188:191], v[172:175], v[14:17]
	v_mfma_f32_16x16x32_bf16 v[10:13], v[196:199], v[172:175], v[10:13]
	v_mfma_f32_16x16x32_bf16 v[6:9], v[188:191], v[180:183], v[6:9]
	v_mfma_f32_16x16x32_bf16 v[2:5], v[196:199], v[180:183], v[2:5]
	v_mfma_f32_16x16x32_bf16 v[46:49], v[192:195], v[160:163], v[46:49]
	v_mfma_f32_16x16x32_bf16 v[42:45], v[200:203], v[160:163], v[42:45]
	v_mfma_f32_16x16x32_bf16 v[30:33], v[192:195], v[168:171], v[30:33]
	v_mfma_f32_16x16x32_bf16 v[26:29], v[200:203], v[168:171], v[26:29]
	v_mfma_f32_16x16x32_bf16 v[14:17], v[192:195], v[176:179], v[14:17]
	v_mfma_f32_16x16x32_bf16 v[10:13], v[200:203], v[176:179], v[10:13]
	v_mfma_f32_16x16x32_bf16 v[6:9], v[192:195], v[184:187], v[6:9]
	v_mfma_f32_16x16x32_bf16 v[2:5], v[200:203], v[184:187], v[2:5]
	s_add_i32 s53, 0, 0x18000
	s_barrier
	ds_read_b128 v[140:143], v250
	ds_read_b128 v[144:147], v250 offset:1024
	ds_read_b128 v[148:151], v250 offset:2048
	ds_read_b128 v[152:155], v250 offset:3072
	s_add_u32 s12, s18, 0x160000
	s_addc_u32 s13, s19, 0
	s_mov_b32 m0, s42
	ds_read_b128 v[156:159], v139 offset:32768
	ds_read_b128 v[160:163], v139 offset:33792
	ds_read_b128 v[164:167], v139 offset:34816
	ds_read_b128 v[168:171], v139 offset:35840
	ds_read_b128 v[172:175], v139 offset:36864
	ds_read_b128 v[176:179], v139 offset:37888
	ds_read_b128 v[180:183], v139 offset:38912
	global_load_lds_dwordx4 v0, s[12:13]
	s_mov_b32 m0, s43
	ds_read_b128 v[184:187], v139 offset:39936
	global_load_lds_dwordx4 v130, s[12:13]
	s_waitcnt lgkmcnt(8)
	s_barrier
	s_waitcnt lgkmcnt(0)
	v_mfma_f32_16x16x32_bf16 v[126:129], v[140:143], v[156:159], v[126:129]
	v_mfma_f32_16x16x32_bf16 v[122:125], v[148:151], v[156:159], v[122:125]
	v_mfma_f32_16x16x32_bf16 v[118:121], v[140:143], v[164:167], v[118:121]
	v_mfma_f32_16x16x32_bf16 v[114:117], v[148:151], v[164:167], v[114:117]
	v_mfma_f32_16x16x32_bf16 v[106:109], v[140:143], v[172:175], v[106:109]
	v_mfma_f32_16x16x32_bf16 v[98:101], v[148:151], v[172:175], v[98:101]
	v_mfma_f32_16x16x32_bf16 v[90:93], v[140:143], v[180:183], v[90:93]
	v_mfma_f32_16x16x32_bf16 v[82:85], v[148:151], v[180:183], v[82:85]
	v_mfma_f32_16x16x32_bf16 v[126:129], v[144:147], v[160:163], v[126:129]
	v_mfma_f32_16x16x32_bf16 v[122:125], v[152:155], v[160:163], v[122:125]
	v_mfma_f32_16x16x32_bf16 v[118:121], v[144:147], v[168:171], v[118:121]
	v_mfma_f32_16x16x32_bf16 v[114:117], v[152:155], v[168:171], v[114:117]
	v_mfma_f32_16x16x32_bf16 v[106:109], v[144:147], v[176:179], v[106:109]
	v_mfma_f32_16x16x32_bf16 v[98:101], v[152:155], v[176:179], v[98:101]
	v_mfma_f32_16x16x32_bf16 v[90:93], v[144:147], v[184:187], v[90:93]
	v_mfma_f32_16x16x32_bf16 v[82:85], v[152:155], v[184:187], v[82:85]
	s_barrier
; #define PG8_STAGE(bufoff, gbase, voff) do { _Pragma("unroll") for (int _i = 0; _i < 2; ++_i) \
;         __builtin_amdgcn_global_load_lds((const unsigned*)((const char*)(gbase) + (voff)[_i]), (LAS unsigned*)(lds + (bufoff) + ldsw + _i * 8192), 16, 0, 0); } while (0)
; #define PG8_LDA(dst, b, h) do { _Pragma("unroll") for (int m = 0; m < 4; ++m) _Pragma("unroll") for (int k = 0; k < 2; ++k) dst[m][k] = *(const LAS bf16x8*)(lds + PG8_SA(b, h) + aoff + m * 2048 + k * 1024); } while (0)
; #define PG8_LDB(dst, b, h) do { _Pragma("unroll") for (int n = 0; n < 2; ++n) _Pragma("unroll") for (int k = 0; k < 2; ++k) dst[n][k] = *(const LAS bf16x8*)(lds + PG8_SB(b, h) + boff + n * 2048 + k * 1024); } while (0)
; #define PG8_MMA(ai, bj, At, Bt) do { __builtin_amdgcn_s_setprio(1); _Pragma("unroll") for (int m = 0; m < 4; ++m) _Pragma("unroll") for (int n = 0; n < 2; ++n) _Pragma("unroll") for (int k = 0; k < 2; ++k) \
;         acc[ai][bj][m][n] = __builtin_amdgcn_mfma_f32_16x16x32_bf16(Bt[n][k], At[m][k], acc[ai][bj][m][n], 0, 0, 0); __builtin_amdgcn_s_setprio(0); } while (0)
; #define PG8_WAIT_V(n) asm volatile("s_waitcnt vmcnt(" #n ")" ::: "memory")
; #define PG8_WAIT_L(n) asm volatile("s_waitcnt lgkmcnt(" #n ")" ::: "memory")
; #define PG8_BAR __builtin_amdgcn_s_barrier()
; #define PG8_SCHED __builtin_amdgcn_sched_barrier(0)
; template <class Epi, class Sched>
; __device__ __forceinline__ void gemm_phase(LAS unsigned char* lds, const Gemm g, const Sched& S, const Epi& E, const int tid) {
;     ...
;             PG8_LDB(B1, 1, 1); PG8_STAGE(PG8_SB(1, 0), b3, voffB);
;             PG8_BAR; PG8_WAIT_L(0); PG8_MMA(0, 1, At, B1); PG8_BAR;
;             PG8_LDA(At, 1, 1); PG8_STAGE(PG8_SA(1, 0), a3, voffA);
;             PG8_BAR; PG8_WAIT_L(0); PG8_MMA(1, 0, At, B0); PG8_BAR; PG8_SCHED;
;             PG8_STAGE(PG8_SB(1, 1), b3 + hstep, voffB);
;             PG8_WAIT_V(6); PG8_BAR; PG8_MMA(1, 1, At, B1); PG8_BAR;
;         }
	s_add_i32 s18, 0, 0x1c000
	s_add_i32 s12, s53, s39
	s_add_u32 s98, s16, s36
	s_addc_u32 s99, s17, s37
	s_mov_b32 m0, s12
	ds_read_b128 v[188:191], v249
	ds_read_b128 v[192:195], v249 offset:1024
	ds_read_b128 v[196:199], v249 offset:2048
	ds_read_b128 v[200:203], v249 offset:3072
	global_load_lds_dwordx4 v0, s[98:99]
	s_add_i32 m0, s12, 0x2000
	s_add_u32 s98, s16, s36
	s_addc_u32 s99, s17, s37
	global_load_lds_dwordx4 v130, s[98:99]
	s_barrier
	s_waitcnt lgkmcnt(0)
	v_mfma_f32_16x16x32_bf16 v[110:113], v[188:191], v[156:159], v[110:113]
	v_mfma_f32_16x16x32_bf16 v[102:105], v[196:199], v[156:159], v[102:105]
	v_mfma_f32_16x16x32_bf16 v[94:97], v[188:191], v[164:167], v[94:97]
	v_mfma_f32_16x16x32_bf16 v[86:89], v[196:199], v[164:167], v[86:89]
	v_mfma_f32_16x16x32_bf16 v[78:81], v[188:191], v[172:175], v[78:81]
	v_mfma_f32_16x16x32_bf16 v[74:77], v[196:199], v[172:175], v[74:77]
	v_mfma_f32_16x16x32_bf16 v[70:73], v[188:191], v[180:183], v[70:73]
	v_mfma_f32_16x16x32_bf16 v[66:69], v[196:199], v[180:183], v[66:69]
	v_mfma_f32_16x16x32_bf16 v[110:113], v[192:195], v[160:163], v[110:113]
	v_mfma_f32_16x16x32_bf16 v[102:105], v[200:203], v[160:163], v[102:105]
	v_mfma_f32_16x16x32_bf16 v[94:97], v[192:195], v[168:171], v[94:97]
	v_mfma_f32_16x16x32_bf16 v[86:89], v[200:203], v[168:171], v[86:89]
	v_mfma_f32_16x16x32_bf16 v[78:81], v[192:195], v[176:179], v[78:81]
	v_mfma_f32_16x16x32_bf16 v[74:77], v[200:203], v[176:179], v[74:77]
	v_mfma_f32_16x16x32_bf16 v[70:73], v[192:195], v[184:187], v[70:73]
	v_mfma_f32_16x16x32_bf16 v[66:69], v[200:203], v[184:187], v[66:69]
	s_mov_b32 m0, s45
	v_lshl_add_u64 v[204:205], v[208:209], 0, s[36:37]
	s_barrier
	ds_read_b128 v[156:159], v139 offset:49152
	ds_read_b128 v[160:163], v139 offset:50176
	ds_read_b128 v[164:167], v139 offset:51200
	ds_read_b128 v[168:171], v139 offset:52224
	ds_read_b128 v[172:175], v139 offset:53248
	ds_read_b128 v[176:179], v139 offset:54272
	ds_read_b128 v[180:183], v139 offset:55296
	ds_read_b128 v[184:187], v139 offset:56320
	global_load_lds_dwordx4 v[204:205], off
	s_mov_b32 m0, s46
	v_lshl_add_u64 v[204:205], v[210:211], 0, s[36:37]
	global_load_lds_dwordx4 v[204:205], off
	s_barrier
	s_waitcnt lgkmcnt(0)
	v_mfma_f32_16x16x32_bf16 v[62:65], v[140:143], v[156:159], v[62:65]
	v_mfma_f32_16x16x32_bf16 v[58:61], v[148:151], v[156:159], v[58:61]
	v_mfma_f32_16x16x32_bf16 v[54:57], v[140:143], v[164:167], v[54:57]
	v_mfma_f32_16x16x32_bf16 v[50:53], v[148:151], v[164:167], v[50:53]
	v_mfma_f32_16x16x32_bf16 v[38:41], v[140:143], v[172:175], v[38:41]
	v_mfma_f32_16x16x32_bf16 v[34:37], v[148:151], v[172:175], v[34:37]
	v_mfma_f32_16x16x32_bf16 v[22:25], v[140:143], v[180:183], v[22:25]
	v_mfma_f32_16x16x32_bf16 v[18:21], v[148:151], v[180:183], v[18:21]
	v_mfma_f32_16x16x32_bf16 v[62:65], v[144:147], v[160:163], v[62:65]
	v_mfma_f32_16x16x32_bf16 v[58:61], v[152:155], v[160:163], v[58:61]
	v_mfma_f32_16x16x32_bf16 v[54:57], v[144:147], v[168:171], v[54:57]
	v_mfma_f32_16x16x32_bf16 v[50:53], v[152:155], v[168:171], v[50:53]
	v_mfma_f32_16x16x32_bf16 v[38:41], v[144:147], v[176:179], v[38:41]
	v_mfma_f32_16x16x32_bf16 v[34:37], v[152:155], v[176:179], v[34:37]
	v_mfma_f32_16x16x32_bf16 v[22:25], v[144:147], v[184:187], v[22:25]
	v_mfma_f32_16x16x32_bf16 v[18:21], v[152:155], v[184:187], v[18:21]
	s_barrier
	s_add_u32 s12, s16, 0x160080
	s_addc_u32 s13, s17, 0
	s_add_i32 s16, s18, s39
	s_mov_b32 m0, s16
	s_nop 0
	global_load_lds_dwordx4 v0, s[12:13]
	s_add_i32 m0, s16, 0x2000
	s_nop 0
	global_load_lds_dwordx4 v130, s[12:13]
	s_waitcnt vmcnt(6)
	s_barrier
	v_mfma_f32_16x16x32_bf16 v[46:49], v[188:191], v[156:159], v[46:49]
	v_mfma_f32_16x16x32_bf16 v[42:45], v[196:199], v[156:159], v[42:45]
	v_mfma_f32_16x16x32_bf16 v[30:33], v[188:191], v[164:167], v[30:33]
	v_mfma_f32_16x16x32_bf16 v[26:29], v[196:199], v[164:167], v[26:29]
	v_mfma_f32_16x16x32_bf16 v[14:17], v[188:191], v[172:175], v[14:17]
	v_mfma_f32_16x16x32_bf16 v[10:13], v[196:199], v[172:175], v[10:13]
	v_mfma_f32_16x16x32_bf16 v[6:9], v[188:191], v[180:183], v[6:9]
	v_mfma_f32_16x16x32_bf16 v[2:5], v[196:199], v[180:183], v[2:5]
	v_mfma_f32_16x16x32_bf16 v[46:49], v[192:195], v[160:163], v[46:49]
	v_mfma_f32_16x16x32_bf16 v[42:45], v[200:203], v[160:163], v[42:45]
	v_mfma_f32_16x16x32_bf16 v[30:33], v[192:195], v[168:171], v[30:33]
	v_mfma_f32_16x16x32_bf16 v[26:29], v[200:203], v[168:171], v[26:29]
	v_mfma_f32_16x16x32_bf16 v[14:17], v[192:195], v[176:179], v[14:17]
	v_mfma_f32_16x16x32_bf16 v[10:13], v[200:203], v[176:179], v[10:13]
	v_mfma_f32_16x16x32_bf16 v[6:9], v[192:195], v[184:187], v[6:9]
	v_mfma_f32_16x16x32_bf16 v[2:5], v[200:203], v[184:187], v[2:5]
	s_add_i32 s52, s52, 2
	s_add_u32 s5, s5, 0x100
	s_addc_u32 s11, s11, 0
	s_cmp_gt_u32 s52, 5
	s_mov_b64 s[12:13], s[14:15]
	s_barrier
; #define PG8_WAIT_V(n) asm volatile("s_waitcnt vmcnt(" #n ")" ::: "memory")
; #define PG8_BAR __builtin_amdgcn_s_barrier()
;     __device__ __forceinline__ void operator()(const f32x4 (&acc)[2][2][4][2], const Unit& u, int wr, int wc, int fr, int fq) const {
;         const int row0 = u.pm * BM + wr * 64 + fr, col0 = u.pn * BM + wc * 32 + 4 * fq;
;         float* base = (u.nt < ntfull) ? part + ((size_t)u.ks * MCTX - MLAT) * ldc : C;
; #pragma unroll
;         for (int ai = 0; ai < 2; ++ai)
; #pragma unroll
;             for (int m = 0; m < 4; ++m) { float* rowp = base + (size_t)(row0 + ai * HALF + m * 16) * ldc + col0;
; #pragma unroll
;                 for (int bj = 0; bj < 2; ++bj)
; #pragma unroll
;                     for (int n = 0; n < 2; ++n) *(f32x4*)(rowp + bj * HALF + n * 16) = acc[ai][bj][m][n]; }
;     }
; template <class Epi, class Sched>
; __device__ __forceinline__ void gemm_phase(LAS unsigned char* lds, const Gemm g, const Sched& S, const Epi& E, const int tid) {
;     ...
;         if constexpr (!Epi::AFTER_DRAIN) { if constexpr (Epi::PRELOAD) E(acc, cur, wr, wc, fr, fq, lds); else E(acc, cur, wr, wc, fr, fq); S.done(cur); }
;         if (!has_next) break;
; #pragma unroll
;         for (int a = 0; a < 2; ++a)
; #pragma unroll
;             for (int b = 0; b < 2; ++b)
; #pragma unroll
;                 for (int m = 0; m < 4; ++m)
; #pragma unroll
;                     for (int n = 0; n < 2; ++n) acc[a][b][m][n] = (f32x4){0.f, 0.f, 0.f, 0.f};
;         cur = nxt; cA = nA; cB = nB; ++ui;
;     }
;     PG8_WAIT_V(0);
;     if (wr == 0) PG8_BAR;
;     PG8_BAR;
	s_cbranch_scc0 .LBB0_1680
	s_ashr_i32 s5, s4, 31
	s_lshl_b64 s[4:5], s[4:5], 22
	s_add_u32 s4, s47, s4
	v_lshl_or_b32 v140, s40, 8, v138
	v_lshl_add_u32 v142, s29, 8, v136
	s_addc_u32 s5, s48, s5
	v_ashrrev_i32_e32 v141, 31, v140
	v_ashrrev_i32_e32 v143, 31, v142
	v_lshl_add_u64 v[140:141], v[140:141], 2, s[4:5]
	v_lshlrev_b64 v[144:145], 13, v[142:143]
	v_lshl_add_u64 v[144:145], v[140:141], 0, v[144:145]
	global_store_dwordx4 v[144:145], v[126:129], off
	global_store_dwordx4 v[144:145], v[122:125], off offset:64
	global_store_dwordx4 v[144:145], v[110:113], off offset:512
	global_store_dwordx4 v[144:145], v[102:105], off offset:576
	s_mov_b64 s[4:5], 0x100000
	s_mov_b32 s29, s50
	v_or_b32_e32 v102, 16, v142
	v_ashrrev_i32_e32 v103, 31, v102
	v_lshlrev_b64 v[102:103], 13, v[102:103]
	v_lshl_add_u64 v[102:103], v[140:141], 0, v[102:103]
	global_store_dwordx4 v[102:103], v[118:121], off
	global_store_dwordx4 v[102:103], v[114:117], off offset:64
	global_store_dwordx4 v[102:103], v[94:97], off offset:512
	global_store_dwordx4 v[102:103], v[86:89], off offset:576
	s_mov_b32 s40, s51
	s_mov_b64 s[14:15], s[2:3]
	v_or_b32_e32 v86, 32, v142
	v_ashrrev_i32_e32 v87, 31, v86
	v_lshlrev_b64 v[86:87], 13, v[86:87]
	v_lshl_add_u64 v[86:87], v[140:141], 0, v[86:87]
	global_store_dwordx4 v[86:87], v[106:109], off
	global_store_dwordx4 v[86:87], v[98:101], off offset:64
	global_store_dwordx4 v[86:87], v[78:81], off offset:512
	global_store_dwordx4 v[86:87], v[74:77], off offset:576
	s_mov_b64 s[12:13], s[6:7]
	s_mov_b64 s[52:53], 0xc000
	v_or_b32_e32 v74, 48, v142
	v_ashrrev_i32_e32 v75, 31, v74
	v_lshlrev_b64 v[74:75], 13, v[74:75]
	v_lshl_add_u64 v[74:75], v[140:141], 0, v[74:75]
	global_store_dwordx4 v[74:75], v[90:93], off
	global_store_dwordx4 v[74:75], v[82:85], off offset:64
	global_store_dwordx4 v[74:75], v[70:73], off offset:512
	global_store_dwordx4 v[74:75], v[66:69], off offset:576
	s_mov_b64 s[54:55], 0x8000
	s_nop 0
	v_lshl_add_u64 v[66:67], v[144:145], 0, s[4:5]
	s_mov_b32 s4, 0x100000
	v_add_co_u32_e32 v68, vcc, s4, v144
	s_mov_b64 s[4:5], 0x120000
	s_nop 0
	v_addc_co_u32_e32 v69, vcc, 0, v145, vcc
	global_store_dwordx4 v[68:69], v[62:65], off
	global_store_dwordx4 v[66:67], v[58:61], off offset:64
	global_store_dwordx4 v[66:67], v[46:49], off offset:512
	global_store_dwordx4 v[66:67], v[42:45], off offset:576
	s_nop 1
	v_lshl_add_u64 v[42:43], v[144:145], 0, s[4:5]
	s_mov_b32 s4, 0x120000
	v_add_co_u32_e32 v44, vcc, s4, v144
	s_mov_b64 s[4:5], 0x140000
	s_nop 0
	v_addc_co_u32_e32 v45, vcc, 0, v145, vcc
	global_store_dwordx4 v[44:45], v[54:57], off
	global_store_dwordx4 v[42:43], v[50:53], off offset:64
	global_store_dwordx4 v[42:43], v[30:33], off offset:512
	global_store_dwordx4 v[42:43], v[26:29], off offset:576
	s_nop 1
	v_lshl_add_u64 v[26:27], v[144:145], 0, s[4:5]
	s_mov_b32 s4, 0x140000
	v_add_co_u32_e32 v28, vcc, s4, v144
	s_mov_b64 s[4:5], 0x160000
	s_nop 0
	v_addc_co_u32_e32 v29, vcc, 0, v145, vcc
	global_store_dwordx4 v[28:29], v[38:41], off
	global_store_dwordx4 v[26:27], v[34:37], off offset:64
	global_store_dwordx4 v[26:27], v[14:17], off offset:512
	global_store_dwordx4 v[26:27], v[10:13], off offset:576
	s_nop 1
	v_add_co_u32_e32 v12, vcc, 0x160000, v144
	v_lshl_add_u64 v[10:11], v[144:145], 0, s[4:5]
	s_nop 0
	v_addc_co_u32_e32 v13, vcc, 0, v145, vcc
	s_and_b64 vcc, exec, s[0:1]
	s_mov_b32 s4, s10
	global_store_dwordx4 v[12:13], v[22:25], off
	global_store_dwordx4 v[10:11], v[18:21], off offset:64
	global_store_dwordx4 v[10:11], v[6:9], off offset:512
	global_store_dwordx4 v[10:11], v[2:5], off offset:576
	s_cbranch_vccz .LBB0_1675
	s_waitcnt vmcnt(0)
	s_cmpk_gt_u32 s21, 0xff
	s_cbranch_scc1 .LBB0_1684
	s_barrier
